# K-loops: remaining 6 VALU address ops per iteration removed (stage loads via SGPR base, B-fragment LDS reads via one per-tile base VGPR + immediates)
# baseline (speedup 1.0000x reference)
.LBB0_161:
	s_add_u32 s86, s69, s6
	s_addc_u32 s87, s70, s7
	s_add_u32 s88, s71, s8
	s_addc_u32 s89, s72, s9
	s_ashr_i32 s23, s22, 31
	s_lshl_b64 s[6:7], s[22:23], 19
	s_add_u32 s24, s34, s6
	s_addc_u32 s25, s35, s7
	s_and_b64 s[8:9], s[0:1], exec
	s_cselect_b32 s23, s25, s43
	s_cselect_b32 s90, s24, s42
	s_ashr_i32 s21, s20, 31
	s_lshl_b64 s[8:9], s[20:21], 19
	s_add_u32 s26, s17, s8
	s_addc_u32 s27, s19, s9
	s_and_b64 s[48:49], s[0:1], exec
	s_cselect_b32 s21, s27, s39
	s_cselect_b32 s91, s26, s38
	s_add_u32 s48, s90, 0x80
	s_addc_u32 s49, s23, 0
	s_add_u32 s54, s91, 0x80
	s_addc_u32 s55, s21, 0
	v_lshl_add_u64 v[128:129], s[42:43], 0, v[150:151]
	v_lshl_add_u64 v[130:131], s[42:43], 0, v[152:153]
	s_mov_b32 s92, 0
	s_mov_b64 s[56:57], 0
	v_add_u32_e32 v232, 0x10000, v171
	s_add_u32 s64, s42, s56
	s_addc_u32 s65, s43, s57
	s_mov_b64 s[100:101], s[64:65]
	s_add_u32 s94, s38, s56
	s_addc_u32 s93, s39, s57
	s_add_u32 s58, s64, 0x180
	s_addc_u32 s59, s65, 0
	s_add_u32 s60, s94, 0x180
	s_addc_u32 s61, s93, 0
	s_add_u32 s64, s64, 0x100
	s_addc_u32 s65, s65, 0
	s_add_u32 s62, s94, 0x100
	s_addc_u32 s63, s93, 0
	s_cmpk_eq_i32 s56, 0x700
	s_cselect_b32 s58, s48, s58
	s_cselect_b32 s59, s49, s59
	s_cselect_b32 s60, s54, s60
	s_cselect_b32 s61, s55, s61
	s_cselect_b32 s64, s90, s64
	s_cselect_b32 s65, s23, s65
	s_cselect_b32 s62, s91, s62
	s_cselect_b32 s63, s21, s63
	ds_read_b128 v[132:135], v232
	ds_read_b128 v[158:161], v232 offset:1024
	ds_read_b128 v[162:165], v232 offset:2048
	ds_read_b128 v[166:169], v232 offset:3072
	ds_read_b128 v[184:187], v232 offset:16384
	ds_read_b128 v[188:191], v232 offset:17408
	ds_read_b128 v[192:195], v232 offset:18432
	ds_read_b128 v[196:199], v232 offset:19456
	s_add_i32 m0, s29, 0xc000
	ds_read_b128 v[200:203], v181
	ds_read_b128 v[204:207], v181 offset:1024
	ds_read_b128 v[208:211], v181 offset:2048
	ds_read_b128 v[212:215], v181 offset:3072
	ds_read_b128 v[216:219], v181 offset:4096
	ds_read_b128 v[220:223], v181 offset:5120
	ds_read_b128 v[224:227], v181 offset:6144
	global_load_lds_dwordx4 v150, s[100:101]
	s_add_i32 m0, s29, 0xe000
	ds_read_b128 v[228:231], v181 offset:7168
	global_load_lds_dwordx4 v152, s[100:101]
	s_waitcnt vmcnt(8)
	s_waitcnt lgkmcnt(0)
	s_barrier
	s_setprio 1
	s_waitcnt lgkmcnt(0)
	v_mfma_f32_16x16x32_bf16 v[124:127], v[132:135], v[200:203], 0
	v_mfma_f32_16x16x32_bf16 v[120:123], v[162:165], v[200:203], 0
	v_mfma_f32_16x16x32_bf16 v[108:111], v[132:135], v[208:211], 0
	v_mfma_f32_16x16x32_bf16 v[104:107], v[162:165], v[208:211], 0
	v_mfma_f32_16x16x32_bf16 v[92:95], v[132:135], v[216:219], 0
	v_mfma_f32_16x16x32_bf16 v[88:91], v[162:165], v[216:219], 0
	v_mfma_f32_16x16x32_bf16 v[76:79], v[132:135], v[224:227], 0
	v_mfma_f32_16x16x32_bf16 v[72:75], v[162:165], v[224:227], 0
	v_mfma_f32_16x16x32_bf16 v[124:127], v[158:161], v[204:207], v[124:127]
	v_mfma_f32_16x16x32_bf16 v[120:123], v[166:169], v[204:207], v[120:123]
	v_mfma_f32_16x16x32_bf16 v[108:111], v[158:161], v[212:215], v[108:111]
	v_mfma_f32_16x16x32_bf16 v[104:107], v[166:169], v[212:215], v[104:107]
	v_mfma_f32_16x16x32_bf16 v[92:95], v[158:161], v[220:223], v[92:95]
	v_mfma_f32_16x16x32_bf16 v[88:91], v[166:169], v[220:223], v[88:91]
	v_mfma_f32_16x16x32_bf16 v[76:79], v[158:161], v[228:231], v[76:79]
	v_mfma_f32_16x16x32_bf16 v[72:75], v[166:169], v[228:231], v[72:75]
	s_setprio 0
	s_setprio 1
	v_mfma_f32_16x16x32_bf16 v[116:119], v[184:187], v[200:203], 0
	v_mfma_f32_16x16x32_bf16 v[112:115], v[192:195], v[200:203], 0
	v_mfma_f32_16x16x32_bf16 v[100:103], v[184:187], v[208:211], 0
	v_mfma_f32_16x16x32_bf16 v[96:99], v[192:195], v[208:211], 0
	v_mfma_f32_16x16x32_bf16 v[84:87], v[184:187], v[216:219], 0
	v_mfma_f32_16x16x32_bf16 v[80:83], v[192:195], v[216:219], 0
	v_mfma_f32_16x16x32_bf16 v[68:71], v[184:187], v[224:227], 0
	v_mfma_f32_16x16x32_bf16 v[64:67], v[192:195], v[224:227], 0
	v_mfma_f32_16x16x32_bf16 v[116:119], v[188:191], v[204:207], v[116:119]
	v_mfma_f32_16x16x32_bf16 v[112:115], v[196:199], v[204:207], v[112:115]
	v_mfma_f32_16x16x32_bf16 v[100:103], v[188:191], v[212:215], v[100:103]
	v_mfma_f32_16x16x32_bf16 v[96:99], v[196:199], v[212:215], v[96:99]
	v_mfma_f32_16x16x32_bf16 v[84:87], v[188:191], v[220:223], v[84:87]
	v_mfma_f32_16x16x32_bf16 v[80:83], v[196:199], v[220:223], v[80:83]
	v_mfma_f32_16x16x32_bf16 v[68:71], v[188:191], v[228:231], v[68:71]
	v_mfma_f32_16x16x32_bf16 v[64:67], v[196:199], v[228:231], v[64:67]
	s_setprio 0
	s_barrier
	s_add_i32 s10, s82, s66
	s_mov_b32 m0, s10
	ds_read_b128 v[200:203], v181 offset:16384
	ds_read_b128 v[204:207], v181 offset:17408
	ds_read_b128 v[208:211], v181 offset:18432
	global_load_lds_dwordx4 v138, s[62:63]
	s_add_i32 m0, s10, 0x2000
	ds_read_b128 v[212:215], v181 offset:19456
	global_load_lds_dwordx4 v142, s[62:63]
	s_add_u32 s62, s62, 0x40000
	s_addc_u32 s63, s63, 0
	s_add_i32 s10, s83, s66
	s_mov_b32 m0, s10
	ds_read_b128 v[216:219], v181 offset:20480
	global_load_lds_dwordx4 v138, s[62:63]
	s_add_i32 m0, s10, 0x2000
	ds_read_b128 v[220:223], v181 offset:21504
	global_load_lds_dwordx4 v142, s[62:63]
	s_mov_b32 m0, s29
	ds_read_b128 v[224:227], v181 offset:22528
	global_load_lds_dwordx4 v136, s[64:65]
	s_mov_b32 m0, s31
	ds_read_b128 v[228:231], v181 offset:23552
	global_load_lds_dwordx4 v140, s[64:65]
	s_waitcnt vmcnt(8)
	s_waitcnt lgkmcnt(0)
	s_barrier
	s_setprio 1
	s_waitcnt lgkmcnt(0)
	v_mfma_f32_16x16x32_bf16 v[60:63], v[132:135], v[200:203], 0
	v_mfma_f32_16x16x32_bf16 v[56:59], v[162:165], v[200:203], 0
	v_mfma_f32_16x16x32_bf16 v[44:47], v[132:135], v[208:211], 0
	v_mfma_f32_16x16x32_bf16 v[40:43], v[162:165], v[208:211], 0
	v_mfma_f32_16x16x32_bf16 v[28:31], v[132:135], v[216:219], 0
	v_mfma_f32_16x16x32_bf16 v[24:27], v[162:165], v[216:219], 0
	v_mfma_f32_16x16x32_bf16 v[12:15], v[132:135], v[224:227], 0
	v_mfma_f32_16x16x32_bf16 v[8:11], v[162:165], v[224:227], 0
	v_mfma_f32_16x16x32_bf16 v[60:63], v[158:161], v[204:207], v[60:63]
	v_mfma_f32_16x16x32_bf16 v[56:59], v[166:169], v[204:207], v[56:59]
	v_mfma_f32_16x16x32_bf16 v[44:47], v[158:161], v[212:215], v[44:47]
	v_mfma_f32_16x16x32_bf16 v[40:43], v[166:169], v[212:215], v[40:43]
	v_mfma_f32_16x16x32_bf16 v[28:31], v[158:161], v[220:223], v[28:31]
	v_mfma_f32_16x16x32_bf16 v[24:27], v[166:169], v[220:223], v[24:27]
	v_mfma_f32_16x16x32_bf16 v[12:15], v[158:161], v[228:231], v[12:15]
	v_mfma_f32_16x16x32_bf16 v[8:11], v[166:169], v[228:231], v[8:11]
	s_setprio 0
	s_setprio 1
	v_mfma_f32_16x16x32_bf16 v[52:55], v[184:187], v[200:203], 0
	v_mfma_f32_16x16x32_bf16 v[48:51], v[192:195], v[200:203], 0
	v_mfma_f32_16x16x32_bf16 v[36:39], v[184:187], v[208:211], 0
	v_mfma_f32_16x16x32_bf16 v[32:35], v[192:195], v[208:211], 0
	v_mfma_f32_16x16x32_bf16 v[20:23], v[184:187], v[216:219], 0
	v_mfma_f32_16x16x32_bf16 v[16:19], v[192:195], v[216:219], 0
	v_mfma_f32_16x16x32_bf16 v[4:7], v[184:187], v[224:227], 0
	v_mfma_f32_16x16x32_bf16 v[0:3], v[192:195], v[224:227], 0
	v_mfma_f32_16x16x32_bf16 v[52:55], v[188:191], v[204:207], v[52:55]
	v_mfma_f32_16x16x32_bf16 v[48:51], v[196:199], v[204:207], v[48:51]
	v_mfma_f32_16x16x32_bf16 v[36:39], v[188:191], v[212:215], v[36:39]
	v_mfma_f32_16x16x32_bf16 v[32:35], v[196:199], v[212:215], v[32:35]
	v_mfma_f32_16x16x32_bf16 v[20:23], v[188:191], v[220:223], v[20:23]
	v_mfma_f32_16x16x32_bf16 v[16:19], v[196:199], v[220:223], v[16:19]
	v_mfma_f32_16x16x32_bf16 v[4:7], v[188:191], v[228:231], v[4:7]
	v_mfma_f32_16x16x32_bf16 v[0:3], v[196:199], v[228:231], v[0:3]
	s_setprio 0
	s_barrier
	s_add_i32 s10, 0, 0x18000
	s_add_i32 s93, 0, 0x1c000
	ds_read_b128 v[132:135], v232 offset:32768
	ds_read_b128 v[158:161], v232 offset:33792
	ds_read_b128 v[162:165], v232 offset:34816
	ds_read_b128 v[166:169], v232 offset:35840
	ds_read_b128 v[184:187], v232 offset:49152
	ds_read_b128 v[188:191], v232 offset:50176
	ds_read_b128 v[192:195], v232 offset:51200
	ds_read_b128 v[196:199], v232 offset:52224
	s_add_u32 s62, s64, 0x40000
	s_addc_u32 s63, s65, 0
	s_mov_b32 m0, s67
	ds_read_b128 v[200:203], v181 offset:32768
	ds_read_b128 v[204:207], v181 offset:33792
	ds_read_b128 v[208:211], v181 offset:34816
	ds_read_b128 v[212:215], v181 offset:35840
	ds_read_b128 v[216:219], v181 offset:36864
	ds_read_b128 v[220:223], v181 offset:37888
	ds_read_b128 v[224:227], v181 offset:38912
	global_load_lds_dwordx4 v136, s[62:63]
	s_mov_b32 m0, s68
	ds_read_b128 v[228:231], v181 offset:39936
	global_load_lds_dwordx4 v140, s[62:63]
	s_waitcnt vmcnt(8)
	s_waitcnt lgkmcnt(0)
	s_barrier
	s_setprio 1
	s_waitcnt lgkmcnt(0)
	v_mfma_f32_16x16x32_bf16 v[124:127], v[132:135], v[200:203], v[124:127]
	v_mfma_f32_16x16x32_bf16 v[120:123], v[162:165], v[200:203], v[120:123]
	v_mfma_f32_16x16x32_bf16 v[108:111], v[132:135], v[208:211], v[108:111]
	v_mfma_f32_16x16x32_bf16 v[104:107], v[162:165], v[208:211], v[104:107]
	v_mfma_f32_16x16x32_bf16 v[92:95], v[132:135], v[216:219], v[92:95]
	v_mfma_f32_16x16x32_bf16 v[88:91], v[162:165], v[216:219], v[88:91]
	v_mfma_f32_16x16x32_bf16 v[76:79], v[132:135], v[224:227], v[76:79]
	v_mfma_f32_16x16x32_bf16 v[72:75], v[162:165], v[224:227], v[72:75]
	v_mfma_f32_16x16x32_bf16 v[124:127], v[158:161], v[204:207], v[124:127]
	v_mfma_f32_16x16x32_bf16 v[120:123], v[166:169], v[204:207], v[120:123]
	v_mfma_f32_16x16x32_bf16 v[108:111], v[158:161], v[212:215], v[108:111]
	v_mfma_f32_16x16x32_bf16 v[104:107], v[166:169], v[212:215], v[104:107]
	v_mfma_f32_16x16x32_bf16 v[92:95], v[158:161], v[220:223], v[92:95]
	v_mfma_f32_16x16x32_bf16 v[88:91], v[166:169], v[220:223], v[88:91]
	v_mfma_f32_16x16x32_bf16 v[76:79], v[158:161], v[228:231], v[76:79]
	v_mfma_f32_16x16x32_bf16 v[72:75], v[166:169], v[228:231], v[72:75]
	s_setprio 0
	s_setprio 1
	v_mfma_f32_16x16x32_bf16 v[116:119], v[184:187], v[200:203], v[116:119]
	v_mfma_f32_16x16x32_bf16 v[112:115], v[192:195], v[200:203], v[112:115]
	v_mfma_f32_16x16x32_bf16 v[100:103], v[184:187], v[208:211], v[100:103]
	v_mfma_f32_16x16x32_bf16 v[96:99], v[192:195], v[208:211], v[96:99]
	v_mfma_f32_16x16x32_bf16 v[84:87], v[184:187], v[216:219], v[84:87]
	v_mfma_f32_16x16x32_bf16 v[80:83], v[192:195], v[216:219], v[80:83]
	v_mfma_f32_16x16x32_bf16 v[68:71], v[184:187], v[224:227], v[68:71]
	v_mfma_f32_16x16x32_bf16 v[64:67], v[192:195], v[224:227], v[64:67]
	v_mfma_f32_16x16x32_bf16 v[116:119], v[188:191], v[204:207], v[116:119]
	v_mfma_f32_16x16x32_bf16 v[112:115], v[196:199], v[204:207], v[112:115]
	v_mfma_f32_16x16x32_bf16 v[100:103], v[188:191], v[212:215], v[100:103]
	v_mfma_f32_16x16x32_bf16 v[96:99], v[196:199], v[212:215], v[96:99]
	v_mfma_f32_16x16x32_bf16 v[84:87], v[188:191], v[220:223], v[84:87]
	v_mfma_f32_16x16x32_bf16 v[80:83], v[196:199], v[220:223], v[80:83]
	v_mfma_f32_16x16x32_bf16 v[68:71], v[188:191], v[228:231], v[68:71]
	v_mfma_f32_16x16x32_bf16 v[64:67], v[196:199], v[228:231], v[64:67]
	s_setprio 0
	s_barrier
	s_add_i32 s10, s10, s66
	s_mov_b32 m0, s10
	ds_read_b128 v[200:203], v181 offset:49152
	ds_read_b128 v[204:207], v181 offset:50176
	ds_read_b128 v[208:211], v181 offset:51200
	global_load_lds_dwordx4 v138, s[60:61]
	s_add_i32 m0, s10, 0x2000
	ds_read_b128 v[212:215], v181 offset:52224
	global_load_lds_dwordx4 v142, s[60:61]
	s_add_u32 s60, s60, 0x40000
	s_addc_u32 s61, s61, 0
	s_add_i32 s10, s93, s66
	s_mov_b32 m0, s10
	ds_read_b128 v[216:219], v181 offset:53248
	global_load_lds_dwordx4 v138, s[60:61]
	s_add_i32 m0, s10, 0x2000
	ds_read_b128 v[220:223], v181 offset:54272
	global_load_lds_dwordx4 v142, s[60:61]
	s_mov_b32 m0, s73
	ds_read_b128 v[224:227], v181 offset:55296
	global_load_lds_dwordx4 v136, s[58:59]
	s_mov_b32 m0, s78
	ds_read_b128 v[228:231], v181 offset:56320
	global_load_lds_dwordx4 v140, s[58:59]
	s_waitcnt vmcnt(8)
	s_waitcnt lgkmcnt(0)
	s_barrier
	s_setprio 1
	s_waitcnt lgkmcnt(0)
	v_mfma_f32_16x16x32_bf16 v[60:63], v[132:135], v[200:203], v[60:63]
	v_mfma_f32_16x16x32_bf16 v[56:59], v[162:165], v[200:203], v[56:59]
	v_mfma_f32_16x16x32_bf16 v[44:47], v[132:135], v[208:211], v[44:47]
	v_mfma_f32_16x16x32_bf16 v[40:43], v[162:165], v[208:211], v[40:43]
	v_mfma_f32_16x16x32_bf16 v[28:31], v[132:135], v[216:219], v[28:31]
	v_mfma_f32_16x16x32_bf16 v[24:27], v[162:165], v[216:219], v[24:27]
	v_mfma_f32_16x16x32_bf16 v[12:15], v[132:135], v[224:227], v[12:15]
	v_mfma_f32_16x16x32_bf16 v[8:11], v[162:165], v[224:227], v[8:11]
	v_mfma_f32_16x16x32_bf16 v[60:63], v[158:161], v[204:207], v[60:63]
	v_mfma_f32_16x16x32_bf16 v[56:59], v[166:169], v[204:207], v[56:59]
	v_mfma_f32_16x16x32_bf16 v[44:47], v[158:161], v[212:215], v[44:47]
	v_mfma_f32_16x16x32_bf16 v[40:43], v[166:169], v[212:215], v[40:43]
	v_mfma_f32_16x16x32_bf16 v[28:31], v[158:161], v[220:223], v[28:31]
	v_mfma_f32_16x16x32_bf16 v[24:27], v[166:169], v[220:223], v[24:27]
	v_mfma_f32_16x16x32_bf16 v[12:15], v[158:161], v[228:231], v[12:15]
	v_mfma_f32_16x16x32_bf16 v[8:11], v[166:169], v[228:231], v[8:11]
	s_setprio 0
	s_setprio 1
	v_mfma_f32_16x16x32_bf16 v[52:55], v[184:187], v[200:203], v[52:55]
	v_mfma_f32_16x16x32_bf16 v[48:51], v[192:195], v[200:203], v[48:51]
	v_mfma_f32_16x16x32_bf16 v[36:39], v[184:187], v[208:211], v[36:39]
	v_mfma_f32_16x16x32_bf16 v[32:35], v[192:195], v[208:211], v[32:35]
	v_mfma_f32_16x16x32_bf16 v[20:23], v[184:187], v[216:219], v[20:23]
	v_mfma_f32_16x16x32_bf16 v[16:19], v[192:195], v[216:219], v[16:19]
	v_mfma_f32_16x16x32_bf16 v[4:7], v[184:187], v[224:227], v[4:7]
	v_mfma_f32_16x16x32_bf16 v[0:3], v[192:195], v[224:227], v[0:3]
	v_mfma_f32_16x16x32_bf16 v[52:55], v[188:191], v[204:207], v[52:55]
	v_mfma_f32_16x16x32_bf16 v[48:51], v[196:199], v[204:207], v[48:51]
	v_mfma_f32_16x16x32_bf16 v[36:39], v[188:191], v[212:215], v[36:39]
	v_mfma_f32_16x16x32_bf16 v[32:35], v[196:199], v[212:215], v[32:35]
	v_mfma_f32_16x16x32_bf16 v[20:23], v[188:191], v[220:223], v[20:23]
	v_mfma_f32_16x16x32_bf16 v[16:19], v[196:199], v[220:223], v[16:19]
	v_mfma_f32_16x16x32_bf16 v[4:7], v[188:191], v[228:231], v[4:7]
	v_mfma_f32_16x16x32_bf16 v[0:3], v[196:199], v[228:231], v[0:3]
	s_setprio 0
	s_barrier
	s_add_i32 s10, s92, 2
	s_add_u32 s56, s56, 0x100
	s_addc_u32 s57, s57, 0
	s_cmp_gt_u32 s92, 13
	s_mov_b32 s92, s10
	s_cbranch_scc1 .LBB0_169
	s_branch .LBB0_163
.LBB0_162:
	ds_read_b128 v[132:135], v232
	ds_read_b128 v[158:161], v232 offset:1024
	ds_read_b128 v[162:165], v232 offset:2048
	ds_read_b128 v[166:169], v232 offset:3072
	ds_read_b128 v[184:187], v232 offset:16384
	ds_read_b128 v[188:191], v232 offset:17408
	ds_read_b128 v[192:195], v232 offset:18432
	ds_read_b128 v[196:199], v232 offset:19456
	s_add_i32 m0, s29, 0xc000
	ds_read_b128 v[200:203], v181
	ds_read_b128 v[204:207], v181 offset:1024
	ds_read_b128 v[208:211], v181 offset:2048
	ds_read_b128 v[212:215], v181 offset:3072
	ds_read_b128 v[216:219], v181 offset:4096
	ds_read_b128 v[220:223], v181 offset:5120
	ds_read_b128 v[224:227], v181 offset:6144
	global_load_lds_dwordx4 v150, s[100:101]
	s_add_i32 m0, s29, 0xe000
	ds_read_b128 v[228:231], v181 offset:7168
	global_load_lds_dwordx4 v152, s[100:101]
	s_waitcnt vmcnt(8)
	s_waitcnt lgkmcnt(0)
	s_barrier
	s_setprio 1
	s_waitcnt lgkmcnt(0)
	v_mfma_f32_16x16x32_bf16 v[124:127], v[132:135], v[200:203], v[124:127]
	v_mfma_f32_16x16x32_bf16 v[120:123], v[162:165], v[200:203], v[120:123]
	v_mfma_f32_16x16x32_bf16 v[108:111], v[132:135], v[208:211], v[108:111]
	v_mfma_f32_16x16x32_bf16 v[104:107], v[162:165], v[208:211], v[104:107]
	v_mfma_f32_16x16x32_bf16 v[92:95], v[132:135], v[216:219], v[92:95]
	v_mfma_f32_16x16x32_bf16 v[88:91], v[162:165], v[216:219], v[88:91]
	v_mfma_f32_16x16x32_bf16 v[76:79], v[132:135], v[224:227], v[76:79]
	v_mfma_f32_16x16x32_bf16 v[72:75], v[162:165], v[224:227], v[72:75]
	v_mfma_f32_16x16x32_bf16 v[124:127], v[158:161], v[204:207], v[124:127]
	v_mfma_f32_16x16x32_bf16 v[120:123], v[166:169], v[204:207], v[120:123]
	v_mfma_f32_16x16x32_bf16 v[108:111], v[158:161], v[212:215], v[108:111]
	v_mfma_f32_16x16x32_bf16 v[104:107], v[166:169], v[212:215], v[104:107]
	v_mfma_f32_16x16x32_bf16 v[92:95], v[158:161], v[220:223], v[92:95]
	v_mfma_f32_16x16x32_bf16 v[88:91], v[166:169], v[220:223], v[88:91]
	v_mfma_f32_16x16x32_bf16 v[76:79], v[158:161], v[228:231], v[76:79]
	v_mfma_f32_16x16x32_bf16 v[72:75], v[166:169], v[228:231], v[72:75]
	s_setprio 0
	s_setprio 1
	v_mfma_f32_16x16x32_bf16 v[116:119], v[184:187], v[200:203], v[116:119]
	v_mfma_f32_16x16x32_bf16 v[112:115], v[192:195], v[200:203], v[112:115]
	v_mfma_f32_16x16x32_bf16 v[100:103], v[184:187], v[208:211], v[100:103]
	v_mfma_f32_16x16x32_bf16 v[96:99], v[192:195], v[208:211], v[96:99]
	v_mfma_f32_16x16x32_bf16 v[84:87], v[184:187], v[216:219], v[84:87]
	v_mfma_f32_16x16x32_bf16 v[80:83], v[192:195], v[216:219], v[80:83]
	v_mfma_f32_16x16x32_bf16 v[68:71], v[184:187], v[224:227], v[68:71]
	v_mfma_f32_16x16x32_bf16 v[64:67], v[192:195], v[224:227], v[64:67]
	v_mfma_f32_16x16x32_bf16 v[116:119], v[188:191], v[204:207], v[116:119]
	v_mfma_f32_16x16x32_bf16 v[112:115], v[196:199], v[204:207], v[112:115]
	v_mfma_f32_16x16x32_bf16 v[100:103], v[188:191], v[212:215], v[100:103]
	v_mfma_f32_16x16x32_bf16 v[96:99], v[196:199], v[212:215], v[96:99]
	v_mfma_f32_16x16x32_bf16 v[84:87], v[188:191], v[220:223], v[84:87]
	v_mfma_f32_16x16x32_bf16 v[80:83], v[196:199], v[220:223], v[80:83]
	v_mfma_f32_16x16x32_bf16 v[68:71], v[188:191], v[228:231], v[68:71]
	v_mfma_f32_16x16x32_bf16 v[64:67], v[196:199], v[228:231], v[64:67]
	s_setprio 0
	s_barrier
	s_add_i32 s10, s82, s66
	s_mov_b32 m0, s10
	ds_read_b128 v[200:203], v181 offset:16384
	ds_read_b128 v[204:207], v181 offset:17408
	ds_read_b128 v[208:211], v181 offset:18432
	global_load_lds_dwordx4 v138, s[62:63]
	s_add_i32 m0, s10, 0x2000
	ds_read_b128 v[212:215], v181 offset:19456
	global_load_lds_dwordx4 v142, s[62:63]
	s_add_u32 s62, s62, 0x40000
	s_addc_u32 s63, s63, 0
	s_add_i32 s10, s83, s66
	s_mov_b32 m0, s10
	ds_read_b128 v[216:219], v181 offset:20480
	global_load_lds_dwordx4 v138, s[62:63]
	s_add_i32 m0, s10, 0x2000
	ds_read_b128 v[220:223], v181 offset:21504
	global_load_lds_dwordx4 v142, s[62:63]
	s_mov_b32 m0, s29
	ds_read_b128 v[224:227], v181 offset:22528
	global_load_lds_dwordx4 v136, s[64:65]
	s_mov_b32 m0, s31
	ds_read_b128 v[228:231], v181 offset:23552
	global_load_lds_dwordx4 v140, s[64:65]
	s_waitcnt vmcnt(8)
	s_waitcnt lgkmcnt(0)
	s_barrier
	s_setprio 1
	s_waitcnt lgkmcnt(0)
	v_mfma_f32_16x16x32_bf16 v[60:63], v[132:135], v[200:203], v[60:63]
	v_mfma_f32_16x16x32_bf16 v[56:59], v[162:165], v[200:203], v[56:59]
	v_mfma_f32_16x16x32_bf16 v[44:47], v[132:135], v[208:211], v[44:47]
	v_mfma_f32_16x16x32_bf16 v[40:43], v[162:165], v[208:211], v[40:43]
	v_mfma_f32_16x16x32_bf16 v[28:31], v[132:135], v[216:219], v[28:31]
	v_mfma_f32_16x16x32_bf16 v[24:27], v[162:165], v[216:219], v[24:27]
	v_mfma_f32_16x16x32_bf16 v[12:15], v[132:135], v[224:227], v[12:15]
	v_mfma_f32_16x16x32_bf16 v[8:11], v[162:165], v[224:227], v[8:11]
	v_mfma_f32_16x16x32_bf16 v[60:63], v[158:161], v[204:207], v[60:63]
	v_mfma_f32_16x16x32_bf16 v[56:59], v[166:169], v[204:207], v[56:59]
	v_mfma_f32_16x16x32_bf16 v[44:47], v[158:161], v[212:215], v[44:47]
	v_mfma_f32_16x16x32_bf16 v[40:43], v[166:169], v[212:215], v[40:43]
	v_mfma_f32_16x16x32_bf16 v[28:31], v[158:161], v[220:223], v[28:31]
	v_mfma_f32_16x16x32_bf16 v[24:27], v[166:169], v[220:223], v[24:27]
	v_mfma_f32_16x16x32_bf16 v[12:15], v[158:161], v[228:231], v[12:15]
	v_mfma_f32_16x16x32_bf16 v[8:11], v[166:169], v[228:231], v[8:11]
	s_setprio 0
	s_setprio 1
	v_mfma_f32_16x16x32_bf16 v[52:55], v[184:187], v[200:203], v[52:55]
	v_mfma_f32_16x16x32_bf16 v[48:51], v[192:195], v[200:203], v[48:51]
	v_mfma_f32_16x16x32_bf16 v[36:39], v[184:187], v[208:211], v[36:39]
	v_mfma_f32_16x16x32_bf16 v[32:35], v[192:195], v[208:211], v[32:35]
	v_mfma_f32_16x16x32_bf16 v[20:23], v[184:187], v[216:219], v[20:23]
	v_mfma_f32_16x16x32_bf16 v[16:19], v[192:195], v[216:219], v[16:19]
	v_mfma_f32_16x16x32_bf16 v[4:7], v[184:187], v[224:227], v[4:7]
	v_mfma_f32_16x16x32_bf16 v[0:3], v[192:195], v[224:227], v[0:3]
	v_mfma_f32_16x16x32_bf16 v[52:55], v[188:191], v[204:207], v[52:55]
	v_mfma_f32_16x16x32_bf16 v[48:51], v[196:199], v[204:207], v[48:51]
	v_mfma_f32_16x16x32_bf16 v[36:39], v[188:191], v[212:215], v[36:39]
	v_mfma_f32_16x16x32_bf16 v[32:35], v[196:199], v[212:215], v[32:35]
	v_mfma_f32_16x16x32_bf16 v[20:23], v[188:191], v[220:223], v[20:23]
	v_mfma_f32_16x16x32_bf16 v[16:19], v[196:199], v[220:223], v[16:19]
	v_mfma_f32_16x16x32_bf16 v[4:7], v[188:191], v[228:231], v[4:7]
	v_mfma_f32_16x16x32_bf16 v[0:3], v[196:199], v[228:231], v[0:3]
	s_setprio 0
	s_barrier
	s_add_i32 s10, 0, 0x18000
	s_add_i32 s93, 0, 0x1c000
	ds_read_b128 v[132:135], v232 offset:32768
	ds_read_b128 v[158:161], v232 offset:33792
	ds_read_b128 v[162:165], v232 offset:34816
	ds_read_b128 v[166:169], v232 offset:35840
	ds_read_b128 v[184:187], v232 offset:49152
	ds_read_b128 v[188:191], v232 offset:50176
	ds_read_b128 v[192:195], v232 offset:51200
	ds_read_b128 v[196:199], v232 offset:52224
	s_add_u32 s62, s64, 0x40000
	s_addc_u32 s63, s65, 0
	s_mov_b32 m0, s67
	ds_read_b128 v[200:203], v181 offset:32768
	ds_read_b128 v[204:207], v181 offset:33792
	ds_read_b128 v[208:211], v181 offset:34816
	ds_read_b128 v[212:215], v181 offset:35840
	ds_read_b128 v[216:219], v181 offset:36864
	ds_read_b128 v[220:223], v181 offset:37888
	ds_read_b128 v[224:227], v181 offset:38912
	global_load_lds_dwordx4 v136, s[62:63]
	s_mov_b32 m0, s68
	ds_read_b128 v[228:231], v181 offset:39936
	global_load_lds_dwordx4 v140, s[62:63]
	s_waitcnt vmcnt(8)
	s_waitcnt lgkmcnt(0)
	s_barrier
	s_setprio 1
	s_waitcnt lgkmcnt(0)
	v_mfma_f32_16x16x32_bf16 v[124:127], v[132:135], v[200:203], v[124:127]
	v_mfma_f32_16x16x32_bf16 v[120:123], v[162:165], v[200:203], v[120:123]
	v_mfma_f32_16x16x32_bf16 v[108:111], v[132:135], v[208:211], v[108:111]
	v_mfma_f32_16x16x32_bf16 v[104:107], v[162:165], v[208:211], v[104:107]
	v_mfma_f32_16x16x32_bf16 v[92:95], v[132:135], v[216:219], v[92:95]
	v_mfma_f32_16x16x32_bf16 v[88:91], v[162:165], v[216:219], v[88:91]
	v_mfma_f32_16x16x32_bf16 v[76:79], v[132:135], v[224:227], v[76:79]
	v_mfma_f32_16x16x32_bf16 v[72:75], v[162:165], v[224:227], v[72:75]
	v_mfma_f32_16x16x32_bf16 v[124:127], v[158:161], v[204:207], v[124:127]
	v_mfma_f32_16x16x32_bf16 v[120:123], v[166:169], v[204:207], v[120:123]
	v_mfma_f32_16x16x32_bf16 v[108:111], v[158:161], v[212:215], v[108:111]
	v_mfma_f32_16x16x32_bf16 v[104:107], v[166:169], v[212:215], v[104:107]
	v_mfma_f32_16x16x32_bf16 v[92:95], v[158:161], v[220:223], v[92:95]
	v_mfma_f32_16x16x32_bf16 v[88:91], v[166:169], v[220:223], v[88:91]
	v_mfma_f32_16x16x32_bf16 v[76:79], v[158:161], v[228:231], v[76:79]
	v_mfma_f32_16x16x32_bf16 v[72:75], v[166:169], v[228:231], v[72:75]
	s_setprio 0
	s_setprio 1
	v_mfma_f32_16x16x32_bf16 v[116:119], v[184:187], v[200:203], v[116:119]
	v_mfma_f32_16x16x32_bf16 v[112:115], v[192:195], v[200:203], v[112:115]
	v_mfma_f32_16x16x32_bf16 v[100:103], v[184:187], v[208:211], v[100:103]
	v_mfma_f32_16x16x32_bf16 v[96:99], v[192:195], v[208:211], v[96:99]
	v_mfma_f32_16x16x32_bf16 v[84:87], v[184:187], v[216:219], v[84:87]
	v_mfma_f32_16x16x32_bf16 v[80:83], v[192:195], v[216:219], v[80:83]
	v_mfma_f32_16x16x32_bf16 v[68:71], v[184:187], v[224:227], v[68:71]
	v_mfma_f32_16x16x32_bf16 v[64:67], v[192:195], v[224:227], v[64:67]
	v_mfma_f32_16x16x32_bf16 v[116:119], v[188:191], v[204:207], v[116:119]
	v_mfma_f32_16x16x32_bf16 v[112:115], v[196:199], v[204:207], v[112:115]
	v_mfma_f32_16x16x32_bf16 v[100:103], v[188:191], v[212:215], v[100:103]
	v_mfma_f32_16x16x32_bf16 v[96:99], v[196:199], v[212:215], v[96:99]
	v_mfma_f32_16x16x32_bf16 v[84:87], v[188:191], v[220:223], v[84:87]
	v_mfma_f32_16x16x32_bf16 v[80:83], v[196:199], v[220:223], v[80:83]
	v_mfma_f32_16x16x32_bf16 v[68:71], v[188:191], v[228:231], v[68:71]
	v_mfma_f32_16x16x32_bf16 v[64:67], v[196:199], v[228:231], v[64:67]
	s_setprio 0
	s_barrier
	s_add_i32 s10, s10, s66
	s_mov_b32 m0, s10
	ds_read_b128 v[200:203], v181 offset:49152
	ds_read_b128 v[204:207], v181 offset:50176
	ds_read_b128 v[208:211], v181 offset:51200
	global_load_lds_dwordx4 v138, s[60:61]
	s_add_i32 m0, s10, 0x2000
	ds_read_b128 v[212:215], v181 offset:52224
	global_load_lds_dwordx4 v142, s[60:61]
	s_add_u32 s60, s60, 0x40000
	s_addc_u32 s61, s61, 0
	s_add_i32 s10, s93, s66
	s_mov_b32 m0, s10
	ds_read_b128 v[216:219], v181 offset:53248
	global_load_lds_dwordx4 v138, s[60:61]
	s_add_i32 m0, s10, 0x2000
	ds_read_b128 v[220:223], v181 offset:54272
	global_load_lds_dwordx4 v142, s[60:61]
	s_mov_b32 m0, s73
	ds_read_b128 v[224:227], v181 offset:55296
	global_load_lds_dwordx4 v136, s[58:59]
	s_mov_b32 m0, s78
	ds_read_b128 v[228:231], v181 offset:56320
	global_load_lds_dwordx4 v140, s[58:59]
	s_waitcnt vmcnt(8)
	s_waitcnt lgkmcnt(0)
	s_barrier
	s_setprio 1
	s_waitcnt lgkmcnt(0)
	v_mfma_f32_16x16x32_bf16 v[60:63], v[132:135], v[200:203], v[60:63]
	v_mfma_f32_16x16x32_bf16 v[56:59], v[162:165], v[200:203], v[56:59]
	v_mfma_f32_16x16x32_bf16 v[44:47], v[132:135], v[208:211], v[44:47]
	v_mfma_f32_16x16x32_bf16 v[40:43], v[162:165], v[208:211], v[40:43]
	v_mfma_f32_16x16x32_bf16 v[28:31], v[132:135], v[216:219], v[28:31]
	v_mfma_f32_16x16x32_bf16 v[24:27], v[162:165], v[216:219], v[24:27]
	v_mfma_f32_16x16x32_bf16 v[12:15], v[132:135], v[224:227], v[12:15]
	v_mfma_f32_16x16x32_bf16 v[8:11], v[162:165], v[224:227], v[8:11]
	v_mfma_f32_16x16x32_bf16 v[60:63], v[158:161], v[204:207], v[60:63]
	v_mfma_f32_16x16x32_bf16 v[56:59], v[166:169], v[204:207], v[56:59]
	v_mfma_f32_16x16x32_bf16 v[44:47], v[158:161], v[212:215], v[44:47]
	v_mfma_f32_16x16x32_bf16 v[40:43], v[166:169], v[212:215], v[40:43]
	v_mfma_f32_16x16x32_bf16 v[28:31], v[158:161], v[220:223], v[28:31]
	v_mfma_f32_16x16x32_bf16 v[24:27], v[166:169], v[220:223], v[24:27]
	v_mfma_f32_16x16x32_bf16 v[12:15], v[158:161], v[228:231], v[12:15]
	v_mfma_f32_16x16x32_bf16 v[8:11], v[166:169], v[228:231], v[8:11]
	s_setprio 0
	s_setprio 1
	v_mfma_f32_16x16x32_bf16 v[52:55], v[184:187], v[200:203], v[52:55]
	v_mfma_f32_16x16x32_bf16 v[48:51], v[192:195], v[200:203], v[48:51]
	v_mfma_f32_16x16x32_bf16 v[36:39], v[184:187], v[208:211], v[36:39]
	v_mfma_f32_16x16x32_bf16 v[32:35], v[192:195], v[208:211], v[32:35]
	v_mfma_f32_16x16x32_bf16 v[20:23], v[184:187], v[216:219], v[20:23]
	v_mfma_f32_16x16x32_bf16 v[16:19], v[192:195], v[216:219], v[16:19]
	v_mfma_f32_16x16x32_bf16 v[4:7], v[184:187], v[224:227], v[4:7]
	v_mfma_f32_16x16x32_bf16 v[0:3], v[192:195], v[224:227], v[0:3]
	v_mfma_f32_16x16x32_bf16 v[52:55], v[188:191], v[204:207], v[52:55]
	v_mfma_f32_16x16x32_bf16 v[48:51], v[196:199], v[204:207], v[48:51]
	v_mfma_f32_16x16x32_bf16 v[36:39], v[188:191], v[212:215], v[36:39]
	v_mfma_f32_16x16x32_bf16 v[32:35], v[196:199], v[212:215], v[32:35]
	v_mfma_f32_16x16x32_bf16 v[20:23], v[188:191], v[220:223], v[20:23]
	v_mfma_f32_16x16x32_bf16 v[16:19], v[196:199], v[220:223], v[16:19]
	v_mfma_f32_16x16x32_bf16 v[4:7], v[188:191], v[228:231], v[4:7]
	v_mfma_f32_16x16x32_bf16 v[0:3], v[196:199], v[228:231], v[0:3]
	s_setprio 0
	s_barrier
	s_add_i32 s10, s92, 2
	s_add_u32 s56, s56, 0x100
	s_addc_u32 s57, s57, 0
	s_cmp_gt_u32 s92, 13
	s_mov_b32 s92, s10
	s_cbranch_scc1 .LBB0_169
.LBB0_163:
	s_add_u32 s64, s42, s56
	s_addc_u32 s65, s43, s57
	s_mov_b64 s[100:101], s[64:65]
	s_add_u32 s94, s38, s56
	s_addc_u32 s93, s39, s57
	s_add_u32 s58, s64, 0x180
	s_addc_u32 s59, s65, 0
	s_add_u32 s60, s94, 0x180
	s_addc_u32 s61, s93, 0
	s_add_u32 s64, s64, 0x100
	s_addc_u32 s65, s65, 0
	s_add_u32 s62, s94, 0x100
	s_addc_u32 s63, s93, 0
	s_cmpk_eq_i32 s56, 0x700
	s_cselect_b32 s58, s48, s58
	s_cselect_b32 s59, s49, s59
	s_cselect_b32 s60, s54, s60
	s_cselect_b32 s61, s55, s61
	s_cselect_b32 s64, s90, s64
	s_cselect_b32 s65, s23, s65
	s_cselect_b32 s62, s91, s62
	s_cselect_b32 s63, s21, s63
	s_branch .LBB0_162

.LBB0_713:
	s_add_u32 s19, s63, s6
	s_addc_u32 s29, s64, s7
	s_add_u32 s31, s65, s8
	s_addc_u32 s79, s66, s9
	s_ashr_i32 s23, s22, 31
	s_lshl_b64 s[6:7], s[22:23], 19
	s_add_u32 s24, s34, s6
	s_addc_u32 s25, s35, s7
	s_and_b64 s[8:9], s[4:5], exec
	s_cselect_b32 s23, s25, s45
	s_cselect_b32 s80, s24, s44
	s_ashr_i32 s21, s20, 31
	s_lshl_b64 s[8:9], s[20:21], 19
	s_add_u32 s26, s42, s8
	s_addc_u32 s27, s43, s9
	s_and_b64 s[36:37], s[4:5], exec
	s_cselect_b32 s21, s27, s39
	s_cselect_b32 s81, s26, s38
	s_add_u32 s36, s80, 0x80
	s_addc_u32 s37, s23, 0
	s_add_u32 s46, s81, 0x80
	s_addc_u32 s47, s21, 0
	v_lshl_add_u64 v[128:129], s[44:45], 0, v[156:157]
	v_lshl_add_u64 v[130:131], s[44:45], 0, v[158:159]
	s_mov_b32 s82, 0
	s_mov_b64 s[48:49], 0
	v_add_u32_e32 v168, 0x10000, v171
	s_add_u32 s56, s44, s48
	s_addc_u32 s57, s45, s49
	s_mov_b64 s[100:101], s[56:57]
	s_add_u32 s84, s38, s48
	s_addc_u32 s83, s39, s49
	s_add_u32 s50, s56, 0x180
	s_addc_u32 s51, s57, 0
	s_add_u32 s52, s84, 0x180
	s_addc_u32 s53, s83, 0
	s_add_u32 s56, s56, 0x100
	s_addc_u32 s57, s57, 0
	s_add_u32 s54, s84, 0x100
	s_addc_u32 s55, s83, 0
	s_cmpk_eq_i32 s48, 0x700
	s_cselect_b32 s50, s36, s50
	s_cselect_b32 s51, s37, s51
	s_cselect_b32 s52, s46, s52
	s_cselect_b32 s53, s47, s53
	s_cselect_b32 s56, s80, s56
	s_cselect_b32 s57, s23, s57
	s_cselect_b32 s54, s81, s54
	s_cselect_b32 s55, s21, s55
	ds_read_b128 v[132:135], v168
	ds_read_b128 v[136:139], v168 offset:1024
	ds_read_b128 v[140:143], v168 offset:2048
	ds_read_b128 v[164:167], v168 offset:3072
	ds_read_b128 v[174:177], v168 offset:16384
	ds_read_b128 v[178:181], v168 offset:17408
	ds_read_b128 v[182:185], v168 offset:18432
	ds_read_b128 v[186:189], v168 offset:19456
	s_add_i32 m0, s59, 0xc000
	ds_read_b128 v[190:193], v172
	ds_read_b128 v[194:197], v172 offset:1024
	ds_read_b128 v[198:201], v172 offset:2048
	ds_read_b128 v[202:205], v172 offset:3072
	ds_read_b128 v[206:209], v172 offset:4096
	ds_read_b128 v[210:213], v172 offset:5120
	ds_read_b128 v[214:217], v172 offset:6144
	global_load_lds_dwordx4 v156, s[100:101]
	s_add_i32 m0, s59, 0xe000
	ds_read_b128 v[218:221], v172 offset:7168
	global_load_lds_dwordx4 v158, s[100:101]
	s_waitcnt vmcnt(8)
	s_waitcnt lgkmcnt(0)
	s_barrier
	s_setprio 1
	s_waitcnt lgkmcnt(0)
	v_mfma_f32_16x16x32_bf16 v[124:127], v[132:135], v[190:193], 0
	v_mfma_f32_16x16x32_bf16 v[120:123], v[140:143], v[190:193], 0
	v_mfma_f32_16x16x32_bf16 v[108:111], v[132:135], v[198:201], 0
	v_mfma_f32_16x16x32_bf16 v[104:107], v[140:143], v[198:201], 0
	v_mfma_f32_16x16x32_bf16 v[92:95], v[132:135], v[206:209], 0
	v_mfma_f32_16x16x32_bf16 v[88:91], v[140:143], v[206:209], 0
	v_mfma_f32_16x16x32_bf16 v[76:79], v[132:135], v[214:217], 0
	v_mfma_f32_16x16x32_bf16 v[72:75], v[140:143], v[214:217], 0
	v_mfma_f32_16x16x32_bf16 v[124:127], v[136:139], v[194:197], v[124:127]
	v_mfma_f32_16x16x32_bf16 v[120:123], v[164:167], v[194:197], v[120:123]
	v_mfma_f32_16x16x32_bf16 v[108:111], v[136:139], v[202:205], v[108:111]
	v_mfma_f32_16x16x32_bf16 v[104:107], v[164:167], v[202:205], v[104:107]
	v_mfma_f32_16x16x32_bf16 v[92:95], v[136:139], v[210:213], v[92:95]
	v_mfma_f32_16x16x32_bf16 v[88:91], v[164:167], v[210:213], v[88:91]
	v_mfma_f32_16x16x32_bf16 v[76:79], v[136:139], v[218:221], v[76:79]
	v_mfma_f32_16x16x32_bf16 v[72:75], v[164:167], v[218:221], v[72:75]
	s_setprio 0
	s_setprio 1
	v_mfma_f32_16x16x32_bf16 v[116:119], v[174:177], v[190:193], 0
	v_mfma_f32_16x16x32_bf16 v[112:115], v[182:185], v[190:193], 0
	v_mfma_f32_16x16x32_bf16 v[100:103], v[174:177], v[198:201], 0
	v_mfma_f32_16x16x32_bf16 v[96:99], v[182:185], v[198:201], 0
	v_mfma_f32_16x16x32_bf16 v[84:87], v[174:177], v[206:209], 0
	v_mfma_f32_16x16x32_bf16 v[80:83], v[182:185], v[206:209], 0
	v_mfma_f32_16x16x32_bf16 v[68:71], v[174:177], v[214:217], 0
	v_mfma_f32_16x16x32_bf16 v[64:67], v[182:185], v[214:217], 0
	v_mfma_f32_16x16x32_bf16 v[116:119], v[178:181], v[194:197], v[116:119]
	v_mfma_f32_16x16x32_bf16 v[112:115], v[186:189], v[194:197], v[112:115]
	v_mfma_f32_16x16x32_bf16 v[100:103], v[178:181], v[202:205], v[100:103]
	v_mfma_f32_16x16x32_bf16 v[96:99], v[186:189], v[202:205], v[96:99]
	v_mfma_f32_16x16x32_bf16 v[84:87], v[178:181], v[210:213], v[84:87]
	v_mfma_f32_16x16x32_bf16 v[80:83], v[186:189], v[210:213], v[80:83]
	v_mfma_f32_16x16x32_bf16 v[68:71], v[178:181], v[218:221], v[68:71]
	v_mfma_f32_16x16x32_bf16 v[64:67], v[186:189], v[218:221], v[64:67]
	s_setprio 0
	s_barrier
	s_add_i32 s10, s72, s58
	s_mov_b32 m0, s10
	ds_read_b128 v[190:193], v172 offset:16384
	ds_read_b128 v[194:197], v172 offset:17408
	ds_read_b128 v[198:201], v172 offset:18432
	global_load_lds_dwordx4 v146, s[54:55]
	s_add_i32 m0, s10, 0x2000
	ds_read_b128 v[202:205], v172 offset:19456
	global_load_lds_dwordx4 v150, s[54:55]
	s_add_u32 s54, s54, 0x40000
	s_addc_u32 s55, s55, 0
	s_add_i32 s10, s73, s58
	s_mov_b32 m0, s10
	ds_read_b128 v[206:209], v172 offset:20480
	global_load_lds_dwordx4 v146, s[54:55]
	s_add_i32 m0, s10, 0x2000
	ds_read_b128 v[210:213], v172 offset:21504
	global_load_lds_dwordx4 v150, s[54:55]
	s_mov_b32 m0, s59
	ds_read_b128 v[214:217], v172 offset:22528
	global_load_lds_dwordx4 v144, s[56:57]
	s_mov_b32 m0, s60
	ds_read_b128 v[218:221], v172 offset:23552
	global_load_lds_dwordx4 v148, s[56:57]
	s_waitcnt vmcnt(8)
	s_waitcnt lgkmcnt(0)
	s_barrier
	s_setprio 1
	s_waitcnt lgkmcnt(0)
	v_mfma_f32_16x16x32_bf16 v[60:63], v[132:135], v[190:193], 0
	v_mfma_f32_16x16x32_bf16 v[56:59], v[140:143], v[190:193], 0
	v_mfma_f32_16x16x32_bf16 v[44:47], v[132:135], v[198:201], 0
	v_mfma_f32_16x16x32_bf16 v[40:43], v[140:143], v[198:201], 0
	v_mfma_f32_16x16x32_bf16 v[28:31], v[132:135], v[206:209], 0
	v_mfma_f32_16x16x32_bf16 v[24:27], v[140:143], v[206:209], 0
	v_mfma_f32_16x16x32_bf16 v[12:15], v[132:135], v[214:217], 0
	v_mfma_f32_16x16x32_bf16 v[8:11], v[140:143], v[214:217], 0
	v_mfma_f32_16x16x32_bf16 v[60:63], v[136:139], v[194:197], v[60:63]
	v_mfma_f32_16x16x32_bf16 v[56:59], v[164:167], v[194:197], v[56:59]
	v_mfma_f32_16x16x32_bf16 v[44:47], v[136:139], v[202:205], v[44:47]
	v_mfma_f32_16x16x32_bf16 v[40:43], v[164:167], v[202:205], v[40:43]
	v_mfma_f32_16x16x32_bf16 v[28:31], v[136:139], v[210:213], v[28:31]
	v_mfma_f32_16x16x32_bf16 v[24:27], v[164:167], v[210:213], v[24:27]
	v_mfma_f32_16x16x32_bf16 v[12:15], v[136:139], v[218:221], v[12:15]
	v_mfma_f32_16x16x32_bf16 v[8:11], v[164:167], v[218:221], v[8:11]
	s_setprio 0
	s_setprio 1
	v_mfma_f32_16x16x32_bf16 v[52:55], v[174:177], v[190:193], 0
	v_mfma_f32_16x16x32_bf16 v[48:51], v[182:185], v[190:193], 0
	v_mfma_f32_16x16x32_bf16 v[36:39], v[174:177], v[198:201], 0
	v_mfma_f32_16x16x32_bf16 v[32:35], v[182:185], v[198:201], 0
	v_mfma_f32_16x16x32_bf16 v[20:23], v[174:177], v[206:209], 0
	v_mfma_f32_16x16x32_bf16 v[16:19], v[182:185], v[206:209], 0
	v_mfma_f32_16x16x32_bf16 v[4:7], v[174:177], v[214:217], 0
	v_mfma_f32_16x16x32_bf16 v[0:3], v[182:185], v[214:217], 0
	v_mfma_f32_16x16x32_bf16 v[52:55], v[178:181], v[194:197], v[52:55]
	v_mfma_f32_16x16x32_bf16 v[48:51], v[186:189], v[194:197], v[48:51]
	v_mfma_f32_16x16x32_bf16 v[36:39], v[178:181], v[202:205], v[36:39]
	v_mfma_f32_16x16x32_bf16 v[32:35], v[186:189], v[202:205], v[32:35]
	v_mfma_f32_16x16x32_bf16 v[20:23], v[178:181], v[210:213], v[20:23]
	v_mfma_f32_16x16x32_bf16 v[16:19], v[186:189], v[210:213], v[16:19]
	v_mfma_f32_16x16x32_bf16 v[4:7], v[178:181], v[218:221], v[4:7]
	v_mfma_f32_16x16x32_bf16 v[0:3], v[186:189], v[218:221], v[0:3]
	s_setprio 0
	s_barrier
	s_add_i32 s10, 0, 0x18000
	s_add_i32 s83, 0, 0x1c000
	ds_read_b128 v[132:135], v168 offset:32768
	ds_read_b128 v[136:139], v168 offset:33792
	ds_read_b128 v[140:143], v168 offset:34816
	ds_read_b128 v[164:167], v168 offset:35840
	ds_read_b128 v[174:177], v168 offset:49152
	ds_read_b128 v[178:181], v168 offset:50176
	ds_read_b128 v[182:185], v168 offset:51200
	ds_read_b128 v[186:189], v168 offset:52224
	s_add_u32 s54, s56, 0x40000
	s_addc_u32 s55, s57, 0
	s_mov_b32 m0, s61
	ds_read_b128 v[190:193], v172 offset:32768
	ds_read_b128 v[194:197], v172 offset:33792
	ds_read_b128 v[198:201], v172 offset:34816
	ds_read_b128 v[202:205], v172 offset:35840
	ds_read_b128 v[206:209], v172 offset:36864
	ds_read_b128 v[210:213], v172 offset:37888
	ds_read_b128 v[214:217], v172 offset:38912
	global_load_lds_dwordx4 v144, s[54:55]
	s_mov_b32 m0, s62
	ds_read_b128 v[218:221], v172 offset:39936
	global_load_lds_dwordx4 v148, s[54:55]
	s_waitcnt vmcnt(8)
	s_waitcnt lgkmcnt(0)
	s_barrier
	s_setprio 1
	s_waitcnt lgkmcnt(0)
	v_mfma_f32_16x16x32_bf16 v[124:127], v[132:135], v[190:193], v[124:127]
	v_mfma_f32_16x16x32_bf16 v[120:123], v[140:143], v[190:193], v[120:123]
	v_mfma_f32_16x16x32_bf16 v[108:111], v[132:135], v[198:201], v[108:111]
	v_mfma_f32_16x16x32_bf16 v[104:107], v[140:143], v[198:201], v[104:107]
	v_mfma_f32_16x16x32_bf16 v[92:95], v[132:135], v[206:209], v[92:95]
	v_mfma_f32_16x16x32_bf16 v[88:91], v[140:143], v[206:209], v[88:91]
	v_mfma_f32_16x16x32_bf16 v[76:79], v[132:135], v[214:217], v[76:79]
	v_mfma_f32_16x16x32_bf16 v[72:75], v[140:143], v[214:217], v[72:75]
	v_mfma_f32_16x16x32_bf16 v[124:127], v[136:139], v[194:197], v[124:127]
	v_mfma_f32_16x16x32_bf16 v[120:123], v[164:167], v[194:197], v[120:123]
	v_mfma_f32_16x16x32_bf16 v[108:111], v[136:139], v[202:205], v[108:111]
	v_mfma_f32_16x16x32_bf16 v[104:107], v[164:167], v[202:205], v[104:107]
	v_mfma_f32_16x16x32_bf16 v[92:95], v[136:139], v[210:213], v[92:95]
	v_mfma_f32_16x16x32_bf16 v[88:91], v[164:167], v[210:213], v[88:91]
	v_mfma_f32_16x16x32_bf16 v[76:79], v[136:139], v[218:221], v[76:79]
	v_mfma_f32_16x16x32_bf16 v[72:75], v[164:167], v[218:221], v[72:75]
	s_setprio 0
	s_setprio 1
	v_mfma_f32_16x16x32_bf16 v[116:119], v[174:177], v[190:193], v[116:119]
	v_mfma_f32_16x16x32_bf16 v[112:115], v[182:185], v[190:193], v[112:115]
	v_mfma_f32_16x16x32_bf16 v[100:103], v[174:177], v[198:201], v[100:103]
	v_mfma_f32_16x16x32_bf16 v[96:99], v[182:185], v[198:201], v[96:99]
	v_mfma_f32_16x16x32_bf16 v[84:87], v[174:177], v[206:209], v[84:87]
	v_mfma_f32_16x16x32_bf16 v[80:83], v[182:185], v[206:209], v[80:83]
	v_mfma_f32_16x16x32_bf16 v[68:71], v[174:177], v[214:217], v[68:71]
	v_mfma_f32_16x16x32_bf16 v[64:67], v[182:185], v[214:217], v[64:67]
	v_mfma_f32_16x16x32_bf16 v[116:119], v[178:181], v[194:197], v[116:119]
	v_mfma_f32_16x16x32_bf16 v[112:115], v[186:189], v[194:197], v[112:115]
	v_mfma_f32_16x16x32_bf16 v[100:103], v[178:181], v[202:205], v[100:103]
	v_mfma_f32_16x16x32_bf16 v[96:99], v[186:189], v[202:205], v[96:99]
	v_mfma_f32_16x16x32_bf16 v[84:87], v[178:181], v[210:213], v[84:87]
	v_mfma_f32_16x16x32_bf16 v[80:83], v[186:189], v[210:213], v[80:83]
	v_mfma_f32_16x16x32_bf16 v[68:71], v[178:181], v[218:221], v[68:71]
	v_mfma_f32_16x16x32_bf16 v[64:67], v[186:189], v[218:221], v[64:67]
	s_setprio 0
	s_barrier
	s_add_i32 s10, s10, s58
	s_mov_b32 m0, s10
	ds_read_b128 v[190:193], v172 offset:49152
	ds_read_b128 v[194:197], v172 offset:50176
	ds_read_b128 v[198:201], v172 offset:51200
	global_load_lds_dwordx4 v146, s[52:53]
	s_add_i32 m0, s10, 0x2000
	ds_read_b128 v[202:205], v172 offset:52224
	global_load_lds_dwordx4 v150, s[52:53]
	s_add_u32 s52, s52, 0x40000
	s_addc_u32 s53, s53, 0
	s_add_i32 s10, s83, s58
	s_mov_b32 m0, s10
	ds_read_b128 v[206:209], v172 offset:53248
	global_load_lds_dwordx4 v146, s[52:53]
	s_add_i32 m0, s10, 0x2000
	ds_read_b128 v[210:213], v172 offset:54272
	global_load_lds_dwordx4 v150, s[52:53]
	s_mov_b32 m0, s68
	ds_read_b128 v[214:217], v172 offset:55296
	global_load_lds_dwordx4 v144, s[50:51]
	s_mov_b32 m0, s69
	ds_read_b128 v[218:221], v172 offset:56320
	global_load_lds_dwordx4 v148, s[50:51]
	s_waitcnt vmcnt(8)
	s_waitcnt lgkmcnt(0)
	s_barrier
	s_setprio 1
	s_waitcnt lgkmcnt(0)
	v_mfma_f32_16x16x32_bf16 v[60:63], v[132:135], v[190:193], v[60:63]
	v_mfma_f32_16x16x32_bf16 v[56:59], v[140:143], v[190:193], v[56:59]
	v_mfma_f32_16x16x32_bf16 v[44:47], v[132:135], v[198:201], v[44:47]
	v_mfma_f32_16x16x32_bf16 v[40:43], v[140:143], v[198:201], v[40:43]
	v_mfma_f32_16x16x32_bf16 v[28:31], v[132:135], v[206:209], v[28:31]
	v_mfma_f32_16x16x32_bf16 v[24:27], v[140:143], v[206:209], v[24:27]
	v_mfma_f32_16x16x32_bf16 v[12:15], v[132:135], v[214:217], v[12:15]
	v_mfma_f32_16x16x32_bf16 v[8:11], v[140:143], v[214:217], v[8:11]
	v_mfma_f32_16x16x32_bf16 v[60:63], v[136:139], v[194:197], v[60:63]
	v_mfma_f32_16x16x32_bf16 v[56:59], v[164:167], v[194:197], v[56:59]
	v_mfma_f32_16x16x32_bf16 v[44:47], v[136:139], v[202:205], v[44:47]
	v_mfma_f32_16x16x32_bf16 v[40:43], v[164:167], v[202:205], v[40:43]
	v_mfma_f32_16x16x32_bf16 v[28:31], v[136:139], v[210:213], v[28:31]
	v_mfma_f32_16x16x32_bf16 v[24:27], v[164:167], v[210:213], v[24:27]
	v_mfma_f32_16x16x32_bf16 v[12:15], v[136:139], v[218:221], v[12:15]
	v_mfma_f32_16x16x32_bf16 v[8:11], v[164:167], v[218:221], v[8:11]
	s_setprio 0
	s_setprio 1
	v_mfma_f32_16x16x32_bf16 v[52:55], v[174:177], v[190:193], v[52:55]
	v_mfma_f32_16x16x32_bf16 v[48:51], v[182:185], v[190:193], v[48:51]
	v_mfma_f32_16x16x32_bf16 v[36:39], v[174:177], v[198:201], v[36:39]
	v_mfma_f32_16x16x32_bf16 v[32:35], v[182:185], v[198:201], v[32:35]
	v_mfma_f32_16x16x32_bf16 v[20:23], v[174:177], v[206:209], v[20:23]
	v_mfma_f32_16x16x32_bf16 v[16:19], v[182:185], v[206:209], v[16:19]
	v_mfma_f32_16x16x32_bf16 v[4:7], v[174:177], v[214:217], v[4:7]
	v_mfma_f32_16x16x32_bf16 v[0:3], v[182:185], v[214:217], v[0:3]
	v_mfma_f32_16x16x32_bf16 v[52:55], v[178:181], v[194:197], v[52:55]
	v_mfma_f32_16x16x32_bf16 v[48:51], v[186:189], v[194:197], v[48:51]
	v_mfma_f32_16x16x32_bf16 v[36:39], v[178:181], v[202:205], v[36:39]
	v_mfma_f32_16x16x32_bf16 v[32:35], v[186:189], v[202:205], v[32:35]
	v_mfma_f32_16x16x32_bf16 v[20:23], v[178:181], v[210:213], v[20:23]
	v_mfma_f32_16x16x32_bf16 v[16:19], v[186:189], v[210:213], v[16:19]
	v_mfma_f32_16x16x32_bf16 v[4:7], v[178:181], v[218:221], v[4:7]
	v_mfma_f32_16x16x32_bf16 v[0:3], v[186:189], v[218:221], v[0:3]
	s_setprio 0
	s_barrier
	s_add_i32 s10, s82, 2
	s_add_u32 s48, s48, 0x100
	s_addc_u32 s49, s49, 0
	s_cmp_gt_u32 s82, 13
	s_mov_b32 s82, s10
	s_cbranch_scc1 .LBB0_721
	s_branch .LBB0_715
.LBB0_714:
	ds_read_b128 v[132:135], v168
	ds_read_b128 v[136:139], v168 offset:1024
	ds_read_b128 v[140:143], v168 offset:2048
	ds_read_b128 v[164:167], v168 offset:3072
	ds_read_b128 v[174:177], v168 offset:16384
	ds_read_b128 v[178:181], v168 offset:17408
	ds_read_b128 v[182:185], v168 offset:18432
	ds_read_b128 v[186:189], v168 offset:19456
	s_add_i32 m0, s59, 0xc000
	ds_read_b128 v[190:193], v172
	ds_read_b128 v[194:197], v172 offset:1024
	ds_read_b128 v[198:201], v172 offset:2048
	ds_read_b128 v[202:205], v172 offset:3072
	ds_read_b128 v[206:209], v172 offset:4096
	ds_read_b128 v[210:213], v172 offset:5120
	ds_read_b128 v[214:217], v172 offset:6144
	global_load_lds_dwordx4 v156, s[100:101]
	s_add_i32 m0, s59, 0xe000
	ds_read_b128 v[218:221], v172 offset:7168
	global_load_lds_dwordx4 v158, s[100:101]
	s_waitcnt vmcnt(8)
	s_waitcnt lgkmcnt(0)
	s_barrier
	s_setprio 1
	s_waitcnt lgkmcnt(0)
	v_mfma_f32_16x16x32_bf16 v[124:127], v[132:135], v[190:193], v[124:127]
	v_mfma_f32_16x16x32_bf16 v[120:123], v[140:143], v[190:193], v[120:123]
	v_mfma_f32_16x16x32_bf16 v[108:111], v[132:135], v[198:201], v[108:111]
	v_mfma_f32_16x16x32_bf16 v[104:107], v[140:143], v[198:201], v[104:107]
	v_mfma_f32_16x16x32_bf16 v[92:95], v[132:135], v[206:209], v[92:95]
	v_mfma_f32_16x16x32_bf16 v[88:91], v[140:143], v[206:209], v[88:91]
	v_mfma_f32_16x16x32_bf16 v[76:79], v[132:135], v[214:217], v[76:79]
	v_mfma_f32_16x16x32_bf16 v[72:75], v[140:143], v[214:217], v[72:75]
	v_mfma_f32_16x16x32_bf16 v[124:127], v[136:139], v[194:197], v[124:127]
	v_mfma_f32_16x16x32_bf16 v[120:123], v[164:167], v[194:197], v[120:123]
	v_mfma_f32_16x16x32_bf16 v[108:111], v[136:139], v[202:205], v[108:111]
	v_mfma_f32_16x16x32_bf16 v[104:107], v[164:167], v[202:205], v[104:107]
	v_mfma_f32_16x16x32_bf16 v[92:95], v[136:139], v[210:213], v[92:95]
	v_mfma_f32_16x16x32_bf16 v[88:91], v[164:167], v[210:213], v[88:91]
	v_mfma_f32_16x16x32_bf16 v[76:79], v[136:139], v[218:221], v[76:79]
	v_mfma_f32_16x16x32_bf16 v[72:75], v[164:167], v[218:221], v[72:75]
	s_setprio 0
	s_setprio 1
	v_mfma_f32_16x16x32_bf16 v[116:119], v[174:177], v[190:193], v[116:119]
	v_mfma_f32_16x16x32_bf16 v[112:115], v[182:185], v[190:193], v[112:115]
	v_mfma_f32_16x16x32_bf16 v[100:103], v[174:177], v[198:201], v[100:103]
	v_mfma_f32_16x16x32_bf16 v[96:99], v[182:185], v[198:201], v[96:99]
	v_mfma_f32_16x16x32_bf16 v[84:87], v[174:177], v[206:209], v[84:87]
	v_mfma_f32_16x16x32_bf16 v[80:83], v[182:185], v[206:209], v[80:83]
	v_mfma_f32_16x16x32_bf16 v[68:71], v[174:177], v[214:217], v[68:71]
	v_mfma_f32_16x16x32_bf16 v[64:67], v[182:185], v[214:217], v[64:67]
	v_mfma_f32_16x16x32_bf16 v[116:119], v[178:181], v[194:197], v[116:119]
	v_mfma_f32_16x16x32_bf16 v[112:115], v[186:189], v[194:197], v[112:115]
	v_mfma_f32_16x16x32_bf16 v[100:103], v[178:181], v[202:205], v[100:103]
	v_mfma_f32_16x16x32_bf16 v[96:99], v[186:189], v[202:205], v[96:99]
	v_mfma_f32_16x16x32_bf16 v[84:87], v[178:181], v[210:213], v[84:87]
	v_mfma_f32_16x16x32_bf16 v[80:83], v[186:189], v[210:213], v[80:83]
	v_mfma_f32_16x16x32_bf16 v[68:71], v[178:181], v[218:221], v[68:71]
	v_mfma_f32_16x16x32_bf16 v[64:67], v[186:189], v[218:221], v[64:67]
	s_setprio 0
	s_barrier
	s_add_i32 s10, s72, s58
	s_mov_b32 m0, s10
	ds_read_b128 v[190:193], v172 offset:16384
	ds_read_b128 v[194:197], v172 offset:17408
	ds_read_b128 v[198:201], v172 offset:18432
	global_load_lds_dwordx4 v146, s[54:55]
	s_add_i32 m0, s10, 0x2000
	ds_read_b128 v[202:205], v172 offset:19456
	global_load_lds_dwordx4 v150, s[54:55]
	s_add_u32 s54, s54, 0x40000
	s_addc_u32 s55, s55, 0
	s_add_i32 s10, s73, s58
	s_mov_b32 m0, s10
	ds_read_b128 v[206:209], v172 offset:20480
	global_load_lds_dwordx4 v146, s[54:55]
	s_add_i32 m0, s10, 0x2000
	ds_read_b128 v[210:213], v172 offset:21504
	global_load_lds_dwordx4 v150, s[54:55]
	s_mov_b32 m0, s59
	ds_read_b128 v[214:217], v172 offset:22528
	global_load_lds_dwordx4 v144, s[56:57]
	s_mov_b32 m0, s60
	ds_read_b128 v[218:221], v172 offset:23552
	global_load_lds_dwordx4 v148, s[56:57]
	s_waitcnt vmcnt(8)
	s_waitcnt lgkmcnt(0)
	s_barrier
	s_setprio 1
	s_waitcnt lgkmcnt(0)
	v_mfma_f32_16x16x32_bf16 v[60:63], v[132:135], v[190:193], v[60:63]
	v_mfma_f32_16x16x32_bf16 v[56:59], v[140:143], v[190:193], v[56:59]
	v_mfma_f32_16x16x32_bf16 v[44:47], v[132:135], v[198:201], v[44:47]
	v_mfma_f32_16x16x32_bf16 v[40:43], v[140:143], v[198:201], v[40:43]
	v_mfma_f32_16x16x32_bf16 v[28:31], v[132:135], v[206:209], v[28:31]
	v_mfma_f32_16x16x32_bf16 v[24:27], v[140:143], v[206:209], v[24:27]
	v_mfma_f32_16x16x32_bf16 v[12:15], v[132:135], v[214:217], v[12:15]
	v_mfma_f32_16x16x32_bf16 v[8:11], v[140:143], v[214:217], v[8:11]
	v_mfma_f32_16x16x32_bf16 v[60:63], v[136:139], v[194:197], v[60:63]
	v_mfma_f32_16x16x32_bf16 v[56:59], v[164:167], v[194:197], v[56:59]
	v_mfma_f32_16x16x32_bf16 v[44:47], v[136:139], v[202:205], v[44:47]
	v_mfma_f32_16x16x32_bf16 v[40:43], v[164:167], v[202:205], v[40:43]
	v_mfma_f32_16x16x32_bf16 v[28:31], v[136:139], v[210:213], v[28:31]
	v_mfma_f32_16x16x32_bf16 v[24:27], v[164:167], v[210:213], v[24:27]
	v_mfma_f32_16x16x32_bf16 v[12:15], v[136:139], v[218:221], v[12:15]
	v_mfma_f32_16x16x32_bf16 v[8:11], v[164:167], v[218:221], v[8:11]
	s_setprio 0
	s_setprio 1
	v_mfma_f32_16x16x32_bf16 v[52:55], v[174:177], v[190:193], v[52:55]
	v_mfma_f32_16x16x32_bf16 v[48:51], v[182:185], v[190:193], v[48:51]
	v_mfma_f32_16x16x32_bf16 v[36:39], v[174:177], v[198:201], v[36:39]
	v_mfma_f32_16x16x32_bf16 v[32:35], v[182:185], v[198:201], v[32:35]
	v_mfma_f32_16x16x32_bf16 v[20:23], v[174:177], v[206:209], v[20:23]
	v_mfma_f32_16x16x32_bf16 v[16:19], v[182:185], v[206:209], v[16:19]
	v_mfma_f32_16x16x32_bf16 v[4:7], v[174:177], v[214:217], v[4:7]
	v_mfma_f32_16x16x32_bf16 v[0:3], v[182:185], v[214:217], v[0:3]
	v_mfma_f32_16x16x32_bf16 v[52:55], v[178:181], v[194:197], v[52:55]
	v_mfma_f32_16x16x32_bf16 v[48:51], v[186:189], v[194:197], v[48:51]
	v_mfma_f32_16x16x32_bf16 v[36:39], v[178:181], v[202:205], v[36:39]
	v_mfma_f32_16x16x32_bf16 v[32:35], v[186:189], v[202:205], v[32:35]
	v_mfma_f32_16x16x32_bf16 v[20:23], v[178:181], v[210:213], v[20:23]
	v_mfma_f32_16x16x32_bf16 v[16:19], v[186:189], v[210:213], v[16:19]
	v_mfma_f32_16x16x32_bf16 v[4:7], v[178:181], v[218:221], v[4:7]
	v_mfma_f32_16x16x32_bf16 v[0:3], v[186:189], v[218:221], v[0:3]
	s_setprio 0
	s_barrier
	s_add_i32 s10, 0, 0x18000
	s_add_i32 s83, 0, 0x1c000
	ds_read_b128 v[132:135], v168 offset:32768
	ds_read_b128 v[136:139], v168 offset:33792
	ds_read_b128 v[140:143], v168 offset:34816
	ds_read_b128 v[164:167], v168 offset:35840
	ds_read_b128 v[174:177], v168 offset:49152
	ds_read_b128 v[178:181], v168 offset:50176
	ds_read_b128 v[182:185], v168 offset:51200
	ds_read_b128 v[186:189], v168 offset:52224
	s_add_u32 s54, s56, 0x40000
	s_addc_u32 s55, s57, 0
	s_mov_b32 m0, s61
	ds_read_b128 v[190:193], v172 offset:32768
	ds_read_b128 v[194:197], v172 offset:33792
	ds_read_b128 v[198:201], v172 offset:34816
	ds_read_b128 v[202:205], v172 offset:35840
	ds_read_b128 v[206:209], v172 offset:36864
	ds_read_b128 v[210:213], v172 offset:37888
	ds_read_b128 v[214:217], v172 offset:38912
	global_load_lds_dwordx4 v144, s[54:55]
	s_mov_b32 m0, s62
	ds_read_b128 v[218:221], v172 offset:39936
	global_load_lds_dwordx4 v148, s[54:55]
	s_waitcnt vmcnt(8)
	s_waitcnt lgkmcnt(0)
	s_barrier
	s_setprio 1
	s_waitcnt lgkmcnt(0)
	v_mfma_f32_16x16x32_bf16 v[124:127], v[132:135], v[190:193], v[124:127]
	v_mfma_f32_16x16x32_bf16 v[120:123], v[140:143], v[190:193], v[120:123]
	v_mfma_f32_16x16x32_bf16 v[108:111], v[132:135], v[198:201], v[108:111]
	v_mfma_f32_16x16x32_bf16 v[104:107], v[140:143], v[198:201], v[104:107]
	v_mfma_f32_16x16x32_bf16 v[92:95], v[132:135], v[206:209], v[92:95]
	v_mfma_f32_16x16x32_bf16 v[88:91], v[140:143], v[206:209], v[88:91]
	v_mfma_f32_16x16x32_bf16 v[76:79], v[132:135], v[214:217], v[76:79]
	v_mfma_f32_16x16x32_bf16 v[72:75], v[140:143], v[214:217], v[72:75]
	v_mfma_f32_16x16x32_bf16 v[124:127], v[136:139], v[194:197], v[124:127]
	v_mfma_f32_16x16x32_bf16 v[120:123], v[164:167], v[194:197], v[120:123]
	v_mfma_f32_16x16x32_bf16 v[108:111], v[136:139], v[202:205], v[108:111]
	v_mfma_f32_16x16x32_bf16 v[104:107], v[164:167], v[202:205], v[104:107]
	v_mfma_f32_16x16x32_bf16 v[92:95], v[136:139], v[210:213], v[92:95]
	v_mfma_f32_16x16x32_bf16 v[88:91], v[164:167], v[210:213], v[88:91]
	v_mfma_f32_16x16x32_bf16 v[76:79], v[136:139], v[218:221], v[76:79]
	v_mfma_f32_16x16x32_bf16 v[72:75], v[164:167], v[218:221], v[72:75]
	s_setprio 0
	s_setprio 1
	v_mfma_f32_16x16x32_bf16 v[116:119], v[174:177], v[190:193], v[116:119]
	v_mfma_f32_16x16x32_bf16 v[112:115], v[182:185], v[190:193], v[112:115]
	v_mfma_f32_16x16x32_bf16 v[100:103], v[174:177], v[198:201], v[100:103]
	v_mfma_f32_16x16x32_bf16 v[96:99], v[182:185], v[198:201], v[96:99]
	v_mfma_f32_16x16x32_bf16 v[84:87], v[174:177], v[206:209], v[84:87]
	v_mfma_f32_16x16x32_bf16 v[80:83], v[182:185], v[206:209], v[80:83]
	v_mfma_f32_16x16x32_bf16 v[68:71], v[174:177], v[214:217], v[68:71]
	v_mfma_f32_16x16x32_bf16 v[64:67], v[182:185], v[214:217], v[64:67]
	v_mfma_f32_16x16x32_bf16 v[116:119], v[178:181], v[194:197], v[116:119]
	v_mfma_f32_16x16x32_bf16 v[112:115], v[186:189], v[194:197], v[112:115]
	v_mfma_f32_16x16x32_bf16 v[100:103], v[178:181], v[202:205], v[100:103]
	v_mfma_f32_16x16x32_bf16 v[96:99], v[186:189], v[202:205], v[96:99]
	v_mfma_f32_16x16x32_bf16 v[84:87], v[178:181], v[210:213], v[84:87]
	v_mfma_f32_16x16x32_bf16 v[80:83], v[186:189], v[210:213], v[80:83]
	v_mfma_f32_16x16x32_bf16 v[68:71], v[178:181], v[218:221], v[68:71]
	v_mfma_f32_16x16x32_bf16 v[64:67], v[186:189], v[218:221], v[64:67]
	s_setprio 0
	s_barrier
	s_add_i32 s10, s10, s58
	s_mov_b32 m0, s10
	ds_read_b128 v[190:193], v172 offset:49152
	ds_read_b128 v[194:197], v172 offset:50176
	ds_read_b128 v[198:201], v172 offset:51200
	global_load_lds_dwordx4 v146, s[52:53]
	s_add_i32 m0, s10, 0x2000
	ds_read_b128 v[202:205], v172 offset:52224
	global_load_lds_dwordx4 v150, s[52:53]
	s_add_u32 s52, s52, 0x40000
	s_addc_u32 s53, s53, 0
	s_add_i32 s10, s83, s58
	s_mov_b32 m0, s10
	ds_read_b128 v[206:209], v172 offset:53248
	global_load_lds_dwordx4 v146, s[52:53]
	s_add_i32 m0, s10, 0x2000
	ds_read_b128 v[210:213], v172 offset:54272
	global_load_lds_dwordx4 v150, s[52:53]
	s_mov_b32 m0, s68
	ds_read_b128 v[214:217], v172 offset:55296
	global_load_lds_dwordx4 v144, s[50:51]
	s_mov_b32 m0, s69
	ds_read_b128 v[218:221], v172 offset:56320
	global_load_lds_dwordx4 v148, s[50:51]
	s_waitcnt vmcnt(8)
	s_waitcnt lgkmcnt(0)
	s_barrier
	s_setprio 1
	s_waitcnt lgkmcnt(0)
	v_mfma_f32_16x16x32_bf16 v[60:63], v[132:135], v[190:193], v[60:63]
	v_mfma_f32_16x16x32_bf16 v[56:59], v[140:143], v[190:193], v[56:59]
	v_mfma_f32_16x16x32_bf16 v[44:47], v[132:135], v[198:201], v[44:47]
	v_mfma_f32_16x16x32_bf16 v[40:43], v[140:143], v[198:201], v[40:43]
	v_mfma_f32_16x16x32_bf16 v[28:31], v[132:135], v[206:209], v[28:31]
	v_mfma_f32_16x16x32_bf16 v[24:27], v[140:143], v[206:209], v[24:27]
	v_mfma_f32_16x16x32_bf16 v[12:15], v[132:135], v[214:217], v[12:15]
	v_mfma_f32_16x16x32_bf16 v[8:11], v[140:143], v[214:217], v[8:11]
	v_mfma_f32_16x16x32_bf16 v[60:63], v[136:139], v[194:197], v[60:63]
	v_mfma_f32_16x16x32_bf16 v[56:59], v[164:167], v[194:197], v[56:59]
	v_mfma_f32_16x16x32_bf16 v[44:47], v[136:139], v[202:205], v[44:47]
	v_mfma_f32_16x16x32_bf16 v[40:43], v[164:167], v[202:205], v[40:43]
	v_mfma_f32_16x16x32_bf16 v[28:31], v[136:139], v[210:213], v[28:31]
	v_mfma_f32_16x16x32_bf16 v[24:27], v[164:167], v[210:213], v[24:27]
	v_mfma_f32_16x16x32_bf16 v[12:15], v[136:139], v[218:221], v[12:15]
	v_mfma_f32_16x16x32_bf16 v[8:11], v[164:167], v[218:221], v[8:11]
	s_setprio 0
	s_setprio 1
	v_mfma_f32_16x16x32_bf16 v[52:55], v[174:177], v[190:193], v[52:55]
	v_mfma_f32_16x16x32_bf16 v[48:51], v[182:185], v[190:193], v[48:51]
	v_mfma_f32_16x16x32_bf16 v[36:39], v[174:177], v[198:201], v[36:39]
	v_mfma_f32_16x16x32_bf16 v[32:35], v[182:185], v[198:201], v[32:35]
	v_mfma_f32_16x16x32_bf16 v[20:23], v[174:177], v[206:209], v[20:23]
	v_mfma_f32_16x16x32_bf16 v[16:19], v[182:185], v[206:209], v[16:19]
	v_mfma_f32_16x16x32_bf16 v[4:7], v[174:177], v[214:217], v[4:7]
	v_mfma_f32_16x16x32_bf16 v[0:3], v[182:185], v[214:217], v[0:3]
	v_mfma_f32_16x16x32_bf16 v[52:55], v[178:181], v[194:197], v[52:55]
	v_mfma_f32_16x16x32_bf16 v[48:51], v[186:189], v[194:197], v[48:51]
	v_mfma_f32_16x16x32_bf16 v[36:39], v[178:181], v[202:205], v[36:39]
	v_mfma_f32_16x16x32_bf16 v[32:35], v[186:189], v[202:205], v[32:35]
	v_mfma_f32_16x16x32_bf16 v[20:23], v[178:181], v[210:213], v[20:23]
	v_mfma_f32_16x16x32_bf16 v[16:19], v[186:189], v[210:213], v[16:19]
	v_mfma_f32_16x16x32_bf16 v[4:7], v[178:181], v[218:221], v[4:7]
	v_mfma_f32_16x16x32_bf16 v[0:3], v[186:189], v[218:221], v[0:3]
	s_setprio 0
	s_barrier
	s_add_i32 s10, s82, 2
	s_add_u32 s48, s48, 0x100
	s_addc_u32 s49, s49, 0
	s_cmp_gt_u32 s82, 13
	s_mov_b32 s82, s10
	s_cbranch_scc1 .LBB0_721
.LBB0_715:
	s_add_u32 s56, s44, s48
	s_addc_u32 s57, s45, s49
	s_mov_b64 s[100:101], s[56:57]
	s_add_u32 s84, s38, s48
	s_addc_u32 s83, s39, s49
	s_add_u32 s50, s56, 0x180
	s_addc_u32 s51, s57, 0
	s_add_u32 s52, s84, 0x180
	s_addc_u32 s53, s83, 0
	s_add_u32 s56, s56, 0x100
	s_addc_u32 s57, s57, 0
	s_add_u32 s54, s84, 0x100
	s_addc_u32 s55, s83, 0
	s_cmpk_eq_i32 s48, 0x700
	s_cselect_b32 s50, s36, s50
	s_cselect_b32 s51, s37, s51
	s_cselect_b32 s52, s46, s52
	s_cselect_b32 s53, s47, s53
	s_cselect_b32 s56, s80, s56
	s_cselect_b32 s57, s23, s57
	s_cselect_b32 s54, s81, s54
	s_cselect_b32 s55, s21, s55
	s_branch .LBB0_714

.LBB0_805:
	s_add_u32 s27, s61, s4
	s_addc_u32 s72, s62, s5
	s_add_u32 s73, s63, s6
	s_addc_u32 s78, s64, s7
	s_ashr_i32 s21, s20, 31
	s_lshl_b64 s[4:5], s[20:21], 19
	s_add_u32 s22, s40, s4
	s_addc_u32 s23, s41, s5
	s_and_b64 s[6:7], s[0:1], exec
	s_cselect_b32 s21, s23, s31
	s_cselect_b32 s79, s22, s30
	s_ashr_i32 s19, s18, 31
	s_lshl_b64 s[6:7], s[18:19], 19
	s_add_u32 s24, s42, s6
	s_addc_u32 s25, s43, s7
	s_and_b64 s[36:37], s[0:1], exec
	s_cselect_b32 s19, s25, s29
	s_cselect_b32 s80, s24, s28
	s_add_u32 s36, s79, 0x80
	s_addc_u32 s37, s21, 0
	s_add_u32 s38, s80, 0x80
	s_addc_u32 s39, s19, 0
	v_lshl_add_u64 v[148:149], s[30:31], 0, v[140:141]
	v_lshl_add_u64 v[150:151], s[30:31], 0, v[142:143]
	s_mov_b32 s81, 0
	s_mov_b64 s[44:45], 0
	v_add_u32_e32 v154, 0x10000, v157
	s_add_u32 s52, s30, s44
	s_addc_u32 s53, s31, s45
	s_mov_b64 s[100:101], s[52:53]
	s_add_u32 s83, s28, s44
	s_addc_u32 s82, s29, s45
	s_add_u32 s46, s52, 0x180
	s_addc_u32 s47, s53, 0
	s_add_u32 s48, s83, 0x180
	s_addc_u32 s49, s82, 0
	s_add_u32 s52, s52, 0x100
	s_addc_u32 s53, s53, 0
	s_add_u32 s50, s83, 0x100
	s_addc_u32 s51, s82, 0
	s_cmpk_eq_i32 s44, 0x700
	s_cselect_b32 s46, s36, s46
	s_cselect_b32 s47, s37, s47
	s_cselect_b32 s48, s38, s48
	s_cselect_b32 s49, s39, s49
	s_cselect_b32 s52, s79, s52
	s_cselect_b32 s53, s21, s53
	s_cselect_b32 s50, s80, s50
	s_cselect_b32 s51, s19, s51
	ds_read_b128 v[166:169], v154
	ds_read_b128 v[170:173], v154 offset:1024
	ds_read_b128 v[174:177], v154 offset:2048
	ds_read_b128 v[178:181], v154 offset:3072
	ds_read_b128 v[182:185], v154 offset:16384
	ds_read_b128 v[186:189], v154 offset:17408
	ds_read_b128 v[190:193], v154 offset:18432
	ds_read_b128 v[194:197], v154 offset:19456
	s_add_i32 m0, s57, 0xc000
	ds_read_b128 v[198:201], v161
	ds_read_b128 v[202:205], v161 offset:1024
	ds_read_b128 v[206:209], v161 offset:2048
	ds_read_b128 v[210:213], v161 offset:3072
	ds_read_b128 v[214:217], v161 offset:4096
	ds_read_b128 v[218:221], v161 offset:5120
	ds_read_b128 v[222:225], v161 offset:6144
	global_load_lds_dwordx4 v140, s[100:101]
	s_add_i32 m0, s57, 0xe000
	ds_read_b128 v[226:229], v161 offset:7168
	global_load_lds_dwordx4 v142, s[100:101]
	s_waitcnt vmcnt(8)
	s_waitcnt lgkmcnt(0)
	s_barrier
	s_setprio 1
	s_waitcnt lgkmcnt(0)
	v_mfma_f32_16x16x32_bf16 v[124:127], v[166:169], v[198:201], 0
	v_mfma_f32_16x16x32_bf16 v[120:123], v[174:177], v[198:201], 0
	v_mfma_f32_16x16x32_bf16 v[108:111], v[166:169], v[206:209], 0
	v_mfma_f32_16x16x32_bf16 v[104:107], v[174:177], v[206:209], 0
	v_mfma_f32_16x16x32_bf16 v[92:95], v[166:169], v[214:217], 0
	v_mfma_f32_16x16x32_bf16 v[88:91], v[174:177], v[214:217], 0
	v_mfma_f32_16x16x32_bf16 v[76:79], v[166:169], v[222:225], 0
	v_mfma_f32_16x16x32_bf16 v[72:75], v[174:177], v[222:225], 0
	v_mfma_f32_16x16x32_bf16 v[124:127], v[170:173], v[202:205], v[124:127]
	v_mfma_f32_16x16x32_bf16 v[120:123], v[178:181], v[202:205], v[120:123]
	v_mfma_f32_16x16x32_bf16 v[108:111], v[170:173], v[210:213], v[108:111]
	v_mfma_f32_16x16x32_bf16 v[104:107], v[178:181], v[210:213], v[104:107]
	v_mfma_f32_16x16x32_bf16 v[92:95], v[170:173], v[218:221], v[92:95]
	v_mfma_f32_16x16x32_bf16 v[88:91], v[178:181], v[218:221], v[88:91]
	v_mfma_f32_16x16x32_bf16 v[76:79], v[170:173], v[226:229], v[76:79]
	v_mfma_f32_16x16x32_bf16 v[72:75], v[178:181], v[226:229], v[72:75]
	s_setprio 0
	s_setprio 1
	v_mfma_f32_16x16x32_bf16 v[116:119], v[182:185], v[198:201], 0
	v_mfma_f32_16x16x32_bf16 v[112:115], v[190:193], v[198:201], 0
	v_mfma_f32_16x16x32_bf16 v[100:103], v[182:185], v[206:209], 0
	v_mfma_f32_16x16x32_bf16 v[96:99], v[190:193], v[206:209], 0
	v_mfma_f32_16x16x32_bf16 v[84:87], v[182:185], v[214:217], 0
	v_mfma_f32_16x16x32_bf16 v[80:83], v[190:193], v[214:217], 0
	v_mfma_f32_16x16x32_bf16 v[68:71], v[182:185], v[222:225], 0
	v_mfma_f32_16x16x32_bf16 v[64:67], v[190:193], v[222:225], 0
	v_mfma_f32_16x16x32_bf16 v[116:119], v[186:189], v[202:205], v[116:119]
	v_mfma_f32_16x16x32_bf16 v[112:115], v[194:197], v[202:205], v[112:115]
	v_mfma_f32_16x16x32_bf16 v[100:103], v[186:189], v[210:213], v[100:103]
	v_mfma_f32_16x16x32_bf16 v[96:99], v[194:197], v[210:213], v[96:99]
	v_mfma_f32_16x16x32_bf16 v[84:87], v[186:189], v[218:221], v[84:87]
	v_mfma_f32_16x16x32_bf16 v[80:83], v[194:197], v[218:221], v[80:83]
	v_mfma_f32_16x16x32_bf16 v[68:71], v[186:189], v[226:229], v[68:71]
	v_mfma_f32_16x16x32_bf16 v[64:67], v[194:197], v[226:229], v[64:67]
	s_setprio 0
	s_barrier
	s_add_i32 s8, s68, s54
	s_mov_b32 m0, s8
	ds_read_b128 v[198:201], v161 offset:16384
	ds_read_b128 v[202:205], v161 offset:17408
	ds_read_b128 v[206:209], v161 offset:18432
	global_load_lds_dwordx4 v128, s[50:51]
	s_add_i32 m0, s8, 0x2000
	ds_read_b128 v[210:213], v161 offset:19456
	global_load_lds_dwordx4 v130, s[50:51]
	s_add_u32 s50, s50, 0x40000
	s_addc_u32 s51, s51, 0
	s_add_i32 s8, s69, s54
	s_mov_b32 m0, s8
	ds_read_b128 v[214:217], v161 offset:20480
	global_load_lds_dwordx4 v128, s[50:51]
	s_add_i32 m0, s8, 0x2000
	ds_read_b128 v[218:221], v161 offset:21504
	global_load_lds_dwordx4 v130, s[50:51]
	s_mov_b32 m0, s57
	ds_read_b128 v[222:225], v161 offset:22528
	global_load_lds_dwordx4 v134, s[52:53]
	s_mov_b32 m0, s58
	ds_read_b128 v[226:229], v161 offset:23552
	global_load_lds_dwordx4 v132, s[52:53]
	s_waitcnt vmcnt(8)
	s_waitcnt lgkmcnt(0)
	s_barrier
	s_setprio 1
	s_waitcnt lgkmcnt(0)
	v_mfma_f32_16x16x32_bf16 v[60:63], v[166:169], v[198:201], 0
	v_mfma_f32_16x16x32_bf16 v[56:59], v[174:177], v[198:201], 0
	v_mfma_f32_16x16x32_bf16 v[44:47], v[166:169], v[206:209], 0
	v_mfma_f32_16x16x32_bf16 v[40:43], v[174:177], v[206:209], 0
	v_mfma_f32_16x16x32_bf16 v[28:31], v[166:169], v[214:217], 0
	v_mfma_f32_16x16x32_bf16 v[24:27], v[174:177], v[214:217], 0
	v_mfma_f32_16x16x32_bf16 v[12:15], v[166:169], v[222:225], 0
	v_mfma_f32_16x16x32_bf16 v[8:11], v[174:177], v[222:225], 0
	v_mfma_f32_16x16x32_bf16 v[60:63], v[170:173], v[202:205], v[60:63]
	v_mfma_f32_16x16x32_bf16 v[56:59], v[178:181], v[202:205], v[56:59]
	v_mfma_f32_16x16x32_bf16 v[44:47], v[170:173], v[210:213], v[44:47]
	v_mfma_f32_16x16x32_bf16 v[40:43], v[178:181], v[210:213], v[40:43]
	v_mfma_f32_16x16x32_bf16 v[28:31], v[170:173], v[218:221], v[28:31]
	v_mfma_f32_16x16x32_bf16 v[24:27], v[178:181], v[218:221], v[24:27]
	v_mfma_f32_16x16x32_bf16 v[12:15], v[170:173], v[226:229], v[12:15]
	v_mfma_f32_16x16x32_bf16 v[8:11], v[178:181], v[226:229], v[8:11]
	s_setprio 0
	s_setprio 1
	v_mfma_f32_16x16x32_bf16 v[52:55], v[182:185], v[198:201], 0
	v_mfma_f32_16x16x32_bf16 v[48:51], v[190:193], v[198:201], 0
	v_mfma_f32_16x16x32_bf16 v[36:39], v[182:185], v[206:209], 0
	v_mfma_f32_16x16x32_bf16 v[32:35], v[190:193], v[206:209], 0
	v_mfma_f32_16x16x32_bf16 v[20:23], v[182:185], v[214:217], 0
	v_mfma_f32_16x16x32_bf16 v[16:19], v[190:193], v[214:217], 0
	v_mfma_f32_16x16x32_bf16 v[4:7], v[182:185], v[222:225], 0
	v_mfma_f32_16x16x32_bf16 v[0:3], v[190:193], v[222:225], 0
	v_mfma_f32_16x16x32_bf16 v[52:55], v[186:189], v[202:205], v[52:55]
	v_mfma_f32_16x16x32_bf16 v[48:51], v[194:197], v[202:205], v[48:51]
	v_mfma_f32_16x16x32_bf16 v[36:39], v[186:189], v[210:213], v[36:39]
	v_mfma_f32_16x16x32_bf16 v[32:35], v[194:197], v[210:213], v[32:35]
	v_mfma_f32_16x16x32_bf16 v[20:23], v[186:189], v[218:221], v[20:23]
	v_mfma_f32_16x16x32_bf16 v[16:19], v[194:197], v[218:221], v[16:19]
	v_mfma_f32_16x16x32_bf16 v[4:7], v[186:189], v[226:229], v[4:7]
	v_mfma_f32_16x16x32_bf16 v[0:3], v[194:197], v[226:229], v[0:3]
	s_setprio 0
	s_barrier
	s_add_i32 s8, 0, 0x18000
	s_add_i32 s82, 0, 0x1c000
	ds_read_b128 v[166:169], v154 offset:32768
	ds_read_b128 v[170:173], v154 offset:33792
	ds_read_b128 v[174:177], v154 offset:34816
	ds_read_b128 v[178:181], v154 offset:35840
	ds_read_b128 v[182:185], v154 offset:49152
	ds_read_b128 v[186:189], v154 offset:50176
	ds_read_b128 v[190:193], v154 offset:51200
	ds_read_b128 v[194:197], v154 offset:52224
	s_add_u32 s50, s52, 0x40000
	s_addc_u32 s51, s53, 0
	s_mov_b32 m0, s59
	ds_read_b128 v[198:201], v161 offset:32768
	ds_read_b128 v[202:205], v161 offset:33792
	ds_read_b128 v[206:209], v161 offset:34816
	ds_read_b128 v[210:213], v161 offset:35840
	ds_read_b128 v[214:217], v161 offset:36864
	ds_read_b128 v[218:221], v161 offset:37888
	ds_read_b128 v[222:225], v161 offset:38912
	global_load_lds_dwordx4 v134, s[50:51]
	s_mov_b32 m0, s60
	ds_read_b128 v[226:229], v161 offset:39936
	global_load_lds_dwordx4 v132, s[50:51]
	s_waitcnt vmcnt(8)
	s_waitcnt lgkmcnt(0)
	s_barrier
	s_setprio 1
	s_waitcnt lgkmcnt(0)
	v_mfma_f32_16x16x32_bf16 v[124:127], v[166:169], v[198:201], v[124:127]
	v_mfma_f32_16x16x32_bf16 v[120:123], v[174:177], v[198:201], v[120:123]
	v_mfma_f32_16x16x32_bf16 v[108:111], v[166:169], v[206:209], v[108:111]
	v_mfma_f32_16x16x32_bf16 v[104:107], v[174:177], v[206:209], v[104:107]
	v_mfma_f32_16x16x32_bf16 v[92:95], v[166:169], v[214:217], v[92:95]
	v_mfma_f32_16x16x32_bf16 v[88:91], v[174:177], v[214:217], v[88:91]
	v_mfma_f32_16x16x32_bf16 v[76:79], v[166:169], v[222:225], v[76:79]
	v_mfma_f32_16x16x32_bf16 v[72:75], v[174:177], v[222:225], v[72:75]
	v_mfma_f32_16x16x32_bf16 v[124:127], v[170:173], v[202:205], v[124:127]
	v_mfma_f32_16x16x32_bf16 v[120:123], v[178:181], v[202:205], v[120:123]
	v_mfma_f32_16x16x32_bf16 v[108:111], v[170:173], v[210:213], v[108:111]
	v_mfma_f32_16x16x32_bf16 v[104:107], v[178:181], v[210:213], v[104:107]
	v_mfma_f32_16x16x32_bf16 v[92:95], v[170:173], v[218:221], v[92:95]
	v_mfma_f32_16x16x32_bf16 v[88:91], v[178:181], v[218:221], v[88:91]
	v_mfma_f32_16x16x32_bf16 v[76:79], v[170:173], v[226:229], v[76:79]
	v_mfma_f32_16x16x32_bf16 v[72:75], v[178:181], v[226:229], v[72:75]
	s_setprio 0
	s_setprio 1
	v_mfma_f32_16x16x32_bf16 v[116:119], v[182:185], v[198:201], v[116:119]
	v_mfma_f32_16x16x32_bf16 v[112:115], v[190:193], v[198:201], v[112:115]
	v_mfma_f32_16x16x32_bf16 v[100:103], v[182:185], v[206:209], v[100:103]
	v_mfma_f32_16x16x32_bf16 v[96:99], v[190:193], v[206:209], v[96:99]
	v_mfma_f32_16x16x32_bf16 v[84:87], v[182:185], v[214:217], v[84:87]
	v_mfma_f32_16x16x32_bf16 v[80:83], v[190:193], v[214:217], v[80:83]
	v_mfma_f32_16x16x32_bf16 v[68:71], v[182:185], v[222:225], v[68:71]
	v_mfma_f32_16x16x32_bf16 v[64:67], v[190:193], v[222:225], v[64:67]
	v_mfma_f32_16x16x32_bf16 v[116:119], v[186:189], v[202:205], v[116:119]
	v_mfma_f32_16x16x32_bf16 v[112:115], v[194:197], v[202:205], v[112:115]
	v_mfma_f32_16x16x32_bf16 v[100:103], v[186:189], v[210:213], v[100:103]
	v_mfma_f32_16x16x32_bf16 v[96:99], v[194:197], v[210:213], v[96:99]
	v_mfma_f32_16x16x32_bf16 v[84:87], v[186:189], v[218:221], v[84:87]
	v_mfma_f32_16x16x32_bf16 v[80:83], v[194:197], v[218:221], v[80:83]
	v_mfma_f32_16x16x32_bf16 v[68:71], v[186:189], v[226:229], v[68:71]
	v_mfma_f32_16x16x32_bf16 v[64:67], v[194:197], v[226:229], v[64:67]
	s_setprio 0
	s_barrier
	s_add_i32 s8, s8, s54
	s_mov_b32 m0, s8
	ds_read_b128 v[198:201], v161 offset:49152
	ds_read_b128 v[202:205], v161 offset:50176
	ds_read_b128 v[206:209], v161 offset:51200
	global_load_lds_dwordx4 v128, s[48:49]
	s_add_i32 m0, s8, 0x2000
	ds_read_b128 v[210:213], v161 offset:52224
	global_load_lds_dwordx4 v130, s[48:49]
	s_add_u32 s48, s48, 0x40000
	s_addc_u32 s49, s49, 0
	s_add_i32 s8, s82, s54
	s_mov_b32 m0, s8
	ds_read_b128 v[214:217], v161 offset:53248
	global_load_lds_dwordx4 v128, s[48:49]
	s_add_i32 m0, s8, 0x2000
	ds_read_b128 v[218:221], v161 offset:54272
	global_load_lds_dwordx4 v130, s[48:49]
	s_mov_b32 m0, s65
	ds_read_b128 v[222:225], v161 offset:55296
	global_load_lds_dwordx4 v134, s[46:47]
	s_mov_b32 m0, s66
	ds_read_b128 v[226:229], v161 offset:56320
	global_load_lds_dwordx4 v132, s[46:47]
	s_waitcnt vmcnt(8)
	s_waitcnt lgkmcnt(0)
	s_barrier
	s_setprio 1
	s_waitcnt lgkmcnt(0)
	v_mfma_f32_16x16x32_bf16 v[60:63], v[166:169], v[198:201], v[60:63]
	v_mfma_f32_16x16x32_bf16 v[56:59], v[174:177], v[198:201], v[56:59]
	v_mfma_f32_16x16x32_bf16 v[44:47], v[166:169], v[206:209], v[44:47]
	v_mfma_f32_16x16x32_bf16 v[40:43], v[174:177], v[206:209], v[40:43]
	v_mfma_f32_16x16x32_bf16 v[28:31], v[166:169], v[214:217], v[28:31]
	v_mfma_f32_16x16x32_bf16 v[24:27], v[174:177], v[214:217], v[24:27]
	v_mfma_f32_16x16x32_bf16 v[12:15], v[166:169], v[222:225], v[12:15]
	v_mfma_f32_16x16x32_bf16 v[8:11], v[174:177], v[222:225], v[8:11]
	v_mfma_f32_16x16x32_bf16 v[60:63], v[170:173], v[202:205], v[60:63]
	v_mfma_f32_16x16x32_bf16 v[56:59], v[178:181], v[202:205], v[56:59]
	v_mfma_f32_16x16x32_bf16 v[44:47], v[170:173], v[210:213], v[44:47]
	v_mfma_f32_16x16x32_bf16 v[40:43], v[178:181], v[210:213], v[40:43]
	v_mfma_f32_16x16x32_bf16 v[28:31], v[170:173], v[218:221], v[28:31]
	v_mfma_f32_16x16x32_bf16 v[24:27], v[178:181], v[218:221], v[24:27]
	v_mfma_f32_16x16x32_bf16 v[12:15], v[170:173], v[226:229], v[12:15]
	v_mfma_f32_16x16x32_bf16 v[8:11], v[178:181], v[226:229], v[8:11]
	s_setprio 0
	s_setprio 1
	v_mfma_f32_16x16x32_bf16 v[52:55], v[182:185], v[198:201], v[52:55]
	v_mfma_f32_16x16x32_bf16 v[48:51], v[190:193], v[198:201], v[48:51]
	v_mfma_f32_16x16x32_bf16 v[36:39], v[182:185], v[206:209], v[36:39]
	v_mfma_f32_16x16x32_bf16 v[32:35], v[190:193], v[206:209], v[32:35]
	v_mfma_f32_16x16x32_bf16 v[20:23], v[182:185], v[214:217], v[20:23]
	v_mfma_f32_16x16x32_bf16 v[16:19], v[190:193], v[214:217], v[16:19]
	v_mfma_f32_16x16x32_bf16 v[4:7], v[182:185], v[222:225], v[4:7]
	v_mfma_f32_16x16x32_bf16 v[0:3], v[190:193], v[222:225], v[0:3]
	v_mfma_f32_16x16x32_bf16 v[52:55], v[186:189], v[202:205], v[52:55]
	v_mfma_f32_16x16x32_bf16 v[48:51], v[194:197], v[202:205], v[48:51]
	v_mfma_f32_16x16x32_bf16 v[36:39], v[186:189], v[210:213], v[36:39]
	v_mfma_f32_16x16x32_bf16 v[32:35], v[194:197], v[210:213], v[32:35]
	v_mfma_f32_16x16x32_bf16 v[20:23], v[186:189], v[218:221], v[20:23]
	v_mfma_f32_16x16x32_bf16 v[16:19], v[194:197], v[218:221], v[16:19]
	v_mfma_f32_16x16x32_bf16 v[4:7], v[186:189], v[226:229], v[4:7]
	v_mfma_f32_16x16x32_bf16 v[0:3], v[194:197], v[226:229], v[0:3]
	s_setprio 0
	s_barrier
	s_add_i32 s8, s81, 2
	s_add_u32 s44, s44, 0x100
	s_addc_u32 s45, s45, 0
	s_cmp_gt_u32 s81, 13
	s_mov_b32 s81, s8
	s_cbranch_scc1 .LBB0_813
	s_branch .LBB0_807
.LBB0_806:
	ds_read_b128 v[166:169], v154
	ds_read_b128 v[170:173], v154 offset:1024
	ds_read_b128 v[174:177], v154 offset:2048
	ds_read_b128 v[178:181], v154 offset:3072
	ds_read_b128 v[182:185], v154 offset:16384
	ds_read_b128 v[186:189], v154 offset:17408
	ds_read_b128 v[190:193], v154 offset:18432
	ds_read_b128 v[194:197], v154 offset:19456
	s_add_i32 m0, s57, 0xc000
	ds_read_b128 v[198:201], v161
	ds_read_b128 v[202:205], v161 offset:1024
	ds_read_b128 v[206:209], v161 offset:2048
	ds_read_b128 v[210:213], v161 offset:3072
	ds_read_b128 v[214:217], v161 offset:4096
	ds_read_b128 v[218:221], v161 offset:5120
	ds_read_b128 v[222:225], v161 offset:6144
	global_load_lds_dwordx4 v140, s[100:101]
	s_add_i32 m0, s57, 0xe000
	ds_read_b128 v[226:229], v161 offset:7168
	global_load_lds_dwordx4 v142, s[100:101]
	s_waitcnt vmcnt(8)
	s_waitcnt lgkmcnt(0)
	s_barrier
	s_setprio 1
	s_waitcnt lgkmcnt(0)
	v_mfma_f32_16x16x32_bf16 v[124:127], v[166:169], v[198:201], v[124:127]
	v_mfma_f32_16x16x32_bf16 v[120:123], v[174:177], v[198:201], v[120:123]
	v_mfma_f32_16x16x32_bf16 v[108:111], v[166:169], v[206:209], v[108:111]
	v_mfma_f32_16x16x32_bf16 v[104:107], v[174:177], v[206:209], v[104:107]
	v_mfma_f32_16x16x32_bf16 v[92:95], v[166:169], v[214:217], v[92:95]
	v_mfma_f32_16x16x32_bf16 v[88:91], v[174:177], v[214:217], v[88:91]
	v_mfma_f32_16x16x32_bf16 v[76:79], v[166:169], v[222:225], v[76:79]
	v_mfma_f32_16x16x32_bf16 v[72:75], v[174:177], v[222:225], v[72:75]
	v_mfma_f32_16x16x32_bf16 v[124:127], v[170:173], v[202:205], v[124:127]
	v_mfma_f32_16x16x32_bf16 v[120:123], v[178:181], v[202:205], v[120:123]
	v_mfma_f32_16x16x32_bf16 v[108:111], v[170:173], v[210:213], v[108:111]
	v_mfma_f32_16x16x32_bf16 v[104:107], v[178:181], v[210:213], v[104:107]
	v_mfma_f32_16x16x32_bf16 v[92:95], v[170:173], v[218:221], v[92:95]
	v_mfma_f32_16x16x32_bf16 v[88:91], v[178:181], v[218:221], v[88:91]
	v_mfma_f32_16x16x32_bf16 v[76:79], v[170:173], v[226:229], v[76:79]
	v_mfma_f32_16x16x32_bf16 v[72:75], v[178:181], v[226:229], v[72:75]
	s_setprio 0
	s_setprio 1
	v_mfma_f32_16x16x32_bf16 v[116:119], v[182:185], v[198:201], v[116:119]
	v_mfma_f32_16x16x32_bf16 v[112:115], v[190:193], v[198:201], v[112:115]
	v_mfma_f32_16x16x32_bf16 v[100:103], v[182:185], v[206:209], v[100:103]
	v_mfma_f32_16x16x32_bf16 v[96:99], v[190:193], v[206:209], v[96:99]
	v_mfma_f32_16x16x32_bf16 v[84:87], v[182:185], v[214:217], v[84:87]
	v_mfma_f32_16x16x32_bf16 v[80:83], v[190:193], v[214:217], v[80:83]
	v_mfma_f32_16x16x32_bf16 v[68:71], v[182:185], v[222:225], v[68:71]
	v_mfma_f32_16x16x32_bf16 v[64:67], v[190:193], v[222:225], v[64:67]
	v_mfma_f32_16x16x32_bf16 v[116:119], v[186:189], v[202:205], v[116:119]
	v_mfma_f32_16x16x32_bf16 v[112:115], v[194:197], v[202:205], v[112:115]
	v_mfma_f32_16x16x32_bf16 v[100:103], v[186:189], v[210:213], v[100:103]
	v_mfma_f32_16x16x32_bf16 v[96:99], v[194:197], v[210:213], v[96:99]
	v_mfma_f32_16x16x32_bf16 v[84:87], v[186:189], v[218:221], v[84:87]
	v_mfma_f32_16x16x32_bf16 v[80:83], v[194:197], v[218:221], v[80:83]
	v_mfma_f32_16x16x32_bf16 v[68:71], v[186:189], v[226:229], v[68:71]
	v_mfma_f32_16x16x32_bf16 v[64:67], v[194:197], v[226:229], v[64:67]
	s_setprio 0
	s_barrier
	s_add_i32 s8, s68, s54
	s_mov_b32 m0, s8
	ds_read_b128 v[198:201], v161 offset:16384
	ds_read_b128 v[202:205], v161 offset:17408
	ds_read_b128 v[206:209], v161 offset:18432
	global_load_lds_dwordx4 v128, s[50:51]
	s_add_i32 m0, s8, 0x2000
	ds_read_b128 v[210:213], v161 offset:19456
	global_load_lds_dwordx4 v130, s[50:51]
	s_add_u32 s50, s50, 0x40000
	s_addc_u32 s51, s51, 0
	s_add_i32 s8, s69, s54
	s_mov_b32 m0, s8
	ds_read_b128 v[214:217], v161 offset:20480
	global_load_lds_dwordx4 v128, s[50:51]
	s_add_i32 m0, s8, 0x2000
	ds_read_b128 v[218:221], v161 offset:21504
	global_load_lds_dwordx4 v130, s[50:51]
	s_mov_b32 m0, s57
	ds_read_b128 v[222:225], v161 offset:22528
	global_load_lds_dwordx4 v134, s[52:53]
	s_mov_b32 m0, s58
	ds_read_b128 v[226:229], v161 offset:23552
	global_load_lds_dwordx4 v132, s[52:53]
	s_waitcnt vmcnt(8)
	s_waitcnt lgkmcnt(0)
	s_barrier
	s_setprio 1
	s_waitcnt lgkmcnt(0)
	v_mfma_f32_16x16x32_bf16 v[60:63], v[166:169], v[198:201], v[60:63]
	v_mfma_f32_16x16x32_bf16 v[56:59], v[174:177], v[198:201], v[56:59]
	v_mfma_f32_16x16x32_bf16 v[44:47], v[166:169], v[206:209], v[44:47]
	v_mfma_f32_16x16x32_bf16 v[40:43], v[174:177], v[206:209], v[40:43]
	v_mfma_f32_16x16x32_bf16 v[28:31], v[166:169], v[214:217], v[28:31]
	v_mfma_f32_16x16x32_bf16 v[24:27], v[174:177], v[214:217], v[24:27]
	v_mfma_f32_16x16x32_bf16 v[12:15], v[166:169], v[222:225], v[12:15]
	v_mfma_f32_16x16x32_bf16 v[8:11], v[174:177], v[222:225], v[8:11]
	v_mfma_f32_16x16x32_bf16 v[60:63], v[170:173], v[202:205], v[60:63]
	v_mfma_f32_16x16x32_bf16 v[56:59], v[178:181], v[202:205], v[56:59]
	v_mfma_f32_16x16x32_bf16 v[44:47], v[170:173], v[210:213], v[44:47]
	v_mfma_f32_16x16x32_bf16 v[40:43], v[178:181], v[210:213], v[40:43]
	v_mfma_f32_16x16x32_bf16 v[28:31], v[170:173], v[218:221], v[28:31]
	v_mfma_f32_16x16x32_bf16 v[24:27], v[178:181], v[218:221], v[24:27]
	v_mfma_f32_16x16x32_bf16 v[12:15], v[170:173], v[226:229], v[12:15]
	v_mfma_f32_16x16x32_bf16 v[8:11], v[178:181], v[226:229], v[8:11]
	s_setprio 0
	s_setprio 1
	v_mfma_f32_16x16x32_bf16 v[52:55], v[182:185], v[198:201], v[52:55]
	v_mfma_f32_16x16x32_bf16 v[48:51], v[190:193], v[198:201], v[48:51]
	v_mfma_f32_16x16x32_bf16 v[36:39], v[182:185], v[206:209], v[36:39]
	v_mfma_f32_16x16x32_bf16 v[32:35], v[190:193], v[206:209], v[32:35]
	v_mfma_f32_16x16x32_bf16 v[20:23], v[182:185], v[214:217], v[20:23]
	v_mfma_f32_16x16x32_bf16 v[16:19], v[190:193], v[214:217], v[16:19]
	v_mfma_f32_16x16x32_bf16 v[4:7], v[182:185], v[222:225], v[4:7]
	v_mfma_f32_16x16x32_bf16 v[0:3], v[190:193], v[222:225], v[0:3]
	v_mfma_f32_16x16x32_bf16 v[52:55], v[186:189], v[202:205], v[52:55]
	v_mfma_f32_16x16x32_bf16 v[48:51], v[194:197], v[202:205], v[48:51]
	v_mfma_f32_16x16x32_bf16 v[36:39], v[186:189], v[210:213], v[36:39]
	v_mfma_f32_16x16x32_bf16 v[32:35], v[194:197], v[210:213], v[32:35]
	v_mfma_f32_16x16x32_bf16 v[20:23], v[186:189], v[218:221], v[20:23]
	v_mfma_f32_16x16x32_bf16 v[16:19], v[194:197], v[218:221], v[16:19]
	v_mfma_f32_16x16x32_bf16 v[4:7], v[186:189], v[226:229], v[4:7]
	v_mfma_f32_16x16x32_bf16 v[0:3], v[194:197], v[226:229], v[0:3]
	s_setprio 0
	s_barrier
	s_add_i32 s8, 0, 0x18000
	s_add_i32 s82, 0, 0x1c000
	ds_read_b128 v[166:169], v154 offset:32768
	ds_read_b128 v[170:173], v154 offset:33792
	ds_read_b128 v[174:177], v154 offset:34816
	ds_read_b128 v[178:181], v154 offset:35840
	ds_read_b128 v[182:185], v154 offset:49152
	ds_read_b128 v[186:189], v154 offset:50176
	ds_read_b128 v[190:193], v154 offset:51200
	ds_read_b128 v[194:197], v154 offset:52224
	s_add_u32 s50, s52, 0x40000
	s_addc_u32 s51, s53, 0
	s_mov_b32 m0, s59
	ds_read_b128 v[198:201], v161 offset:32768
	ds_read_b128 v[202:205], v161 offset:33792
	ds_read_b128 v[206:209], v161 offset:34816
	ds_read_b128 v[210:213], v161 offset:35840
	ds_read_b128 v[214:217], v161 offset:36864
	ds_read_b128 v[218:221], v161 offset:37888
	ds_read_b128 v[222:225], v161 offset:38912
	global_load_lds_dwordx4 v134, s[50:51]
	s_mov_b32 m0, s60
	ds_read_b128 v[226:229], v161 offset:39936
	global_load_lds_dwordx4 v132, s[50:51]
	s_waitcnt vmcnt(8)
	s_waitcnt lgkmcnt(0)
	s_barrier
	s_setprio 1
	s_waitcnt lgkmcnt(0)
	v_mfma_f32_16x16x32_bf16 v[124:127], v[166:169], v[198:201], v[124:127]
	v_mfma_f32_16x16x32_bf16 v[120:123], v[174:177], v[198:201], v[120:123]
	v_mfma_f32_16x16x32_bf16 v[108:111], v[166:169], v[206:209], v[108:111]
	v_mfma_f32_16x16x32_bf16 v[104:107], v[174:177], v[206:209], v[104:107]
	v_mfma_f32_16x16x32_bf16 v[92:95], v[166:169], v[214:217], v[92:95]
	v_mfma_f32_16x16x32_bf16 v[88:91], v[174:177], v[214:217], v[88:91]
	v_mfma_f32_16x16x32_bf16 v[76:79], v[166:169], v[222:225], v[76:79]
	v_mfma_f32_16x16x32_bf16 v[72:75], v[174:177], v[222:225], v[72:75]
	v_mfma_f32_16x16x32_bf16 v[124:127], v[170:173], v[202:205], v[124:127]
	v_mfma_f32_16x16x32_bf16 v[120:123], v[178:181], v[202:205], v[120:123]
	v_mfma_f32_16x16x32_bf16 v[108:111], v[170:173], v[210:213], v[108:111]
	v_mfma_f32_16x16x32_bf16 v[104:107], v[178:181], v[210:213], v[104:107]
	v_mfma_f32_16x16x32_bf16 v[92:95], v[170:173], v[218:221], v[92:95]
	v_mfma_f32_16x16x32_bf16 v[88:91], v[178:181], v[218:221], v[88:91]
	v_mfma_f32_16x16x32_bf16 v[76:79], v[170:173], v[226:229], v[76:79]
	v_mfma_f32_16x16x32_bf16 v[72:75], v[178:181], v[226:229], v[72:75]
	s_setprio 0
	s_setprio 1
	v_mfma_f32_16x16x32_bf16 v[116:119], v[182:185], v[198:201], v[116:119]
	v_mfma_f32_16x16x32_bf16 v[112:115], v[190:193], v[198:201], v[112:115]
	v_mfma_f32_16x16x32_bf16 v[100:103], v[182:185], v[206:209], v[100:103]
	v_mfma_f32_16x16x32_bf16 v[96:99], v[190:193], v[206:209], v[96:99]
	v_mfma_f32_16x16x32_bf16 v[84:87], v[182:185], v[214:217], v[84:87]
	v_mfma_f32_16x16x32_bf16 v[80:83], v[190:193], v[214:217], v[80:83]
	v_mfma_f32_16x16x32_bf16 v[68:71], v[182:185], v[222:225], v[68:71]
	v_mfma_f32_16x16x32_bf16 v[64:67], v[190:193], v[222:225], v[64:67]
	v_mfma_f32_16x16x32_bf16 v[116:119], v[186:189], v[202:205], v[116:119]
	v_mfma_f32_16x16x32_bf16 v[112:115], v[194:197], v[202:205], v[112:115]
	v_mfma_f32_16x16x32_bf16 v[100:103], v[186:189], v[210:213], v[100:103]
	v_mfma_f32_16x16x32_bf16 v[96:99], v[194:197], v[210:213], v[96:99]
	v_mfma_f32_16x16x32_bf16 v[84:87], v[186:189], v[218:221], v[84:87]
	v_mfma_f32_16x16x32_bf16 v[80:83], v[194:197], v[218:221], v[80:83]
	v_mfma_f32_16x16x32_bf16 v[68:71], v[186:189], v[226:229], v[68:71]
	v_mfma_f32_16x16x32_bf16 v[64:67], v[194:197], v[226:229], v[64:67]
	s_setprio 0
	s_barrier
	s_add_i32 s8, s8, s54
	s_mov_b32 m0, s8
	ds_read_b128 v[198:201], v161 offset:49152
	ds_read_b128 v[202:205], v161 offset:50176
	ds_read_b128 v[206:209], v161 offset:51200
	global_load_lds_dwordx4 v128, s[48:49]
	s_add_i32 m0, s8, 0x2000
	ds_read_b128 v[210:213], v161 offset:52224
	global_load_lds_dwordx4 v130, s[48:49]
	s_add_u32 s48, s48, 0x40000
	s_addc_u32 s49, s49, 0
	s_add_i32 s8, s82, s54
	s_mov_b32 m0, s8
	ds_read_b128 v[214:217], v161 offset:53248
	global_load_lds_dwordx4 v128, s[48:49]
	s_add_i32 m0, s8, 0x2000
	ds_read_b128 v[218:221], v161 offset:54272
	global_load_lds_dwordx4 v130, s[48:49]
	s_mov_b32 m0, s65
	ds_read_b128 v[222:225], v161 offset:55296
	global_load_lds_dwordx4 v134, s[46:47]
	s_mov_b32 m0, s66
	ds_read_b128 v[226:229], v161 offset:56320
	global_load_lds_dwordx4 v132, s[46:47]
	s_waitcnt vmcnt(8)
	s_waitcnt lgkmcnt(0)
	s_barrier
	s_setprio 1
	s_waitcnt lgkmcnt(0)
	v_mfma_f32_16x16x32_bf16 v[60:63], v[166:169], v[198:201], v[60:63]
	v_mfma_f32_16x16x32_bf16 v[56:59], v[174:177], v[198:201], v[56:59]
	v_mfma_f32_16x16x32_bf16 v[44:47], v[166:169], v[206:209], v[44:47]
	v_mfma_f32_16x16x32_bf16 v[40:43], v[174:177], v[206:209], v[40:43]
	v_mfma_f32_16x16x32_bf16 v[28:31], v[166:169], v[214:217], v[28:31]
	v_mfma_f32_16x16x32_bf16 v[24:27], v[174:177], v[214:217], v[24:27]
	v_mfma_f32_16x16x32_bf16 v[12:15], v[166:169], v[222:225], v[12:15]
	v_mfma_f32_16x16x32_bf16 v[8:11], v[174:177], v[222:225], v[8:11]
	v_mfma_f32_16x16x32_bf16 v[60:63], v[170:173], v[202:205], v[60:63]
	v_mfma_f32_16x16x32_bf16 v[56:59], v[178:181], v[202:205], v[56:59]
	v_mfma_f32_16x16x32_bf16 v[44:47], v[170:173], v[210:213], v[44:47]
	v_mfma_f32_16x16x32_bf16 v[40:43], v[178:181], v[210:213], v[40:43]
	v_mfma_f32_16x16x32_bf16 v[28:31], v[170:173], v[218:221], v[28:31]
	v_mfma_f32_16x16x32_bf16 v[24:27], v[178:181], v[218:221], v[24:27]
	v_mfma_f32_16x16x32_bf16 v[12:15], v[170:173], v[226:229], v[12:15]
	v_mfma_f32_16x16x32_bf16 v[8:11], v[178:181], v[226:229], v[8:11]
	s_setprio 0
	s_setprio 1
	v_mfma_f32_16x16x32_bf16 v[52:55], v[182:185], v[198:201], v[52:55]
	v_mfma_f32_16x16x32_bf16 v[48:51], v[190:193], v[198:201], v[48:51]
	v_mfma_f32_16x16x32_bf16 v[36:39], v[182:185], v[206:209], v[36:39]
	v_mfma_f32_16x16x32_bf16 v[32:35], v[190:193], v[206:209], v[32:35]
	v_mfma_f32_16x16x32_bf16 v[20:23], v[182:185], v[214:217], v[20:23]
	v_mfma_f32_16x16x32_bf16 v[16:19], v[190:193], v[214:217], v[16:19]
	v_mfma_f32_16x16x32_bf16 v[4:7], v[182:185], v[222:225], v[4:7]
	v_mfma_f32_16x16x32_bf16 v[0:3], v[190:193], v[222:225], v[0:3]
	v_mfma_f32_16x16x32_bf16 v[52:55], v[186:189], v[202:205], v[52:55]
	v_mfma_f32_16x16x32_bf16 v[48:51], v[194:197], v[202:205], v[48:51]
	v_mfma_f32_16x16x32_bf16 v[36:39], v[186:189], v[210:213], v[36:39]
	v_mfma_f32_16x16x32_bf16 v[32:35], v[194:197], v[210:213], v[32:35]
	v_mfma_f32_16x16x32_bf16 v[20:23], v[186:189], v[218:221], v[20:23]
	v_mfma_f32_16x16x32_bf16 v[16:19], v[194:197], v[218:221], v[16:19]
	v_mfma_f32_16x16x32_bf16 v[4:7], v[186:189], v[226:229], v[4:7]
	v_mfma_f32_16x16x32_bf16 v[0:3], v[194:197], v[226:229], v[0:3]
	s_setprio 0
	s_barrier
	s_add_i32 s8, s81, 2
	s_add_u32 s44, s44, 0x100
	s_addc_u32 s45, s45, 0
	s_cmp_gt_u32 s81, 13
	s_mov_b32 s81, s8
	s_cbranch_scc1 .LBB0_813
.LBB0_807:
	s_add_u32 s52, s30, s44
	s_addc_u32 s53, s31, s45
	s_mov_b64 s[100:101], s[52:53]
	s_add_u32 s83, s28, s44
	s_addc_u32 s82, s29, s45
	s_add_u32 s46, s52, 0x180
	s_addc_u32 s47, s53, 0
	s_add_u32 s48, s83, 0x180
	s_addc_u32 s49, s82, 0
	s_add_u32 s52, s52, 0x100
	s_addc_u32 s53, s53, 0
	s_add_u32 s50, s83, 0x100
	s_addc_u32 s51, s82, 0
	s_cmpk_eq_i32 s44, 0x700
	s_cselect_b32 s46, s36, s46
	s_cselect_b32 s47, s37, s47
	s_cselect_b32 s48, s38, s48
	s_cselect_b32 s49, s39, s49
	s_cselect_b32 s52, s79, s52
	s_cselect_b32 s53, s21, s53
	s_cselect_b32 s50, s80, s50
	s_cselect_b32 s51, s19, s51
	s_branch .LBB0_806

.LBB0_895:
	s_add_u32 s70, s55, s28
	s_addc_u32 s71, s56, s29
	s_add_u32 s72, s57, s30
	s_addc_u32 s73, s58, s31
	s_add_u32 s28, s4, 0x80
	s_addc_u32 s29, s5, 0
	s_add_u32 s30, s20, 0x80
	s_addc_u32 s31, s21, 0
	v_lshl_add_u64 v[128:129], s[26:27], 0, v[148:149]
	v_lshl_add_u64 v[130:131], s[26:27], 0, v[150:151]
	s_mov_b32 s78, 0
	s_mov_b64 s[36:37], 0
	v_add_u32_e32 v220, 0x10000, v165
	s_add_u32 s46, s26, s36
	s_addc_u32 s47, s27, s37
	s_mov_b64 s[100:101], s[46:47]
	s_add_u32 s80, s24, s36
	s_addc_u32 s79, s25, s37
	s_add_u32 s38, s46, 0x180
	s_addc_u32 s39, s47, 0
	s_add_u32 s40, s80, 0x180
	s_addc_u32 s41, s79, 0
	s_add_u32 s46, s46, 0x100
	s_addc_u32 s47, s47, 0
	s_add_u32 s44, s80, 0x100
	s_addc_u32 s45, s79, 0
	s_cmpk_eq_i32 s36, 0x1500
	s_cselect_b32 s38, s28, s38
	s_cselect_b32 s39, s29, s39
	s_cselect_b32 s40, s30, s40
	s_cselect_b32 s41, s31, s41
	s_cselect_b32 s46, s4, s46
	s_cselect_b32 s47, s5, s47
	s_cselect_b32 s44, s20, s44
	s_cselect_b32 s45, s21, s45
	ds_read_b128 v[132:135], v220
	ds_read_b128 v[156:159], v220 offset:1024
	ds_read_b128 v[160:163], v220 offset:2048
	ds_read_b128 v[168:171], v220 offset:3072
	ds_read_b128 v[172:175], v220 offset:16384
	ds_read_b128 v[176:179], v220 offset:17408
	ds_read_b128 v[180:183], v220 offset:18432
	ds_read_b128 v[184:187], v220 offset:19456
	s_add_i32 m0, s51, 0xc000
	ds_read_b128 v[188:191], v166
	ds_read_b128 v[192:195], v166 offset:1024
	ds_read_b128 v[196:199], v166 offset:2048
	ds_read_b128 v[200:203], v166 offset:3072
	ds_read_b128 v[204:207], v166 offset:4096
	ds_read_b128 v[208:211], v166 offset:5120
	ds_read_b128 v[212:215], v166 offset:6144
	global_load_lds_dwordx4 v148, s[100:101]
	s_add_i32 m0, s51, 0xe000
	ds_read_b128 v[216:219], v166 offset:7168
	global_load_lds_dwordx4 v150, s[100:101]
	s_waitcnt vmcnt(8)
	s_waitcnt lgkmcnt(0)
	s_barrier
	s_setprio 1
	s_waitcnt lgkmcnt(0)
	v_mfma_f32_16x16x32_bf16 v[124:127], v[132:135], v[188:191], 0
	v_mfma_f32_16x16x32_bf16 v[120:123], v[160:163], v[188:191], 0
	v_mfma_f32_16x16x32_bf16 v[108:111], v[132:135], v[196:199], 0
	v_mfma_f32_16x16x32_bf16 v[104:107], v[160:163], v[196:199], 0
	v_mfma_f32_16x16x32_bf16 v[92:95], v[132:135], v[204:207], 0
	v_mfma_f32_16x16x32_bf16 v[88:91], v[160:163], v[204:207], 0
	v_mfma_f32_16x16x32_bf16 v[76:79], v[132:135], v[212:215], 0
	v_mfma_f32_16x16x32_bf16 v[72:75], v[160:163], v[212:215], 0
	v_mfma_f32_16x16x32_bf16 v[124:127], v[156:159], v[192:195], v[124:127]
	v_mfma_f32_16x16x32_bf16 v[120:123], v[168:171], v[192:195], v[120:123]
	v_mfma_f32_16x16x32_bf16 v[108:111], v[156:159], v[200:203], v[108:111]
	v_mfma_f32_16x16x32_bf16 v[104:107], v[168:171], v[200:203], v[104:107]
	v_mfma_f32_16x16x32_bf16 v[92:95], v[156:159], v[208:211], v[92:95]
	v_mfma_f32_16x16x32_bf16 v[88:91], v[168:171], v[208:211], v[88:91]
	v_mfma_f32_16x16x32_bf16 v[76:79], v[156:159], v[216:219], v[76:79]
	v_mfma_f32_16x16x32_bf16 v[72:75], v[168:171], v[216:219], v[72:75]
	s_setprio 0
	s_setprio 1
	v_mfma_f32_16x16x32_bf16 v[116:119], v[172:175], v[188:191], 0
	v_mfma_f32_16x16x32_bf16 v[112:115], v[180:183], v[188:191], 0
	v_mfma_f32_16x16x32_bf16 v[100:103], v[172:175], v[196:199], 0
	v_mfma_f32_16x16x32_bf16 v[96:99], v[180:183], v[196:199], 0
	v_mfma_f32_16x16x32_bf16 v[84:87], v[172:175], v[204:207], 0
	v_mfma_f32_16x16x32_bf16 v[80:83], v[180:183], v[204:207], 0
	v_mfma_f32_16x16x32_bf16 v[68:71], v[172:175], v[212:215], 0
	v_mfma_f32_16x16x32_bf16 v[64:67], v[180:183], v[212:215], 0
	v_mfma_f32_16x16x32_bf16 v[116:119], v[176:179], v[192:195], v[116:119]
	v_mfma_f32_16x16x32_bf16 v[112:115], v[184:187], v[192:195], v[112:115]
	v_mfma_f32_16x16x32_bf16 v[100:103], v[176:179], v[200:203], v[100:103]
	v_mfma_f32_16x16x32_bf16 v[96:99], v[184:187], v[200:203], v[96:99]
	v_mfma_f32_16x16x32_bf16 v[84:87], v[176:179], v[208:211], v[84:87]
	v_mfma_f32_16x16x32_bf16 v[80:83], v[184:187], v[208:211], v[80:83]
	v_mfma_f32_16x16x32_bf16 v[68:71], v[176:179], v[216:219], v[68:71]
	v_mfma_f32_16x16x32_bf16 v[64:67], v[184:187], v[216:219], v[64:67]
	s_setprio 0
	s_barrier
	s_add_i32 s8, s64, s50
	s_mov_b32 m0, s8
	ds_read_b128 v[188:191], v166 offset:16384
	ds_read_b128 v[192:195], v166 offset:17408
	ds_read_b128 v[196:199], v166 offset:18432
	global_load_lds_dwordx4 v138, s[44:45]
	s_add_i32 m0, s8, 0x2000
	ds_read_b128 v[200:203], v166 offset:19456
	global_load_lds_dwordx4 v142, s[44:45]
	s_add_u32 s44, s44, 0xb0000
	s_addc_u32 s45, s45, 0
	s_add_i32 s8, s65, s50
	s_mov_b32 m0, s8
	ds_read_b128 v[204:207], v166 offset:20480
	global_load_lds_dwordx4 v138, s[44:45]
	s_add_i32 m0, s8, 0x2000
	ds_read_b128 v[208:211], v166 offset:21504
	global_load_lds_dwordx4 v142, s[44:45]
	s_mov_b32 m0, s51
	ds_read_b128 v[212:215], v166 offset:22528
	global_load_lds_dwordx4 v136, s[46:47]
	s_mov_b32 m0, s52
	ds_read_b128 v[216:219], v166 offset:23552
	global_load_lds_dwordx4 v140, s[46:47]
	s_waitcnt vmcnt(8)
	s_waitcnt lgkmcnt(0)
	s_barrier
	s_setprio 1
	s_waitcnt lgkmcnt(0)
	v_mfma_f32_16x16x32_bf16 v[60:63], v[132:135], v[188:191], 0
	v_mfma_f32_16x16x32_bf16 v[56:59], v[160:163], v[188:191], 0
	v_mfma_f32_16x16x32_bf16 v[44:47], v[132:135], v[196:199], 0
	v_mfma_f32_16x16x32_bf16 v[40:43], v[160:163], v[196:199], 0
	v_mfma_f32_16x16x32_bf16 v[28:31], v[132:135], v[204:207], 0
	v_mfma_f32_16x16x32_bf16 v[24:27], v[160:163], v[204:207], 0
	v_mfma_f32_16x16x32_bf16 v[12:15], v[132:135], v[212:215], 0
	v_mfma_f32_16x16x32_bf16 v[8:11], v[160:163], v[212:215], 0
	v_mfma_f32_16x16x32_bf16 v[60:63], v[156:159], v[192:195], v[60:63]
	v_mfma_f32_16x16x32_bf16 v[56:59], v[168:171], v[192:195], v[56:59]
	v_mfma_f32_16x16x32_bf16 v[44:47], v[156:159], v[200:203], v[44:47]
	v_mfma_f32_16x16x32_bf16 v[40:43], v[168:171], v[200:203], v[40:43]
	v_mfma_f32_16x16x32_bf16 v[28:31], v[156:159], v[208:211], v[28:31]
	v_mfma_f32_16x16x32_bf16 v[24:27], v[168:171], v[208:211], v[24:27]
	v_mfma_f32_16x16x32_bf16 v[12:15], v[156:159], v[216:219], v[12:15]
	v_mfma_f32_16x16x32_bf16 v[8:11], v[168:171], v[216:219], v[8:11]
	s_setprio 0
	s_setprio 1
	v_mfma_f32_16x16x32_bf16 v[52:55], v[172:175], v[188:191], 0
	v_mfma_f32_16x16x32_bf16 v[48:51], v[180:183], v[188:191], 0
	v_mfma_f32_16x16x32_bf16 v[36:39], v[172:175], v[196:199], 0
	v_mfma_f32_16x16x32_bf16 v[32:35], v[180:183], v[196:199], 0
	v_mfma_f32_16x16x32_bf16 v[20:23], v[172:175], v[204:207], 0
	v_mfma_f32_16x16x32_bf16 v[16:19], v[180:183], v[204:207], 0
	v_mfma_f32_16x16x32_bf16 v[4:7], v[172:175], v[212:215], 0
	v_mfma_f32_16x16x32_bf16 v[0:3], v[180:183], v[212:215], 0
	v_mfma_f32_16x16x32_bf16 v[52:55], v[176:179], v[192:195], v[52:55]
	v_mfma_f32_16x16x32_bf16 v[48:51], v[184:187], v[192:195], v[48:51]
	v_mfma_f32_16x16x32_bf16 v[36:39], v[176:179], v[200:203], v[36:39]
	v_mfma_f32_16x16x32_bf16 v[32:35], v[184:187], v[200:203], v[32:35]
	v_mfma_f32_16x16x32_bf16 v[20:23], v[176:179], v[208:211], v[20:23]
	v_mfma_f32_16x16x32_bf16 v[16:19], v[184:187], v[208:211], v[16:19]
	v_mfma_f32_16x16x32_bf16 v[4:7], v[176:179], v[216:219], v[4:7]
	v_mfma_f32_16x16x32_bf16 v[0:3], v[184:187], v[216:219], v[0:3]
	s_setprio 0
	s_barrier
	s_add_i32 s8, 0, 0x18000
	s_add_i32 s79, 0, 0x1c000
	ds_read_b128 v[132:135], v220 offset:32768
	ds_read_b128 v[156:159], v220 offset:33792
	ds_read_b128 v[160:163], v220 offset:34816
	ds_read_b128 v[168:171], v220 offset:35840
	ds_read_b128 v[172:175], v220 offset:49152
	ds_read_b128 v[176:179], v220 offset:50176
	ds_read_b128 v[180:183], v220 offset:51200
	ds_read_b128 v[184:187], v220 offset:52224
	s_add_u32 s44, s46, 0xb0000
	s_addc_u32 s45, s47, 0
	s_mov_b32 m0, s53
	ds_read_b128 v[188:191], v166 offset:32768
	ds_read_b128 v[192:195], v166 offset:33792
	ds_read_b128 v[196:199], v166 offset:34816
	ds_read_b128 v[200:203], v166 offset:35840
	ds_read_b128 v[204:207], v166 offset:36864
	ds_read_b128 v[208:211], v166 offset:37888
	ds_read_b128 v[212:215], v166 offset:38912
	global_load_lds_dwordx4 v136, s[44:45]
	s_mov_b32 m0, s54
	ds_read_b128 v[216:219], v166 offset:39936
	global_load_lds_dwordx4 v140, s[44:45]
	s_waitcnt vmcnt(8)
	s_waitcnt lgkmcnt(0)
	s_barrier
	s_setprio 1
	s_waitcnt lgkmcnt(0)
	v_mfma_f32_16x16x32_bf16 v[124:127], v[132:135], v[188:191], v[124:127]
	v_mfma_f32_16x16x32_bf16 v[120:123], v[160:163], v[188:191], v[120:123]
	v_mfma_f32_16x16x32_bf16 v[108:111], v[132:135], v[196:199], v[108:111]
	v_mfma_f32_16x16x32_bf16 v[104:107], v[160:163], v[196:199], v[104:107]
	v_mfma_f32_16x16x32_bf16 v[92:95], v[132:135], v[204:207], v[92:95]
	v_mfma_f32_16x16x32_bf16 v[88:91], v[160:163], v[204:207], v[88:91]
	v_mfma_f32_16x16x32_bf16 v[76:79], v[132:135], v[212:215], v[76:79]
	v_mfma_f32_16x16x32_bf16 v[72:75], v[160:163], v[212:215], v[72:75]
	v_mfma_f32_16x16x32_bf16 v[124:127], v[156:159], v[192:195], v[124:127]
	v_mfma_f32_16x16x32_bf16 v[120:123], v[168:171], v[192:195], v[120:123]
	v_mfma_f32_16x16x32_bf16 v[108:111], v[156:159], v[200:203], v[108:111]
	v_mfma_f32_16x16x32_bf16 v[104:107], v[168:171], v[200:203], v[104:107]
	v_mfma_f32_16x16x32_bf16 v[92:95], v[156:159], v[208:211], v[92:95]
	v_mfma_f32_16x16x32_bf16 v[88:91], v[168:171], v[208:211], v[88:91]
	v_mfma_f32_16x16x32_bf16 v[76:79], v[156:159], v[216:219], v[76:79]
	v_mfma_f32_16x16x32_bf16 v[72:75], v[168:171], v[216:219], v[72:75]
	s_setprio 0
	s_setprio 1
	v_mfma_f32_16x16x32_bf16 v[116:119], v[172:175], v[188:191], v[116:119]
	v_mfma_f32_16x16x32_bf16 v[112:115], v[180:183], v[188:191], v[112:115]
	v_mfma_f32_16x16x32_bf16 v[100:103], v[172:175], v[196:199], v[100:103]
	v_mfma_f32_16x16x32_bf16 v[96:99], v[180:183], v[196:199], v[96:99]
	v_mfma_f32_16x16x32_bf16 v[84:87], v[172:175], v[204:207], v[84:87]
	v_mfma_f32_16x16x32_bf16 v[80:83], v[180:183], v[204:207], v[80:83]
	v_mfma_f32_16x16x32_bf16 v[68:71], v[172:175], v[212:215], v[68:71]
	v_mfma_f32_16x16x32_bf16 v[64:67], v[180:183], v[212:215], v[64:67]
	v_mfma_f32_16x16x32_bf16 v[116:119], v[176:179], v[192:195], v[116:119]
	v_mfma_f32_16x16x32_bf16 v[112:115], v[184:187], v[192:195], v[112:115]
	v_mfma_f32_16x16x32_bf16 v[100:103], v[176:179], v[200:203], v[100:103]
	v_mfma_f32_16x16x32_bf16 v[96:99], v[184:187], v[200:203], v[96:99]
	v_mfma_f32_16x16x32_bf16 v[84:87], v[176:179], v[208:211], v[84:87]
	v_mfma_f32_16x16x32_bf16 v[80:83], v[184:187], v[208:211], v[80:83]
	v_mfma_f32_16x16x32_bf16 v[68:71], v[176:179], v[216:219], v[68:71]
	v_mfma_f32_16x16x32_bf16 v[64:67], v[184:187], v[216:219], v[64:67]
	s_setprio 0
	s_barrier
	s_add_i32 s8, s8, s50
	s_mov_b32 m0, s8
	ds_read_b128 v[188:191], v166 offset:49152
	ds_read_b128 v[192:195], v166 offset:50176
	ds_read_b128 v[196:199], v166 offset:51200
	global_load_lds_dwordx4 v138, s[40:41]
	s_add_i32 m0, s8, 0x2000
	ds_read_b128 v[200:203], v166 offset:52224
	global_load_lds_dwordx4 v142, s[40:41]
	s_add_u32 s40, s40, 0xb0000
	s_addc_u32 s41, s41, 0
	s_add_i32 s8, s79, s50
	s_mov_b32 m0, s8
	ds_read_b128 v[204:207], v166 offset:53248
	global_load_lds_dwordx4 v138, s[40:41]
	s_add_i32 m0, s8, 0x2000
	ds_read_b128 v[208:211], v166 offset:54272
	global_load_lds_dwordx4 v142, s[40:41]
	s_mov_b32 m0, s60
	ds_read_b128 v[212:215], v166 offset:55296
	global_load_lds_dwordx4 v136, s[38:39]
	s_mov_b32 m0, s61
	ds_read_b128 v[216:219], v166 offset:56320
	global_load_lds_dwordx4 v140, s[38:39]
	s_waitcnt vmcnt(8)
	s_waitcnt lgkmcnt(0)
	s_barrier
	s_setprio 1
	s_waitcnt lgkmcnt(0)
	v_mfma_f32_16x16x32_bf16 v[60:63], v[132:135], v[188:191], v[60:63]
	v_mfma_f32_16x16x32_bf16 v[56:59], v[160:163], v[188:191], v[56:59]
	v_mfma_f32_16x16x32_bf16 v[44:47], v[132:135], v[196:199], v[44:47]
	v_mfma_f32_16x16x32_bf16 v[40:43], v[160:163], v[196:199], v[40:43]
	v_mfma_f32_16x16x32_bf16 v[28:31], v[132:135], v[204:207], v[28:31]
	v_mfma_f32_16x16x32_bf16 v[24:27], v[160:163], v[204:207], v[24:27]
	v_mfma_f32_16x16x32_bf16 v[12:15], v[132:135], v[212:215], v[12:15]
	v_mfma_f32_16x16x32_bf16 v[8:11], v[160:163], v[212:215], v[8:11]
	v_mfma_f32_16x16x32_bf16 v[60:63], v[156:159], v[192:195], v[60:63]
	v_mfma_f32_16x16x32_bf16 v[56:59], v[168:171], v[192:195], v[56:59]
	v_mfma_f32_16x16x32_bf16 v[44:47], v[156:159], v[200:203], v[44:47]
	v_mfma_f32_16x16x32_bf16 v[40:43], v[168:171], v[200:203], v[40:43]
	v_mfma_f32_16x16x32_bf16 v[28:31], v[156:159], v[208:211], v[28:31]
	v_mfma_f32_16x16x32_bf16 v[24:27], v[168:171], v[208:211], v[24:27]
	v_mfma_f32_16x16x32_bf16 v[12:15], v[156:159], v[216:219], v[12:15]
	v_mfma_f32_16x16x32_bf16 v[8:11], v[168:171], v[216:219], v[8:11]
	s_setprio 0
	s_setprio 1
	v_mfma_f32_16x16x32_bf16 v[52:55], v[172:175], v[188:191], v[52:55]
	v_mfma_f32_16x16x32_bf16 v[48:51], v[180:183], v[188:191], v[48:51]
	v_mfma_f32_16x16x32_bf16 v[36:39], v[172:175], v[196:199], v[36:39]
	v_mfma_f32_16x16x32_bf16 v[32:35], v[180:183], v[196:199], v[32:35]
	v_mfma_f32_16x16x32_bf16 v[20:23], v[172:175], v[204:207], v[20:23]
	v_mfma_f32_16x16x32_bf16 v[16:19], v[180:183], v[204:207], v[16:19]
	v_mfma_f32_16x16x32_bf16 v[4:7], v[172:175], v[212:215], v[4:7]
	v_mfma_f32_16x16x32_bf16 v[0:3], v[180:183], v[212:215], v[0:3]
	v_mfma_f32_16x16x32_bf16 v[52:55], v[176:179], v[192:195], v[52:55]
	v_mfma_f32_16x16x32_bf16 v[48:51], v[184:187], v[192:195], v[48:51]
	v_mfma_f32_16x16x32_bf16 v[36:39], v[176:179], v[200:203], v[36:39]
	v_mfma_f32_16x16x32_bf16 v[32:35], v[184:187], v[200:203], v[32:35]
	v_mfma_f32_16x16x32_bf16 v[20:23], v[176:179], v[208:211], v[20:23]
	v_mfma_f32_16x16x32_bf16 v[16:19], v[184:187], v[208:211], v[16:19]
	v_mfma_f32_16x16x32_bf16 v[4:7], v[176:179], v[216:219], v[4:7]
	v_mfma_f32_16x16x32_bf16 v[0:3], v[184:187], v[216:219], v[0:3]
	s_setprio 0
	s_barrier
	s_add_i32 s8, s78, 2
	s_add_u32 s36, s36, 0x100
	s_addc_u32 s37, s37, 0
	s_cmp_gt_u32 s78, 41
	s_mov_b32 s78, s8
	s_cbranch_scc1 .LBB0_903
	s_branch .LBB0_897
.LBB0_896:
	ds_read_b128 v[132:135], v220
	ds_read_b128 v[156:159], v220 offset:1024
	ds_read_b128 v[160:163], v220 offset:2048
	ds_read_b128 v[168:171], v220 offset:3072
	ds_read_b128 v[172:175], v220 offset:16384
	ds_read_b128 v[176:179], v220 offset:17408
	ds_read_b128 v[180:183], v220 offset:18432
	ds_read_b128 v[184:187], v220 offset:19456
	s_add_i32 m0, s51, 0xc000
	ds_read_b128 v[188:191], v166
	ds_read_b128 v[192:195], v166 offset:1024
	ds_read_b128 v[196:199], v166 offset:2048
	ds_read_b128 v[200:203], v166 offset:3072
	ds_read_b128 v[204:207], v166 offset:4096
	ds_read_b128 v[208:211], v166 offset:5120
	ds_read_b128 v[212:215], v166 offset:6144
	global_load_lds_dwordx4 v148, s[100:101]
	s_add_i32 m0, s51, 0xe000
	ds_read_b128 v[216:219], v166 offset:7168
	global_load_lds_dwordx4 v150, s[100:101]
	s_waitcnt vmcnt(8)
	s_waitcnt lgkmcnt(0)
	s_barrier
	s_setprio 1
	s_waitcnt lgkmcnt(0)
	v_mfma_f32_16x16x32_bf16 v[124:127], v[132:135], v[188:191], v[124:127]
	v_mfma_f32_16x16x32_bf16 v[120:123], v[160:163], v[188:191], v[120:123]
	v_mfma_f32_16x16x32_bf16 v[108:111], v[132:135], v[196:199], v[108:111]
	v_mfma_f32_16x16x32_bf16 v[104:107], v[160:163], v[196:199], v[104:107]
	v_mfma_f32_16x16x32_bf16 v[92:95], v[132:135], v[204:207], v[92:95]
	v_mfma_f32_16x16x32_bf16 v[88:91], v[160:163], v[204:207], v[88:91]
	v_mfma_f32_16x16x32_bf16 v[76:79], v[132:135], v[212:215], v[76:79]
	v_mfma_f32_16x16x32_bf16 v[72:75], v[160:163], v[212:215], v[72:75]
	v_mfma_f32_16x16x32_bf16 v[124:127], v[156:159], v[192:195], v[124:127]
	v_mfma_f32_16x16x32_bf16 v[120:123], v[168:171], v[192:195], v[120:123]
	v_mfma_f32_16x16x32_bf16 v[108:111], v[156:159], v[200:203], v[108:111]
	v_mfma_f32_16x16x32_bf16 v[104:107], v[168:171], v[200:203], v[104:107]
	v_mfma_f32_16x16x32_bf16 v[92:95], v[156:159], v[208:211], v[92:95]
	v_mfma_f32_16x16x32_bf16 v[88:91], v[168:171], v[208:211], v[88:91]
	v_mfma_f32_16x16x32_bf16 v[76:79], v[156:159], v[216:219], v[76:79]
	v_mfma_f32_16x16x32_bf16 v[72:75], v[168:171], v[216:219], v[72:75]
	s_setprio 0
	s_setprio 1
	v_mfma_f32_16x16x32_bf16 v[116:119], v[172:175], v[188:191], v[116:119]
	v_mfma_f32_16x16x32_bf16 v[112:115], v[180:183], v[188:191], v[112:115]
	v_mfma_f32_16x16x32_bf16 v[100:103], v[172:175], v[196:199], v[100:103]
	v_mfma_f32_16x16x32_bf16 v[96:99], v[180:183], v[196:199], v[96:99]
	v_mfma_f32_16x16x32_bf16 v[84:87], v[172:175], v[204:207], v[84:87]
	v_mfma_f32_16x16x32_bf16 v[80:83], v[180:183], v[204:207], v[80:83]
	v_mfma_f32_16x16x32_bf16 v[68:71], v[172:175], v[212:215], v[68:71]
	v_mfma_f32_16x16x32_bf16 v[64:67], v[180:183], v[212:215], v[64:67]
	v_mfma_f32_16x16x32_bf16 v[116:119], v[176:179], v[192:195], v[116:119]
	v_mfma_f32_16x16x32_bf16 v[112:115], v[184:187], v[192:195], v[112:115]
	v_mfma_f32_16x16x32_bf16 v[100:103], v[176:179], v[200:203], v[100:103]
	v_mfma_f32_16x16x32_bf16 v[96:99], v[184:187], v[200:203], v[96:99]
	v_mfma_f32_16x16x32_bf16 v[84:87], v[176:179], v[208:211], v[84:87]
	v_mfma_f32_16x16x32_bf16 v[80:83], v[184:187], v[208:211], v[80:83]
	v_mfma_f32_16x16x32_bf16 v[68:71], v[176:179], v[216:219], v[68:71]
	v_mfma_f32_16x16x32_bf16 v[64:67], v[184:187], v[216:219], v[64:67]
	s_setprio 0
	s_barrier
	s_add_i32 s8, s64, s50
	s_mov_b32 m0, s8
	ds_read_b128 v[188:191], v166 offset:16384
	ds_read_b128 v[192:195], v166 offset:17408
	ds_read_b128 v[196:199], v166 offset:18432
	global_load_lds_dwordx4 v138, s[44:45]
	s_add_i32 m0, s8, 0x2000
	ds_read_b128 v[200:203], v166 offset:19456
	global_load_lds_dwordx4 v142, s[44:45]
	s_add_u32 s44, s44, 0xb0000
	s_addc_u32 s45, s45, 0
	s_add_i32 s8, s65, s50
	s_mov_b32 m0, s8
	ds_read_b128 v[204:207], v166 offset:20480
	global_load_lds_dwordx4 v138, s[44:45]
	s_add_i32 m0, s8, 0x2000
	ds_read_b128 v[208:211], v166 offset:21504
	global_load_lds_dwordx4 v142, s[44:45]
	s_mov_b32 m0, s51
	ds_read_b128 v[212:215], v166 offset:22528
	global_load_lds_dwordx4 v136, s[46:47]
	s_mov_b32 m0, s52
	ds_read_b128 v[216:219], v166 offset:23552
	global_load_lds_dwordx4 v140, s[46:47]
	s_waitcnt vmcnt(8)
	s_waitcnt lgkmcnt(0)
	s_barrier
	s_setprio 1
	s_waitcnt lgkmcnt(0)
	v_mfma_f32_16x16x32_bf16 v[60:63], v[132:135], v[188:191], v[60:63]
	v_mfma_f32_16x16x32_bf16 v[56:59], v[160:163], v[188:191], v[56:59]
	v_mfma_f32_16x16x32_bf16 v[44:47], v[132:135], v[196:199], v[44:47]
	v_mfma_f32_16x16x32_bf16 v[40:43], v[160:163], v[196:199], v[40:43]
	v_mfma_f32_16x16x32_bf16 v[28:31], v[132:135], v[204:207], v[28:31]
	v_mfma_f32_16x16x32_bf16 v[24:27], v[160:163], v[204:207], v[24:27]
	v_mfma_f32_16x16x32_bf16 v[12:15], v[132:135], v[212:215], v[12:15]
	v_mfma_f32_16x16x32_bf16 v[8:11], v[160:163], v[212:215], v[8:11]
	v_mfma_f32_16x16x32_bf16 v[60:63], v[156:159], v[192:195], v[60:63]
	v_mfma_f32_16x16x32_bf16 v[56:59], v[168:171], v[192:195], v[56:59]
	v_mfma_f32_16x16x32_bf16 v[44:47], v[156:159], v[200:203], v[44:47]
	v_mfma_f32_16x16x32_bf16 v[40:43], v[168:171], v[200:203], v[40:43]
	v_mfma_f32_16x16x32_bf16 v[28:31], v[156:159], v[208:211], v[28:31]
	v_mfma_f32_16x16x32_bf16 v[24:27], v[168:171], v[208:211], v[24:27]
	v_mfma_f32_16x16x32_bf16 v[12:15], v[156:159], v[216:219], v[12:15]
	v_mfma_f32_16x16x32_bf16 v[8:11], v[168:171], v[216:219], v[8:11]
	s_setprio 0
	s_setprio 1
	v_mfma_f32_16x16x32_bf16 v[52:55], v[172:175], v[188:191], v[52:55]
	v_mfma_f32_16x16x32_bf16 v[48:51], v[180:183], v[188:191], v[48:51]
	v_mfma_f32_16x16x32_bf16 v[36:39], v[172:175], v[196:199], v[36:39]
	v_mfma_f32_16x16x32_bf16 v[32:35], v[180:183], v[196:199], v[32:35]
	v_mfma_f32_16x16x32_bf16 v[20:23], v[172:175], v[204:207], v[20:23]
	v_mfma_f32_16x16x32_bf16 v[16:19], v[180:183], v[204:207], v[16:19]
	v_mfma_f32_16x16x32_bf16 v[4:7], v[172:175], v[212:215], v[4:7]
	v_mfma_f32_16x16x32_bf16 v[0:3], v[180:183], v[212:215], v[0:3]
	v_mfma_f32_16x16x32_bf16 v[52:55], v[176:179], v[192:195], v[52:55]
	v_mfma_f32_16x16x32_bf16 v[48:51], v[184:187], v[192:195], v[48:51]
	v_mfma_f32_16x16x32_bf16 v[36:39], v[176:179], v[200:203], v[36:39]
	v_mfma_f32_16x16x32_bf16 v[32:35], v[184:187], v[200:203], v[32:35]
	v_mfma_f32_16x16x32_bf16 v[20:23], v[176:179], v[208:211], v[20:23]
	v_mfma_f32_16x16x32_bf16 v[16:19], v[184:187], v[208:211], v[16:19]
	v_mfma_f32_16x16x32_bf16 v[4:7], v[176:179], v[216:219], v[4:7]
	v_mfma_f32_16x16x32_bf16 v[0:3], v[184:187], v[216:219], v[0:3]
	s_setprio 0
	s_barrier
	s_add_i32 s8, 0, 0x18000
	s_add_i32 s79, 0, 0x1c000
	ds_read_b128 v[132:135], v220 offset:32768
	ds_read_b128 v[156:159], v220 offset:33792
	ds_read_b128 v[160:163], v220 offset:34816
	ds_read_b128 v[168:171], v220 offset:35840
	ds_read_b128 v[172:175], v220 offset:49152
	ds_read_b128 v[176:179], v220 offset:50176
	ds_read_b128 v[180:183], v220 offset:51200
	ds_read_b128 v[184:187], v220 offset:52224
	s_add_u32 s44, s46, 0xb0000
	s_addc_u32 s45, s47, 0
	s_mov_b32 m0, s53
	ds_read_b128 v[188:191], v166 offset:32768
	ds_read_b128 v[192:195], v166 offset:33792
	ds_read_b128 v[196:199], v166 offset:34816
	ds_read_b128 v[200:203], v166 offset:35840
	ds_read_b128 v[204:207], v166 offset:36864
	ds_read_b128 v[208:211], v166 offset:37888
	ds_read_b128 v[212:215], v166 offset:38912
	global_load_lds_dwordx4 v136, s[44:45]
	s_mov_b32 m0, s54
	ds_read_b128 v[216:219], v166 offset:39936
	global_load_lds_dwordx4 v140, s[44:45]
	s_waitcnt vmcnt(8)
	s_waitcnt lgkmcnt(0)
	s_barrier
	s_setprio 1
	s_waitcnt lgkmcnt(0)
	v_mfma_f32_16x16x32_bf16 v[124:127], v[132:135], v[188:191], v[124:127]
	v_mfma_f32_16x16x32_bf16 v[120:123], v[160:163], v[188:191], v[120:123]
	v_mfma_f32_16x16x32_bf16 v[108:111], v[132:135], v[196:199], v[108:111]
	v_mfma_f32_16x16x32_bf16 v[104:107], v[160:163], v[196:199], v[104:107]
	v_mfma_f32_16x16x32_bf16 v[92:95], v[132:135], v[204:207], v[92:95]
	v_mfma_f32_16x16x32_bf16 v[88:91], v[160:163], v[204:207], v[88:91]
	v_mfma_f32_16x16x32_bf16 v[76:79], v[132:135], v[212:215], v[76:79]
	v_mfma_f32_16x16x32_bf16 v[72:75], v[160:163], v[212:215], v[72:75]
	v_mfma_f32_16x16x32_bf16 v[124:127], v[156:159], v[192:195], v[124:127]
	v_mfma_f32_16x16x32_bf16 v[120:123], v[168:171], v[192:195], v[120:123]
	v_mfma_f32_16x16x32_bf16 v[108:111], v[156:159], v[200:203], v[108:111]
	v_mfma_f32_16x16x32_bf16 v[104:107], v[168:171], v[200:203], v[104:107]
	v_mfma_f32_16x16x32_bf16 v[92:95], v[156:159], v[208:211], v[92:95]
	v_mfma_f32_16x16x32_bf16 v[88:91], v[168:171], v[208:211], v[88:91]
	v_mfma_f32_16x16x32_bf16 v[76:79], v[156:159], v[216:219], v[76:79]
	v_mfma_f32_16x16x32_bf16 v[72:75], v[168:171], v[216:219], v[72:75]
	s_setprio 0
	s_setprio 1
	v_mfma_f32_16x16x32_bf16 v[116:119], v[172:175], v[188:191], v[116:119]
	v_mfma_f32_16x16x32_bf16 v[112:115], v[180:183], v[188:191], v[112:115]
	v_mfma_f32_16x16x32_bf16 v[100:103], v[172:175], v[196:199], v[100:103]
	v_mfma_f32_16x16x32_bf16 v[96:99], v[180:183], v[196:199], v[96:99]
	v_mfma_f32_16x16x32_bf16 v[84:87], v[172:175], v[204:207], v[84:87]
	v_mfma_f32_16x16x32_bf16 v[80:83], v[180:183], v[204:207], v[80:83]
	v_mfma_f32_16x16x32_bf16 v[68:71], v[172:175], v[212:215], v[68:71]
	v_mfma_f32_16x16x32_bf16 v[64:67], v[180:183], v[212:215], v[64:67]
	v_mfma_f32_16x16x32_bf16 v[116:119], v[176:179], v[192:195], v[116:119]
	v_mfma_f32_16x16x32_bf16 v[112:115], v[184:187], v[192:195], v[112:115]
	v_mfma_f32_16x16x32_bf16 v[100:103], v[176:179], v[200:203], v[100:103]
	v_mfma_f32_16x16x32_bf16 v[96:99], v[184:187], v[200:203], v[96:99]
	v_mfma_f32_16x16x32_bf16 v[84:87], v[176:179], v[208:211], v[84:87]
	v_mfma_f32_16x16x32_bf16 v[80:83], v[184:187], v[208:211], v[80:83]
	v_mfma_f32_16x16x32_bf16 v[68:71], v[176:179], v[216:219], v[68:71]
	v_mfma_f32_16x16x32_bf16 v[64:67], v[184:187], v[216:219], v[64:67]
	s_setprio 0
	s_barrier
	s_add_i32 s8, s8, s50
	s_mov_b32 m0, s8
	ds_read_b128 v[188:191], v166 offset:49152
	ds_read_b128 v[192:195], v166 offset:50176
	ds_read_b128 v[196:199], v166 offset:51200
	global_load_lds_dwordx4 v138, s[40:41]
	s_add_i32 m0, s8, 0x2000
	ds_read_b128 v[200:203], v166 offset:52224
	global_load_lds_dwordx4 v142, s[40:41]
	s_add_u32 s40, s40, 0xb0000
	s_addc_u32 s41, s41, 0
	s_add_i32 s8, s79, s50
	s_mov_b32 m0, s8
	ds_read_b128 v[204:207], v166 offset:53248
	global_load_lds_dwordx4 v138, s[40:41]
	s_add_i32 m0, s8, 0x2000
	ds_read_b128 v[208:211], v166 offset:54272
	global_load_lds_dwordx4 v142, s[40:41]
	s_mov_b32 m0, s60
	ds_read_b128 v[212:215], v166 offset:55296
	global_load_lds_dwordx4 v136, s[38:39]
	s_mov_b32 m0, s61
	ds_read_b128 v[216:219], v166 offset:56320
	global_load_lds_dwordx4 v140, s[38:39]
	s_waitcnt vmcnt(8)
	s_waitcnt lgkmcnt(0)
	s_barrier
	s_setprio 1
	s_waitcnt lgkmcnt(0)
	v_mfma_f32_16x16x32_bf16 v[60:63], v[132:135], v[188:191], v[60:63]
	v_mfma_f32_16x16x32_bf16 v[56:59], v[160:163], v[188:191], v[56:59]
	v_mfma_f32_16x16x32_bf16 v[44:47], v[132:135], v[196:199], v[44:47]
	v_mfma_f32_16x16x32_bf16 v[40:43], v[160:163], v[196:199], v[40:43]
	v_mfma_f32_16x16x32_bf16 v[28:31], v[132:135], v[204:207], v[28:31]
	v_mfma_f32_16x16x32_bf16 v[24:27], v[160:163], v[204:207], v[24:27]
	v_mfma_f32_16x16x32_bf16 v[12:15], v[132:135], v[212:215], v[12:15]
	v_mfma_f32_16x16x32_bf16 v[8:11], v[160:163], v[212:215], v[8:11]
	v_mfma_f32_16x16x32_bf16 v[60:63], v[156:159], v[192:195], v[60:63]
	v_mfma_f32_16x16x32_bf16 v[56:59], v[168:171], v[192:195], v[56:59]
	v_mfma_f32_16x16x32_bf16 v[44:47], v[156:159], v[200:203], v[44:47]
	v_mfma_f32_16x16x32_bf16 v[40:43], v[168:171], v[200:203], v[40:43]
	v_mfma_f32_16x16x32_bf16 v[28:31], v[156:159], v[208:211], v[28:31]
	v_mfma_f32_16x16x32_bf16 v[24:27], v[168:171], v[208:211], v[24:27]
	v_mfma_f32_16x16x32_bf16 v[12:15], v[156:159], v[216:219], v[12:15]
	v_mfma_f32_16x16x32_bf16 v[8:11], v[168:171], v[216:219], v[8:11]
	s_setprio 0
	s_setprio 1
	v_mfma_f32_16x16x32_bf16 v[52:55], v[172:175], v[188:191], v[52:55]
	v_mfma_f32_16x16x32_bf16 v[48:51], v[180:183], v[188:191], v[48:51]
	v_mfma_f32_16x16x32_bf16 v[36:39], v[172:175], v[196:199], v[36:39]
	v_mfma_f32_16x16x32_bf16 v[32:35], v[180:183], v[196:199], v[32:35]
	v_mfma_f32_16x16x32_bf16 v[20:23], v[172:175], v[204:207], v[20:23]
	v_mfma_f32_16x16x32_bf16 v[16:19], v[180:183], v[204:207], v[16:19]
	v_mfma_f32_16x16x32_bf16 v[4:7], v[172:175], v[212:215], v[4:7]
	v_mfma_f32_16x16x32_bf16 v[0:3], v[180:183], v[212:215], v[0:3]
	v_mfma_f32_16x16x32_bf16 v[52:55], v[176:179], v[192:195], v[52:55]
	v_mfma_f32_16x16x32_bf16 v[48:51], v[184:187], v[192:195], v[48:51]
	v_mfma_f32_16x16x32_bf16 v[36:39], v[176:179], v[200:203], v[36:39]
	v_mfma_f32_16x16x32_bf16 v[32:35], v[184:187], v[200:203], v[32:35]
	v_mfma_f32_16x16x32_bf16 v[20:23], v[176:179], v[208:211], v[20:23]
	v_mfma_f32_16x16x32_bf16 v[16:19], v[184:187], v[208:211], v[16:19]
	v_mfma_f32_16x16x32_bf16 v[4:7], v[176:179], v[216:219], v[4:7]
	v_mfma_f32_16x16x32_bf16 v[0:3], v[184:187], v[216:219], v[0:3]
	s_setprio 0
	s_barrier
	s_add_i32 s8, s78, 2
	s_add_u32 s36, s36, 0x100
	s_addc_u32 s37, s37, 0
	s_cmp_gt_u32 s78, 41
	s_mov_b32 s78, s8
	s_cbranch_scc1 .LBB0_903
.LBB0_897:
	s_add_u32 s46, s26, s36
	s_addc_u32 s47, s27, s37
	s_mov_b64 s[100:101], s[46:47]
	s_add_u32 s80, s24, s36
	s_addc_u32 s79, s25, s37
	s_add_u32 s38, s46, 0x180
	s_addc_u32 s39, s47, 0
	s_add_u32 s40, s80, 0x180
	s_addc_u32 s41, s79, 0
	s_add_u32 s46, s46, 0x100
	s_addc_u32 s47, s47, 0
	s_add_u32 s44, s80, 0x100
	s_addc_u32 s45, s79, 0
	s_cmpk_eq_i32 s36, 0x1500
	s_cselect_b32 s38, s28, s38
	s_cselect_b32 s39, s29, s39
	s_cselect_b32 s40, s30, s40
	s_cselect_b32 s41, s31, s41
	s_cselect_b32 s46, s4, s46
	s_cselect_b32 s47, s5, s47
	s_cselect_b32 s44, s20, s44
	s_cselect_b32 s45, s21, s45
	s_branch .LBB0_896

.LBB0_1017:
	s_add_u32 s65, s54, s6
	s_addc_u32 s66, s55, s7
	s_add_u32 s67, s56, s8
	s_addc_u32 s68, s57, s9
	s_ashr_i32 s19, s18, 31
	s_lshl_b64 s[6:7], s[18:19], 19
	s_add_u32 s20, s34, s6
	s_addc_u32 s21, s35, s7
	s_and_b64 s[8:9], s[0:1], exec
	s_cselect_b32 s19, s21, s29
	s_cselect_b32 s69, s20, s28
	s_ashr_i32 s17, s16, 31
	s_lshl_b64 s[8:9], s[16:17], 19
	s_add_u32 s22, s48, s8
	s_addc_u32 s23, s49, s9
	s_and_b64 s[30:31], s[0:1], exec
	s_cselect_b32 s17, s23, s27
	s_cselect_b32 s70, s22, s26
	s_add_u32 s30, s69, 0x80
	s_addc_u32 s31, s19, 0
	s_add_u32 s36, s70, 0x80
	s_addc_u32 s37, s17, 0
	v_lshl_add_u64 v[128:129], s[28:29], 0, v[196:197]
	v_lshl_add_u64 v[130:131], s[28:29], 0, v[198:199]
	s_mov_b32 s71, 0
	s_mov_b64 s[38:39], 0
	v_add_u32_e32 v216, 0x10000, v220
	s_add_u32 s46, s28, s38
	s_addc_u32 s47, s29, s39
	s_mov_b64 s[100:101], s[46:47]
	s_add_u32 s73, s26, s38
	s_addc_u32 s72, s27, s39
	s_add_u32 s40, s46, 0x180
	s_addc_u32 s41, s47, 0
	s_add_u32 s42, s73, 0x180
	s_addc_u32 s43, s72, 0
	s_add_u32 s46, s46, 0x100
	s_addc_u32 s47, s47, 0
	s_add_u32 s44, s73, 0x100
	s_addc_u32 s45, s72, 0
	s_cmpk_eq_i32 s38, 0x700
	s_cselect_b32 s40, s30, s40
	s_cselect_b32 s41, s31, s41
	s_cselect_b32 s42, s36, s42
	s_cselect_b32 s43, s37, s43
	s_cselect_b32 s46, s69, s46
	s_cselect_b32 s47, s19, s47
	s_cselect_b32 s44, s70, s44
	s_cselect_b32 s45, s17, s45
	ds_read_b128 v[132:135], v216
	ds_read_b128 v[136:139], v216 offset:1024
	ds_read_b128 v[140:143], v216 offset:2048
	ds_read_b128 v[144:147], v216 offset:3072
	ds_read_b128 v[148:151], v216 offset:16384
	ds_read_b128 v[152:155], v216 offset:17408
	ds_read_b128 v[156:159], v216 offset:18432
	ds_read_b128 v[160:163], v216 offset:19456
	s_add_i32 m0, s25, 0xc000
	ds_read_b128 v[164:167], v221
	ds_read_b128 v[168:171], v221 offset:1024
	ds_read_b128 v[172:175], v221 offset:2048
	ds_read_b128 v[176:179], v221 offset:3072
	ds_read_b128 v[180:183], v221 offset:4096
	ds_read_b128 v[204:207], v221 offset:5120
	ds_read_b128 v[208:211], v221 offset:6144
	global_load_lds_dwordx4 v196, s[100:101]
	s_add_i32 m0, s25, 0xe000
	ds_read_b128 v[212:215], v221 offset:7168
	global_load_lds_dwordx4 v198, s[100:101]
	s_waitcnt vmcnt(8)
	s_waitcnt lgkmcnt(0)
	s_barrier
	s_setprio 1
	s_waitcnt lgkmcnt(0)
	v_mfma_f32_16x16x32_bf16 v[124:127], v[132:135], v[164:167], 0
	v_mfma_f32_16x16x32_bf16 v[120:123], v[140:143], v[164:167], 0
	v_mfma_f32_16x16x32_bf16 v[108:111], v[132:135], v[172:175], 0
	v_mfma_f32_16x16x32_bf16 v[104:107], v[140:143], v[172:175], 0
	v_mfma_f32_16x16x32_bf16 v[92:95], v[132:135], v[180:183], 0
	v_mfma_f32_16x16x32_bf16 v[88:91], v[140:143], v[180:183], 0
	v_mfma_f32_16x16x32_bf16 v[76:79], v[132:135], v[208:211], 0
	v_mfma_f32_16x16x32_bf16 v[72:75], v[140:143], v[208:211], 0
	v_mfma_f32_16x16x32_bf16 v[124:127], v[136:139], v[168:171], v[124:127]
	v_mfma_f32_16x16x32_bf16 v[120:123], v[144:147], v[168:171], v[120:123]
	v_mfma_f32_16x16x32_bf16 v[108:111], v[136:139], v[176:179], v[108:111]
	v_mfma_f32_16x16x32_bf16 v[104:107], v[144:147], v[176:179], v[104:107]
	v_mfma_f32_16x16x32_bf16 v[92:95], v[136:139], v[204:207], v[92:95]
	v_mfma_f32_16x16x32_bf16 v[88:91], v[144:147], v[204:207], v[88:91]
	v_mfma_f32_16x16x32_bf16 v[76:79], v[136:139], v[212:215], v[76:79]
	v_mfma_f32_16x16x32_bf16 v[72:75], v[144:147], v[212:215], v[72:75]
	s_setprio 0
	s_setprio 1
	v_mfma_f32_16x16x32_bf16 v[116:119], v[148:151], v[164:167], 0
	v_mfma_f32_16x16x32_bf16 v[112:115], v[156:159], v[164:167], 0
	v_mfma_f32_16x16x32_bf16 v[100:103], v[148:151], v[172:175], 0
	v_mfma_f32_16x16x32_bf16 v[96:99], v[156:159], v[172:175], 0
	v_mfma_f32_16x16x32_bf16 v[84:87], v[148:151], v[180:183], 0
	v_mfma_f32_16x16x32_bf16 v[80:83], v[156:159], v[180:183], 0
	v_mfma_f32_16x16x32_bf16 v[68:71], v[148:151], v[208:211], 0
	v_mfma_f32_16x16x32_bf16 v[64:67], v[156:159], v[208:211], 0
	v_mfma_f32_16x16x32_bf16 v[116:119], v[152:155], v[168:171], v[116:119]
	v_mfma_f32_16x16x32_bf16 v[112:115], v[160:163], v[168:171], v[112:115]
	v_mfma_f32_16x16x32_bf16 v[100:103], v[152:155], v[176:179], v[100:103]
	v_mfma_f32_16x16x32_bf16 v[96:99], v[160:163], v[176:179], v[96:99]
	v_mfma_f32_16x16x32_bf16 v[84:87], v[152:155], v[204:207], v[84:87]
	v_mfma_f32_16x16x32_bf16 v[80:83], v[160:163], v[204:207], v[80:83]
	v_mfma_f32_16x16x32_bf16 v[68:71], v[152:155], v[212:215], v[68:71]
	v_mfma_f32_16x16x32_bf16 v[64:67], v[160:163], v[212:215], v[64:67]
	s_setprio 0
	s_barrier
	s_add_i32 s10, s61, s50
	s_mov_b32 m0, s10
	ds_read_b128 v[164:167], v221 offset:16384
	ds_read_b128 v[168:171], v221 offset:17408
	ds_read_b128 v[172:175], v221 offset:18432
	global_load_lds_dwordx4 v186, s[44:45]
	s_add_i32 m0, s10, 0x2000
	ds_read_b128 v[176:179], v221 offset:19456
	global_load_lds_dwordx4 v190, s[44:45]
	s_add_u32 s44, s44, 0x40000
	s_addc_u32 s45, s45, 0
	s_add_i32 s10, s62, s50
	s_mov_b32 m0, s10
	ds_read_b128 v[180:183], v221 offset:20480
	global_load_lds_dwordx4 v186, s[44:45]
	s_add_i32 m0, s10, 0x2000
	ds_read_b128 v[204:207], v221 offset:21504
	global_load_lds_dwordx4 v190, s[44:45]
	s_mov_b32 m0, s25
	ds_read_b128 v[208:211], v221 offset:22528
	global_load_lds_dwordx4 v184, s[46:47]
	s_mov_b32 m0, s51
	ds_read_b128 v[212:215], v221 offset:23552
	global_load_lds_dwordx4 v188, s[46:47]
	s_waitcnt vmcnt(8)
	s_waitcnt lgkmcnt(0)
	s_barrier
	s_setprio 1
	s_waitcnt lgkmcnt(0)
	v_mfma_f32_16x16x32_bf16 v[60:63], v[132:135], v[164:167], 0
	v_mfma_f32_16x16x32_bf16 v[56:59], v[140:143], v[164:167], 0
	v_mfma_f32_16x16x32_bf16 v[44:47], v[132:135], v[172:175], 0
	v_mfma_f32_16x16x32_bf16 v[40:43], v[140:143], v[172:175], 0
	v_mfma_f32_16x16x32_bf16 v[28:31], v[132:135], v[180:183], 0
	v_mfma_f32_16x16x32_bf16 v[24:27], v[140:143], v[180:183], 0
	v_mfma_f32_16x16x32_bf16 v[12:15], v[132:135], v[208:211], 0
	v_mfma_f32_16x16x32_bf16 v[8:11], v[140:143], v[208:211], 0
	v_mfma_f32_16x16x32_bf16 v[60:63], v[136:139], v[168:171], v[60:63]
	v_mfma_f32_16x16x32_bf16 v[56:59], v[144:147], v[168:171], v[56:59]
	v_mfma_f32_16x16x32_bf16 v[44:47], v[136:139], v[176:179], v[44:47]
	v_mfma_f32_16x16x32_bf16 v[40:43], v[144:147], v[176:179], v[40:43]
	v_mfma_f32_16x16x32_bf16 v[28:31], v[136:139], v[204:207], v[28:31]
	v_mfma_f32_16x16x32_bf16 v[24:27], v[144:147], v[204:207], v[24:27]
	v_mfma_f32_16x16x32_bf16 v[12:15], v[136:139], v[212:215], v[12:15]
	v_mfma_f32_16x16x32_bf16 v[8:11], v[144:147], v[212:215], v[8:11]
	s_setprio 0
	s_setprio 1
	v_mfma_f32_16x16x32_bf16 v[52:55], v[148:151], v[164:167], 0
	v_mfma_f32_16x16x32_bf16 v[48:51], v[156:159], v[164:167], 0
	v_mfma_f32_16x16x32_bf16 v[36:39], v[148:151], v[172:175], 0
	v_mfma_f32_16x16x32_bf16 v[32:35], v[156:159], v[172:175], 0
	v_mfma_f32_16x16x32_bf16 v[20:23], v[148:151], v[180:183], 0
	v_mfma_f32_16x16x32_bf16 v[16:19], v[156:159], v[180:183], 0
	v_mfma_f32_16x16x32_bf16 v[4:7], v[148:151], v[208:211], 0
	v_mfma_f32_16x16x32_bf16 v[0:3], v[156:159], v[208:211], 0
	v_mfma_f32_16x16x32_bf16 v[52:55], v[152:155], v[168:171], v[52:55]
	v_mfma_f32_16x16x32_bf16 v[48:51], v[160:163], v[168:171], v[48:51]
	v_mfma_f32_16x16x32_bf16 v[36:39], v[152:155], v[176:179], v[36:39]
	v_mfma_f32_16x16x32_bf16 v[32:35], v[160:163], v[176:179], v[32:35]
	v_mfma_f32_16x16x32_bf16 v[20:23], v[152:155], v[204:207], v[20:23]
	v_mfma_f32_16x16x32_bf16 v[16:19], v[160:163], v[204:207], v[16:19]
	v_mfma_f32_16x16x32_bf16 v[4:7], v[152:155], v[212:215], v[4:7]
	v_mfma_f32_16x16x32_bf16 v[0:3], v[160:163], v[212:215], v[0:3]
	s_setprio 0
	s_barrier
	s_add_i32 s10, 0, 0x18000
	s_add_i32 s72, 0, 0x1c000
	ds_read_b128 v[132:135], v216 offset:32768
	ds_read_b128 v[136:139], v216 offset:33792
	ds_read_b128 v[140:143], v216 offset:34816
	ds_read_b128 v[144:147], v216 offset:35840
	ds_read_b128 v[148:151], v216 offset:49152
	ds_read_b128 v[152:155], v216 offset:50176
	ds_read_b128 v[156:159], v216 offset:51200
	ds_read_b128 v[160:163], v216 offset:52224
	s_add_u32 s44, s46, 0x40000
	s_addc_u32 s45, s47, 0
	s_mov_b32 m0, s52
	ds_read_b128 v[164:167], v221 offset:32768
	ds_read_b128 v[168:171], v221 offset:33792
	ds_read_b128 v[172:175], v221 offset:34816
	ds_read_b128 v[176:179], v221 offset:35840
	ds_read_b128 v[180:183], v221 offset:36864
	ds_read_b128 v[204:207], v221 offset:37888
	ds_read_b128 v[208:211], v221 offset:38912
	global_load_lds_dwordx4 v184, s[44:45]
	s_mov_b32 m0, s53
	ds_read_b128 v[212:215], v221 offset:39936
	global_load_lds_dwordx4 v188, s[44:45]
	s_waitcnt vmcnt(8)
	s_waitcnt lgkmcnt(0)
	s_barrier
	s_setprio 1
	s_waitcnt lgkmcnt(0)
	v_mfma_f32_16x16x32_bf16 v[124:127], v[132:135], v[164:167], v[124:127]
	v_mfma_f32_16x16x32_bf16 v[120:123], v[140:143], v[164:167], v[120:123]
	v_mfma_f32_16x16x32_bf16 v[108:111], v[132:135], v[172:175], v[108:111]
	v_mfma_f32_16x16x32_bf16 v[104:107], v[140:143], v[172:175], v[104:107]
	v_mfma_f32_16x16x32_bf16 v[92:95], v[132:135], v[180:183], v[92:95]
	v_mfma_f32_16x16x32_bf16 v[88:91], v[140:143], v[180:183], v[88:91]
	v_mfma_f32_16x16x32_bf16 v[76:79], v[132:135], v[208:211], v[76:79]
	v_mfma_f32_16x16x32_bf16 v[72:75], v[140:143], v[208:211], v[72:75]
	v_mfma_f32_16x16x32_bf16 v[124:127], v[136:139], v[168:171], v[124:127]
	v_mfma_f32_16x16x32_bf16 v[120:123], v[144:147], v[168:171], v[120:123]
	v_mfma_f32_16x16x32_bf16 v[108:111], v[136:139], v[176:179], v[108:111]
	v_mfma_f32_16x16x32_bf16 v[104:107], v[144:147], v[176:179], v[104:107]
	v_mfma_f32_16x16x32_bf16 v[92:95], v[136:139], v[204:207], v[92:95]
	v_mfma_f32_16x16x32_bf16 v[88:91], v[144:147], v[204:207], v[88:91]
	v_mfma_f32_16x16x32_bf16 v[76:79], v[136:139], v[212:215], v[76:79]
	v_mfma_f32_16x16x32_bf16 v[72:75], v[144:147], v[212:215], v[72:75]
	s_setprio 0
	s_setprio 1
	v_mfma_f32_16x16x32_bf16 v[116:119], v[148:151], v[164:167], v[116:119]
	v_mfma_f32_16x16x32_bf16 v[112:115], v[156:159], v[164:167], v[112:115]
	v_mfma_f32_16x16x32_bf16 v[100:103], v[148:151], v[172:175], v[100:103]
	v_mfma_f32_16x16x32_bf16 v[96:99], v[156:159], v[172:175], v[96:99]
	v_mfma_f32_16x16x32_bf16 v[84:87], v[148:151], v[180:183], v[84:87]
	v_mfma_f32_16x16x32_bf16 v[80:83], v[156:159], v[180:183], v[80:83]
	v_mfma_f32_16x16x32_bf16 v[68:71], v[148:151], v[208:211], v[68:71]
	v_mfma_f32_16x16x32_bf16 v[64:67], v[156:159], v[208:211], v[64:67]
	v_mfma_f32_16x16x32_bf16 v[116:119], v[152:155], v[168:171], v[116:119]
	v_mfma_f32_16x16x32_bf16 v[112:115], v[160:163], v[168:171], v[112:115]
	v_mfma_f32_16x16x32_bf16 v[100:103], v[152:155], v[176:179], v[100:103]
	v_mfma_f32_16x16x32_bf16 v[96:99], v[160:163], v[176:179], v[96:99]
	v_mfma_f32_16x16x32_bf16 v[84:87], v[152:155], v[204:207], v[84:87]
	v_mfma_f32_16x16x32_bf16 v[80:83], v[160:163], v[204:207], v[80:83]
	v_mfma_f32_16x16x32_bf16 v[68:71], v[152:155], v[212:215], v[68:71]
	v_mfma_f32_16x16x32_bf16 v[64:67], v[160:163], v[212:215], v[64:67]
	s_setprio 0
	s_barrier
	s_add_i32 s10, s10, s50
	s_mov_b32 m0, s10
	ds_read_b128 v[164:167], v221 offset:49152
	ds_read_b128 v[168:171], v221 offset:50176
	ds_read_b128 v[172:175], v221 offset:51200
	global_load_lds_dwordx4 v186, s[42:43]
	s_add_i32 m0, s10, 0x2000
	ds_read_b128 v[176:179], v221 offset:52224
	global_load_lds_dwordx4 v190, s[42:43]
	s_add_u32 s42, s42, 0x40000
	s_addc_u32 s43, s43, 0
	s_add_i32 s10, s72, s50
	s_mov_b32 m0, s10
	ds_read_b128 v[180:183], v221 offset:53248
	global_load_lds_dwordx4 v186, s[42:43]
	s_add_i32 m0, s10, 0x2000
	ds_read_b128 v[204:207], v221 offset:54272
	global_load_lds_dwordx4 v190, s[42:43]
	s_mov_b32 m0, s58
	ds_read_b128 v[208:211], v221 offset:55296
	global_load_lds_dwordx4 v184, s[40:41]
	s_mov_b32 m0, s59
	ds_read_b128 v[212:215], v221 offset:56320
	global_load_lds_dwordx4 v188, s[40:41]
	s_waitcnt vmcnt(8)
	s_waitcnt lgkmcnt(0)
	s_barrier
	s_setprio 1
	s_waitcnt lgkmcnt(0)
	v_mfma_f32_16x16x32_bf16 v[60:63], v[132:135], v[164:167], v[60:63]
	v_mfma_f32_16x16x32_bf16 v[56:59], v[140:143], v[164:167], v[56:59]
	v_mfma_f32_16x16x32_bf16 v[44:47], v[132:135], v[172:175], v[44:47]
	v_mfma_f32_16x16x32_bf16 v[40:43], v[140:143], v[172:175], v[40:43]
	v_mfma_f32_16x16x32_bf16 v[28:31], v[132:135], v[180:183], v[28:31]
	v_mfma_f32_16x16x32_bf16 v[24:27], v[140:143], v[180:183], v[24:27]
	v_mfma_f32_16x16x32_bf16 v[12:15], v[132:135], v[208:211], v[12:15]
	v_mfma_f32_16x16x32_bf16 v[8:11], v[140:143], v[208:211], v[8:11]
	v_mfma_f32_16x16x32_bf16 v[60:63], v[136:139], v[168:171], v[60:63]
	v_mfma_f32_16x16x32_bf16 v[56:59], v[144:147], v[168:171], v[56:59]
	v_mfma_f32_16x16x32_bf16 v[44:47], v[136:139], v[176:179], v[44:47]
	v_mfma_f32_16x16x32_bf16 v[40:43], v[144:147], v[176:179], v[40:43]
	v_mfma_f32_16x16x32_bf16 v[28:31], v[136:139], v[204:207], v[28:31]
	v_mfma_f32_16x16x32_bf16 v[24:27], v[144:147], v[204:207], v[24:27]
	v_mfma_f32_16x16x32_bf16 v[12:15], v[136:139], v[212:215], v[12:15]
	v_mfma_f32_16x16x32_bf16 v[8:11], v[144:147], v[212:215], v[8:11]
	s_setprio 0
	s_setprio 1
	v_mfma_f32_16x16x32_bf16 v[52:55], v[148:151], v[164:167], v[52:55]
	v_mfma_f32_16x16x32_bf16 v[48:51], v[156:159], v[164:167], v[48:51]
	v_mfma_f32_16x16x32_bf16 v[36:39], v[148:151], v[172:175], v[36:39]
	v_mfma_f32_16x16x32_bf16 v[32:35], v[156:159], v[172:175], v[32:35]
	v_mfma_f32_16x16x32_bf16 v[20:23], v[148:151], v[180:183], v[20:23]
	v_mfma_f32_16x16x32_bf16 v[16:19], v[156:159], v[180:183], v[16:19]
	v_mfma_f32_16x16x32_bf16 v[4:7], v[148:151], v[208:211], v[4:7]
	v_mfma_f32_16x16x32_bf16 v[0:3], v[156:159], v[208:211], v[0:3]
	v_mfma_f32_16x16x32_bf16 v[52:55], v[152:155], v[168:171], v[52:55]
	v_mfma_f32_16x16x32_bf16 v[48:51], v[160:163], v[168:171], v[48:51]
	v_mfma_f32_16x16x32_bf16 v[36:39], v[152:155], v[176:179], v[36:39]
	v_mfma_f32_16x16x32_bf16 v[32:35], v[160:163], v[176:179], v[32:35]
	v_mfma_f32_16x16x32_bf16 v[20:23], v[152:155], v[204:207], v[20:23]
	v_mfma_f32_16x16x32_bf16 v[16:19], v[160:163], v[204:207], v[16:19]
	v_mfma_f32_16x16x32_bf16 v[4:7], v[152:155], v[212:215], v[4:7]
	v_mfma_f32_16x16x32_bf16 v[0:3], v[160:163], v[212:215], v[0:3]
	s_setprio 0
	s_barrier
	s_add_i32 s10, s71, 2
	s_add_u32 s38, s38, 0x100
	s_addc_u32 s39, s39, 0
	s_cmp_gt_u32 s71, 13
	s_mov_b32 s71, s10
	s_cbranch_scc1 .LBB0_1025
	s_branch .LBB0_1019
.LBB0_1018:
	ds_read_b128 v[132:135], v216
	ds_read_b128 v[136:139], v216 offset:1024
	ds_read_b128 v[140:143], v216 offset:2048
	ds_read_b128 v[144:147], v216 offset:3072
	ds_read_b128 v[148:151], v216 offset:16384
	ds_read_b128 v[152:155], v216 offset:17408
	ds_read_b128 v[156:159], v216 offset:18432
	ds_read_b128 v[160:163], v216 offset:19456
	s_add_i32 m0, s25, 0xc000
	ds_read_b128 v[164:167], v221
	ds_read_b128 v[168:171], v221 offset:1024
	ds_read_b128 v[172:175], v221 offset:2048
	ds_read_b128 v[176:179], v221 offset:3072
	ds_read_b128 v[180:183], v221 offset:4096
	ds_read_b128 v[204:207], v221 offset:5120
	ds_read_b128 v[208:211], v221 offset:6144
	global_load_lds_dwordx4 v196, s[100:101]
	s_add_i32 m0, s25, 0xe000
	ds_read_b128 v[212:215], v221 offset:7168
	global_load_lds_dwordx4 v198, s[100:101]
	s_waitcnt vmcnt(8)
	s_waitcnt lgkmcnt(0)
	s_barrier
	s_setprio 1
	s_waitcnt lgkmcnt(0)
	v_mfma_f32_16x16x32_bf16 v[124:127], v[132:135], v[164:167], v[124:127]
	v_mfma_f32_16x16x32_bf16 v[120:123], v[140:143], v[164:167], v[120:123]
	v_mfma_f32_16x16x32_bf16 v[108:111], v[132:135], v[172:175], v[108:111]
	v_mfma_f32_16x16x32_bf16 v[104:107], v[140:143], v[172:175], v[104:107]
	v_mfma_f32_16x16x32_bf16 v[92:95], v[132:135], v[180:183], v[92:95]
	v_mfma_f32_16x16x32_bf16 v[88:91], v[140:143], v[180:183], v[88:91]
	v_mfma_f32_16x16x32_bf16 v[76:79], v[132:135], v[208:211], v[76:79]
	v_mfma_f32_16x16x32_bf16 v[72:75], v[140:143], v[208:211], v[72:75]
	v_mfma_f32_16x16x32_bf16 v[124:127], v[136:139], v[168:171], v[124:127]
	v_mfma_f32_16x16x32_bf16 v[120:123], v[144:147], v[168:171], v[120:123]
	v_mfma_f32_16x16x32_bf16 v[108:111], v[136:139], v[176:179], v[108:111]
	v_mfma_f32_16x16x32_bf16 v[104:107], v[144:147], v[176:179], v[104:107]
	v_mfma_f32_16x16x32_bf16 v[92:95], v[136:139], v[204:207], v[92:95]
	v_mfma_f32_16x16x32_bf16 v[88:91], v[144:147], v[204:207], v[88:91]
	v_mfma_f32_16x16x32_bf16 v[76:79], v[136:139], v[212:215], v[76:79]
	v_mfma_f32_16x16x32_bf16 v[72:75], v[144:147], v[212:215], v[72:75]
	s_setprio 0
	s_setprio 1
	v_mfma_f32_16x16x32_bf16 v[116:119], v[148:151], v[164:167], v[116:119]
	v_mfma_f32_16x16x32_bf16 v[112:115], v[156:159], v[164:167], v[112:115]
	v_mfma_f32_16x16x32_bf16 v[100:103], v[148:151], v[172:175], v[100:103]
	v_mfma_f32_16x16x32_bf16 v[96:99], v[156:159], v[172:175], v[96:99]
	v_mfma_f32_16x16x32_bf16 v[84:87], v[148:151], v[180:183], v[84:87]
	v_mfma_f32_16x16x32_bf16 v[80:83], v[156:159], v[180:183], v[80:83]
	v_mfma_f32_16x16x32_bf16 v[68:71], v[148:151], v[208:211], v[68:71]
	v_mfma_f32_16x16x32_bf16 v[64:67], v[156:159], v[208:211], v[64:67]
	v_mfma_f32_16x16x32_bf16 v[116:119], v[152:155], v[168:171], v[116:119]
	v_mfma_f32_16x16x32_bf16 v[112:115], v[160:163], v[168:171], v[112:115]
	v_mfma_f32_16x16x32_bf16 v[100:103], v[152:155], v[176:179], v[100:103]
	v_mfma_f32_16x16x32_bf16 v[96:99], v[160:163], v[176:179], v[96:99]
	v_mfma_f32_16x16x32_bf16 v[84:87], v[152:155], v[204:207], v[84:87]
	v_mfma_f32_16x16x32_bf16 v[80:83], v[160:163], v[204:207], v[80:83]
	v_mfma_f32_16x16x32_bf16 v[68:71], v[152:155], v[212:215], v[68:71]
	v_mfma_f32_16x16x32_bf16 v[64:67], v[160:163], v[212:215], v[64:67]
	s_setprio 0
	s_barrier
	s_add_i32 s10, s61, s50
	s_mov_b32 m0, s10
	ds_read_b128 v[164:167], v221 offset:16384
	ds_read_b128 v[168:171], v221 offset:17408
	ds_read_b128 v[172:175], v221 offset:18432
	global_load_lds_dwordx4 v186, s[44:45]
	s_add_i32 m0, s10, 0x2000
	ds_read_b128 v[176:179], v221 offset:19456
	global_load_lds_dwordx4 v190, s[44:45]
	s_add_u32 s44, s44, 0x40000
	s_addc_u32 s45, s45, 0
	s_add_i32 s10, s62, s50
	s_mov_b32 m0, s10
	ds_read_b128 v[180:183], v221 offset:20480
	global_load_lds_dwordx4 v186, s[44:45]
	s_add_i32 m0, s10, 0x2000
	ds_read_b128 v[204:207], v221 offset:21504
	global_load_lds_dwordx4 v190, s[44:45]
	s_mov_b32 m0, s25
	ds_read_b128 v[208:211], v221 offset:22528
	global_load_lds_dwordx4 v184, s[46:47]
	s_mov_b32 m0, s51
	ds_read_b128 v[212:215], v221 offset:23552
	global_load_lds_dwordx4 v188, s[46:47]
	s_waitcnt vmcnt(8)
	s_waitcnt lgkmcnt(0)
	s_barrier
	s_setprio 1
	s_waitcnt lgkmcnt(0)
	v_mfma_f32_16x16x32_bf16 v[60:63], v[132:135], v[164:167], v[60:63]
	v_mfma_f32_16x16x32_bf16 v[56:59], v[140:143], v[164:167], v[56:59]
	v_mfma_f32_16x16x32_bf16 v[44:47], v[132:135], v[172:175], v[44:47]
	v_mfma_f32_16x16x32_bf16 v[40:43], v[140:143], v[172:175], v[40:43]
	v_mfma_f32_16x16x32_bf16 v[28:31], v[132:135], v[180:183], v[28:31]
	v_mfma_f32_16x16x32_bf16 v[24:27], v[140:143], v[180:183], v[24:27]
	v_mfma_f32_16x16x32_bf16 v[12:15], v[132:135], v[208:211], v[12:15]
	v_mfma_f32_16x16x32_bf16 v[8:11], v[140:143], v[208:211], v[8:11]
	v_mfma_f32_16x16x32_bf16 v[60:63], v[136:139], v[168:171], v[60:63]
	v_mfma_f32_16x16x32_bf16 v[56:59], v[144:147], v[168:171], v[56:59]
	v_mfma_f32_16x16x32_bf16 v[44:47], v[136:139], v[176:179], v[44:47]
	v_mfma_f32_16x16x32_bf16 v[40:43], v[144:147], v[176:179], v[40:43]
	v_mfma_f32_16x16x32_bf16 v[28:31], v[136:139], v[204:207], v[28:31]
	v_mfma_f32_16x16x32_bf16 v[24:27], v[144:147], v[204:207], v[24:27]
	v_mfma_f32_16x16x32_bf16 v[12:15], v[136:139], v[212:215], v[12:15]
	v_mfma_f32_16x16x32_bf16 v[8:11], v[144:147], v[212:215], v[8:11]
	s_setprio 0
	s_setprio 1
	v_mfma_f32_16x16x32_bf16 v[52:55], v[148:151], v[164:167], v[52:55]
	v_mfma_f32_16x16x32_bf16 v[48:51], v[156:159], v[164:167], v[48:51]
	v_mfma_f32_16x16x32_bf16 v[36:39], v[148:151], v[172:175], v[36:39]
	v_mfma_f32_16x16x32_bf16 v[32:35], v[156:159], v[172:175], v[32:35]
	v_mfma_f32_16x16x32_bf16 v[20:23], v[148:151], v[180:183], v[20:23]
	v_mfma_f32_16x16x32_bf16 v[16:19], v[156:159], v[180:183], v[16:19]
	v_mfma_f32_16x16x32_bf16 v[4:7], v[148:151], v[208:211], v[4:7]
	v_mfma_f32_16x16x32_bf16 v[0:3], v[156:159], v[208:211], v[0:3]
	v_mfma_f32_16x16x32_bf16 v[52:55], v[152:155], v[168:171], v[52:55]
	v_mfma_f32_16x16x32_bf16 v[48:51], v[160:163], v[168:171], v[48:51]
	v_mfma_f32_16x16x32_bf16 v[36:39], v[152:155], v[176:179], v[36:39]
	v_mfma_f32_16x16x32_bf16 v[32:35], v[160:163], v[176:179], v[32:35]
	v_mfma_f32_16x16x32_bf16 v[20:23], v[152:155], v[204:207], v[20:23]
	v_mfma_f32_16x16x32_bf16 v[16:19], v[160:163], v[204:207], v[16:19]
	v_mfma_f32_16x16x32_bf16 v[4:7], v[152:155], v[212:215], v[4:7]
	v_mfma_f32_16x16x32_bf16 v[0:3], v[160:163], v[212:215], v[0:3]
	s_setprio 0
	s_barrier
	s_add_i32 s10, 0, 0x18000
	s_add_i32 s72, 0, 0x1c000
	ds_read_b128 v[132:135], v216 offset:32768
	ds_read_b128 v[136:139], v216 offset:33792
	ds_read_b128 v[140:143], v216 offset:34816
	ds_read_b128 v[144:147], v216 offset:35840
	ds_read_b128 v[148:151], v216 offset:49152
	ds_read_b128 v[152:155], v216 offset:50176
	ds_read_b128 v[156:159], v216 offset:51200
	ds_read_b128 v[160:163], v216 offset:52224
	s_add_u32 s44, s46, 0x40000
	s_addc_u32 s45, s47, 0
	s_mov_b32 m0, s52
	ds_read_b128 v[164:167], v221 offset:32768
	ds_read_b128 v[168:171], v221 offset:33792
	ds_read_b128 v[172:175], v221 offset:34816
	ds_read_b128 v[176:179], v221 offset:35840
	ds_read_b128 v[180:183], v221 offset:36864
	ds_read_b128 v[204:207], v221 offset:37888
	ds_read_b128 v[208:211], v221 offset:38912
	global_load_lds_dwordx4 v184, s[44:45]
	s_mov_b32 m0, s53
	ds_read_b128 v[212:215], v221 offset:39936
	global_load_lds_dwordx4 v188, s[44:45]
	s_waitcnt vmcnt(8)
	s_waitcnt lgkmcnt(0)
	s_barrier
	s_setprio 1
	s_waitcnt lgkmcnt(0)
	v_mfma_f32_16x16x32_bf16 v[124:127], v[132:135], v[164:167], v[124:127]
	v_mfma_f32_16x16x32_bf16 v[120:123], v[140:143], v[164:167], v[120:123]
	v_mfma_f32_16x16x32_bf16 v[108:111], v[132:135], v[172:175], v[108:111]
	v_mfma_f32_16x16x32_bf16 v[104:107], v[140:143], v[172:175], v[104:107]
	v_mfma_f32_16x16x32_bf16 v[92:95], v[132:135], v[180:183], v[92:95]
	v_mfma_f32_16x16x32_bf16 v[88:91], v[140:143], v[180:183], v[88:91]
	v_mfma_f32_16x16x32_bf16 v[76:79], v[132:135], v[208:211], v[76:79]
	v_mfma_f32_16x16x32_bf16 v[72:75], v[140:143], v[208:211], v[72:75]
	v_mfma_f32_16x16x32_bf16 v[124:127], v[136:139], v[168:171], v[124:127]
	v_mfma_f32_16x16x32_bf16 v[120:123], v[144:147], v[168:171], v[120:123]
	v_mfma_f32_16x16x32_bf16 v[108:111], v[136:139], v[176:179], v[108:111]
	v_mfma_f32_16x16x32_bf16 v[104:107], v[144:147], v[176:179], v[104:107]
	v_mfma_f32_16x16x32_bf16 v[92:95], v[136:139], v[204:207], v[92:95]
	v_mfma_f32_16x16x32_bf16 v[88:91], v[144:147], v[204:207], v[88:91]
	v_mfma_f32_16x16x32_bf16 v[76:79], v[136:139], v[212:215], v[76:79]
	v_mfma_f32_16x16x32_bf16 v[72:75], v[144:147], v[212:215], v[72:75]
	s_setprio 0
	s_setprio 1
	v_mfma_f32_16x16x32_bf16 v[116:119], v[148:151], v[164:167], v[116:119]
	v_mfma_f32_16x16x32_bf16 v[112:115], v[156:159], v[164:167], v[112:115]
	v_mfma_f32_16x16x32_bf16 v[100:103], v[148:151], v[172:175], v[100:103]
	v_mfma_f32_16x16x32_bf16 v[96:99], v[156:159], v[172:175], v[96:99]
	v_mfma_f32_16x16x32_bf16 v[84:87], v[148:151], v[180:183], v[84:87]
	v_mfma_f32_16x16x32_bf16 v[80:83], v[156:159], v[180:183], v[80:83]
	v_mfma_f32_16x16x32_bf16 v[68:71], v[148:151], v[208:211], v[68:71]
	v_mfma_f32_16x16x32_bf16 v[64:67], v[156:159], v[208:211], v[64:67]
	v_mfma_f32_16x16x32_bf16 v[116:119], v[152:155], v[168:171], v[116:119]
	v_mfma_f32_16x16x32_bf16 v[112:115], v[160:163], v[168:171], v[112:115]
	v_mfma_f32_16x16x32_bf16 v[100:103], v[152:155], v[176:179], v[100:103]
	v_mfma_f32_16x16x32_bf16 v[96:99], v[160:163], v[176:179], v[96:99]
	v_mfma_f32_16x16x32_bf16 v[84:87], v[152:155], v[204:207], v[84:87]
	v_mfma_f32_16x16x32_bf16 v[80:83], v[160:163], v[204:207], v[80:83]
	v_mfma_f32_16x16x32_bf16 v[68:71], v[152:155], v[212:215], v[68:71]
	v_mfma_f32_16x16x32_bf16 v[64:67], v[160:163], v[212:215], v[64:67]
	s_setprio 0
	s_barrier
	s_add_i32 s10, s10, s50
	s_mov_b32 m0, s10
	ds_read_b128 v[164:167], v221 offset:49152
	ds_read_b128 v[168:171], v221 offset:50176
	ds_read_b128 v[172:175], v221 offset:51200
	global_load_lds_dwordx4 v186, s[42:43]
	s_add_i32 m0, s10, 0x2000
	ds_read_b128 v[176:179], v221 offset:52224
	global_load_lds_dwordx4 v190, s[42:43]
	s_add_u32 s42, s42, 0x40000
	s_addc_u32 s43, s43, 0
	s_add_i32 s10, s72, s50
	s_mov_b32 m0, s10
	ds_read_b128 v[180:183], v221 offset:53248
	global_load_lds_dwordx4 v186, s[42:43]
	s_add_i32 m0, s10, 0x2000
	ds_read_b128 v[204:207], v221 offset:54272
	global_load_lds_dwordx4 v190, s[42:43]
	s_mov_b32 m0, s58
	ds_read_b128 v[208:211], v221 offset:55296
	global_load_lds_dwordx4 v184, s[40:41]
	s_mov_b32 m0, s59
	ds_read_b128 v[212:215], v221 offset:56320
	global_load_lds_dwordx4 v188, s[40:41]
	s_waitcnt vmcnt(8)
	s_waitcnt lgkmcnt(0)
	s_barrier
	s_setprio 1
	s_waitcnt lgkmcnt(0)
	v_mfma_f32_16x16x32_bf16 v[60:63], v[132:135], v[164:167], v[60:63]
	v_mfma_f32_16x16x32_bf16 v[56:59], v[140:143], v[164:167], v[56:59]
	v_mfma_f32_16x16x32_bf16 v[44:47], v[132:135], v[172:175], v[44:47]
	v_mfma_f32_16x16x32_bf16 v[40:43], v[140:143], v[172:175], v[40:43]
	v_mfma_f32_16x16x32_bf16 v[28:31], v[132:135], v[180:183], v[28:31]
	v_mfma_f32_16x16x32_bf16 v[24:27], v[140:143], v[180:183], v[24:27]
	v_mfma_f32_16x16x32_bf16 v[12:15], v[132:135], v[208:211], v[12:15]
	v_mfma_f32_16x16x32_bf16 v[8:11], v[140:143], v[208:211], v[8:11]
	v_mfma_f32_16x16x32_bf16 v[60:63], v[136:139], v[168:171], v[60:63]
	v_mfma_f32_16x16x32_bf16 v[56:59], v[144:147], v[168:171], v[56:59]
	v_mfma_f32_16x16x32_bf16 v[44:47], v[136:139], v[176:179], v[44:47]
	v_mfma_f32_16x16x32_bf16 v[40:43], v[144:147], v[176:179], v[40:43]
	v_mfma_f32_16x16x32_bf16 v[28:31], v[136:139], v[204:207], v[28:31]
	v_mfma_f32_16x16x32_bf16 v[24:27], v[144:147], v[204:207], v[24:27]
	v_mfma_f32_16x16x32_bf16 v[12:15], v[136:139], v[212:215], v[12:15]
	v_mfma_f32_16x16x32_bf16 v[8:11], v[144:147], v[212:215], v[8:11]
	s_setprio 0
	s_setprio 1
	v_mfma_f32_16x16x32_bf16 v[52:55], v[148:151], v[164:167], v[52:55]
	v_mfma_f32_16x16x32_bf16 v[48:51], v[156:159], v[164:167], v[48:51]
	v_mfma_f32_16x16x32_bf16 v[36:39], v[148:151], v[172:175], v[36:39]
	v_mfma_f32_16x16x32_bf16 v[32:35], v[156:159], v[172:175], v[32:35]
	v_mfma_f32_16x16x32_bf16 v[20:23], v[148:151], v[180:183], v[20:23]
	v_mfma_f32_16x16x32_bf16 v[16:19], v[156:159], v[180:183], v[16:19]
	v_mfma_f32_16x16x32_bf16 v[4:7], v[148:151], v[208:211], v[4:7]
	v_mfma_f32_16x16x32_bf16 v[0:3], v[156:159], v[208:211], v[0:3]
	v_mfma_f32_16x16x32_bf16 v[52:55], v[152:155], v[168:171], v[52:55]
	v_mfma_f32_16x16x32_bf16 v[48:51], v[160:163], v[168:171], v[48:51]
	v_mfma_f32_16x16x32_bf16 v[36:39], v[152:155], v[176:179], v[36:39]
	v_mfma_f32_16x16x32_bf16 v[32:35], v[160:163], v[176:179], v[32:35]
	v_mfma_f32_16x16x32_bf16 v[20:23], v[152:155], v[204:207], v[20:23]
	v_mfma_f32_16x16x32_bf16 v[16:19], v[160:163], v[204:207], v[16:19]
	v_mfma_f32_16x16x32_bf16 v[4:7], v[152:155], v[212:215], v[4:7]
	v_mfma_f32_16x16x32_bf16 v[0:3], v[160:163], v[212:215], v[0:3]
	s_setprio 0
	s_barrier
	s_add_i32 s10, s71, 2
	s_add_u32 s38, s38, 0x100
	s_addc_u32 s39, s39, 0
	s_cmp_gt_u32 s71, 13
	s_mov_b32 s71, s10
	s_cbranch_scc1 .LBB0_1025
.LBB0_1019:
	s_add_u32 s46, s28, s38
	s_addc_u32 s47, s29, s39
	s_mov_b64 s[100:101], s[46:47]
	s_add_u32 s73, s26, s38
	s_addc_u32 s72, s27, s39
	s_add_u32 s40, s46, 0x180
	s_addc_u32 s41, s47, 0
	s_add_u32 s42, s73, 0x180
	s_addc_u32 s43, s72, 0
	s_add_u32 s46, s46, 0x100
	s_addc_u32 s47, s47, 0
	s_add_u32 s44, s73, 0x100
	s_addc_u32 s45, s72, 0
	s_cmpk_eq_i32 s38, 0x700
	s_cselect_b32 s40, s30, s40
	s_cselect_b32 s41, s31, s41
	s_cselect_b32 s42, s36, s42
	s_cselect_b32 s43, s37, s43
	s_cselect_b32 s46, s69, s46
	s_cselect_b32 s47, s19, s47
	s_cselect_b32 s44, s70, s44
	s_cselect_b32 s45, s17, s45
	s_branch .LBB0_1018
